# MFMA order: each accumulator's k0 and k1 MFMAs issued back-to-back (accumulate chain) in all 8 GEMM loops
# speedup vs baseline: 1.0090x; 1.0090x over previous
; #define PG8_LDA(dst, b, h) do { _Pragma("unroll") for (int m = 0; m < 4; ++m) _Pragma("unroll") for (int k = 0; k < 2; ++k) dst[m][k] = *(const PG8_LAS bf16x8*)(lds + PG8_SA(b, h) + aoff + m * 2048 + k * 1024); } while (0)
; #define PG8_LDB(dst, b, h) do { _Pragma("unroll") for (int n = 0; n < 2; ++n) _Pragma("unroll") for (int k = 0; k < 2; ++k) dst[n][k] = *(const PG8_LAS bf16x8*)(lds + PG8_SB(b, h) + boff + n * 2048 + k * 1024); } while (0)
; #define PG8_MMA(ai, bj, At, Bt) do { __builtin_amdgcn_s_setprio(1); _Pragma("unroll") for (int m = 0; m < 4; ++m) _Pragma("unroll") for (int n = 0; n < 2; ++n) _Pragma("unroll") for (int k = 0; k < 2; ++k) \
;         acc[ai][bj][m][n] = __builtin_amdgcn_mfma_f32_16x16x32_bf16(Bt[n][k], At[m][k], acc[ai][bj][m][n], 0, 0, 0); __builtin_amdgcn_s_setprio(0); } while (0)
; #define PG8_WAIT_V(n) asm volatile("s_waitcnt vmcnt(" #n ")" ::: "memory")
; #define PG8_WAIT_L(n) asm volatile("s_waitcnt lgkmcnt(" #n ")" ::: "memory")
; #define PG8_BAR __builtin_amdgcn_s_barrier()
; #define PG8_SCHED __builtin_amdgcn_sched_barrier(0)
; template <class Epi, class Sched, bool ALIGN_EPI = false, bool SP2 = false>
; __device__ __forceinline__ void gemm_phase(PG8_LAS unsigned char* lds, const Gemm g, const Sched& S, const Epi& E, const int tid) {
;     ...
;             PG8_LDB(B0, 0, 0); PG8_LDB(B1, 0, 1); PG8_SCHED; PG8_LDA(At, 0, 0); PG8_STAGE(PG8_SA(1, 1), a1 + hstepA, voffA);
;             PG8_WAIT_V(8); PG8_WAIT_L(0); PG8_BAR; PG8_MMA(0, 0, At, B0); PG8_MMA(0, 1, At, B1); PG8_BAR; PG8_SCHED;
;             PG8_LDA(At, 0, 1); PG8_STAGE(PG8_SB(0, 0), b2, voffB); PG8_STAGE(PG8_SB(0, 1), b2 + hstepB, voffB); PG8_STAGE(PG8_SA(0, 0), a2, voffA);
;             PG8_WAIT_V(8); PG8_WAIT_L(0); PG8_BAR; PG8_MMA(1, 0, At, B0); PG8_MMA(1, 1, At, B1); PG8_BAR; PG8_SCHED;
.LBB0_380:
	s_or_b64 exec, exec, s[34:35]
	v_add_u32_e32 v145, 0x10000, v154
	ds_read_b128 v[156:159], v145
	ds_read_b128 v[160:163], v145 offset:1024
	ds_read_b128 v[164:167], v145 offset:2048
	ds_read_b128 v[168:171], v145 offset:3072
	v_add_u32_e32 v145, 0x14000, v154
	s_add_u32 s34, s28, 0x100
	ds_read_b128 v[172:175], v145
	ds_read_b128 v[176:179], v145 offset:1024
	ds_read_b128 v[180:183], v145 offset:2048
	ds_read_b128 v[184:187], v145 offset:3072
	s_addc_u32 s35, s29, 0
	s_and_b64 s[30:31], s[30:31], exec
	s_cselect_b32 s42, s91, s34
	s_cselect_b32 s43, s17, s35
	s_cselect_b32 s31, s15, s97
	s_cselect_b32 s30, s95, s96
	s_add_u32 s38, s42, 0x80
	s_addc_u32 s39, s43, 0
	s_add_u32 s40, s30, 0x80
	s_addc_u32 s41, s31, 0
	ds_read_b128 v[188:191], v155
	ds_read_b128 v[192:195], v155 offset:1024
	ds_read_b128 v[196:199], v155 offset:2048
	ds_read_b128 v[200:203], v155 offset:3072
	ds_read_b128 v[204:207], v155 offset:4096
	ds_read_b128 v[208:211], v155 offset:5120
	ds_read_b128 v[212:215], v155 offset:6144
	ds_read_b128 v[216:219], v155 offset:7168
	s_add_u32 s28, s28, 0x80080
	s_addc_u32 s29, s29, 0
	s_mov_b32 m0, s69
	s_nop 0
	global_load_lds_dwordx4 v149, s[28:29]
	s_nop 0
	s_mov_b32 m0, s58
	s_nop 0
	global_load_lds_dwordx4 v151, s[28:29]
	s_waitcnt vmcnt(8)
	s_waitcnt lgkmcnt(0)
	s_barrier
	s_setprio 1
	v_mfma_f32_16x16x32_bf16 v[126:129], v[156:159], v[188:191], v[126:129]
	v_mfma_f32_16x16x32_bf16 v[126:129], v[160:163], v[192:195], v[126:129]
	v_mfma_f32_16x16x32_bf16 v[122:125], v[164:167], v[188:191], v[122:125]
	v_mfma_f32_16x16x32_bf16 v[122:125], v[168:171], v[192:195], v[122:125]
	v_mfma_f32_16x16x32_bf16 v[110:113], v[156:159], v[196:199], v[110:113]
	v_mfma_f32_16x16x32_bf16 v[110:113], v[160:163], v[200:203], v[110:113]
	v_mfma_f32_16x16x32_bf16 v[106:109], v[164:167], v[196:199], v[106:109]
	v_mfma_f32_16x16x32_bf16 v[106:109], v[168:171], v[200:203], v[106:109]
	v_mfma_f32_16x16x32_bf16 v[94:97], v[156:159], v[204:207], v[94:97]
	v_mfma_f32_16x16x32_bf16 v[94:97], v[160:163], v[208:211], v[94:97]
	v_mfma_f32_16x16x32_bf16 v[90:93], v[164:167], v[204:207], v[90:93]
	v_mfma_f32_16x16x32_bf16 v[90:93], v[168:171], v[208:211], v[90:93]
	v_mfma_f32_16x16x32_bf16 v[78:81], v[156:159], v[212:215], v[78:81]
	v_mfma_f32_16x16x32_bf16 v[78:81], v[160:163], v[216:219], v[78:81]
	v_mfma_f32_16x16x32_bf16 v[74:77], v[164:167], v[212:215], v[74:77]
	v_mfma_f32_16x16x32_bf16 v[74:77], v[168:171], v[216:219], v[74:77]
	v_mfma_f32_16x16x32_bf16 v[118:121], v[172:175], v[188:191], v[118:121]
	v_mfma_f32_16x16x32_bf16 v[118:121], v[176:179], v[192:195], v[118:121]
	v_mfma_f32_16x16x32_bf16 v[114:117], v[180:183], v[188:191], v[114:117]
	v_mfma_f32_16x16x32_bf16 v[114:117], v[184:187], v[192:195], v[114:117]
	v_mfma_f32_16x16x32_bf16 v[102:105], v[172:175], v[196:199], v[102:105]
	v_mfma_f32_16x16x32_bf16 v[102:105], v[176:179], v[200:203], v[102:105]
	v_mfma_f32_16x16x32_bf16 v[98:101], v[180:183], v[196:199], v[98:101]
	v_mfma_f32_16x16x32_bf16 v[98:101], v[184:187], v[200:203], v[98:101]
	v_mfma_f32_16x16x32_bf16 v[86:89], v[172:175], v[204:207], v[86:89]
	v_mfma_f32_16x16x32_bf16 v[86:89], v[176:179], v[208:211], v[86:89]
	v_mfma_f32_16x16x32_bf16 v[82:85], v[180:183], v[204:207], v[82:85]
	v_mfma_f32_16x16x32_bf16 v[82:85], v[184:187], v[208:211], v[82:85]
	v_mfma_f32_16x16x32_bf16 v[70:73], v[172:175], v[212:215], v[70:73]
	v_mfma_f32_16x16x32_bf16 v[70:73], v[176:179], v[216:219], v[70:73]
	v_mfma_f32_16x16x32_bf16 v[66:69], v[180:183], v[212:215], v[66:69]
	v_mfma_f32_16x16x32_bf16 v[66:69], v[184:187], v[216:219], v[66:69]
	s_setprio 0
	s_barrier
	ds_read_b128 v[188:191], v155 offset:16384
	ds_read_b128 v[192:195], v155 offset:17408
	ds_read_b128 v[196:199], v155 offset:18432
	ds_read_b128 v[200:203], v155 offset:19456
	ds_read_b128 v[204:207], v155 offset:20480
	ds_read_b128 v[208:211], v155 offset:21504
	ds_read_b128 v[212:215], v155 offset:22528
	ds_read_b128 v[216:219], v155 offset:23552
	s_mov_b32 m0, s23
	s_nop 0
	global_load_lds_dwordx4 v150, s[30:31]
	s_add_u32 s28, s30, 0x80000
	s_mov_b32 m0, s25
	s_nop 0
	global_load_lds_dwordx4 v152, s[30:31]
	s_addc_u32 s29, s31, 0
	s_mov_b32 m0, s48
	s_nop 0
	global_load_lds_dwordx4 v150, s[28:29]
	s_nop 0
	s_mov_b32 m0, s49
	s_nop 0
	global_load_lds_dwordx4 v152, s[28:29]
	s_nop 0
	s_mov_b32 m0, s10
	s_nop 0
	global_load_lds_dwordx4 v149, s[42:43]
	s_nop 0
	s_mov_b32 m0, s50
	s_nop 0
	global_load_lds_dwordx4 v151, s[42:43]
	s_waitcnt vmcnt(8)
	s_waitcnt lgkmcnt(0)
	s_barrier
	s_setprio 1
	v_mfma_f32_16x16x32_bf16 v[62:65], v[156:159], v[188:191], v[62:65]
	v_mfma_f32_16x16x32_bf16 v[62:65], v[160:163], v[192:195], v[62:65]
	v_mfma_f32_16x16x32_bf16 v[58:61], v[164:167], v[188:191], v[58:61]
	v_mfma_f32_16x16x32_bf16 v[58:61], v[168:171], v[192:195], v[58:61]
	v_mfma_f32_16x16x32_bf16 v[46:49], v[156:159], v[196:199], v[46:49]
	v_mfma_f32_16x16x32_bf16 v[46:49], v[160:163], v[200:203], v[46:49]
	v_mfma_f32_16x16x32_bf16 v[42:45], v[164:167], v[196:199], v[42:45]
	v_mfma_f32_16x16x32_bf16 v[42:45], v[168:171], v[200:203], v[42:45]
	v_mfma_f32_16x16x32_bf16 v[30:33], v[156:159], v[204:207], v[30:33]
	v_mfma_f32_16x16x32_bf16 v[30:33], v[160:163], v[208:211], v[30:33]
	v_mfma_f32_16x16x32_bf16 v[26:29], v[164:167], v[204:207], v[26:29]
	v_mfma_f32_16x16x32_bf16 v[26:29], v[168:171], v[208:211], v[26:29]
	v_mfma_f32_16x16x32_bf16 v[14:17], v[156:159], v[212:215], v[14:17]
	v_mfma_f32_16x16x32_bf16 v[14:17], v[160:163], v[216:219], v[14:17]
	v_mfma_f32_16x16x32_bf16 v[10:13], v[164:167], v[212:215], v[10:13]
	v_mfma_f32_16x16x32_bf16 v[10:13], v[168:171], v[216:219], v[10:13]
	v_mfma_f32_16x16x32_bf16 v[54:57], v[172:175], v[188:191], v[54:57]
	v_mfma_f32_16x16x32_bf16 v[54:57], v[176:179], v[192:195], v[54:57]
	v_mfma_f32_16x16x32_bf16 v[50:53], v[180:183], v[188:191], v[50:53]
	v_mfma_f32_16x16x32_bf16 v[50:53], v[184:187], v[192:195], v[50:53]
	v_mfma_f32_16x16x32_bf16 v[38:41], v[172:175], v[196:199], v[38:41]
	v_mfma_f32_16x16x32_bf16 v[38:41], v[176:179], v[200:203], v[38:41]
	v_mfma_f32_16x16x32_bf16 v[34:37], v[180:183], v[196:199], v[34:37]
	v_mfma_f32_16x16x32_bf16 v[34:37], v[184:187], v[200:203], v[34:37]
	v_mfma_f32_16x16x32_bf16 v[22:25], v[172:175], v[204:207], v[22:25]
	v_mfma_f32_16x16x32_bf16 v[22:25], v[176:179], v[208:211], v[22:25]
	v_mfma_f32_16x16x32_bf16 v[18:21], v[180:183], v[204:207], v[18:21]
	v_mfma_f32_16x16x32_bf16 v[18:21], v[184:187], v[208:211], v[18:21]
	v_mfma_f32_16x16x32_bf16 v[6:9], v[172:175], v[212:215], v[6:9]
	v_mfma_f32_16x16x32_bf16 v[6:9], v[176:179], v[216:219], v[6:9]
	v_mfma_f32_16x16x32_bf16 v[2:5], v[180:183], v[212:215], v[2:5]
	v_mfma_f32_16x16x32_bf16 v[2:5], v[184:187], v[216:219], v[2:5]
	s_setprio 0
	s_barrier
; #define PG8_LDA(dst, b, h) do { _Pragma("unroll") for (int m = 0; m < 4; ++m) _Pragma("unroll") for (int k = 0; k < 2; ++k) dst[m][k] = *(const PG8_LAS bf16x8*)(lds + PG8_SA(b, h) + aoff + m * 2048 + k * 1024); } while (0)
; #define PG8_LDB(dst, b, h) do { _Pragma("unroll") for (int n = 0; n < 2; ++n) _Pragma("unroll") for (int k = 0; k < 2; ++k) dst[n][k] = *(const PG8_LAS bf16x8*)(lds + PG8_SB(b, h) + boff + n * 2048 + k * 1024); } while (0)
; #define PG8_MMA(ai, bj, At, Bt) do { __builtin_amdgcn_s_setprio(1); _Pragma("unroll") for (int m = 0; m < 4; ++m) _Pragma("unroll") for (int n = 0; n < 2; ++n) _Pragma("unroll") for (int k = 0; k < 2; ++k) \
;         acc[ai][bj][m][n] = __builtin_amdgcn_mfma_f32_16x16x32_bf16(Bt[n][k], At[m][k], acc[ai][bj][m][n], 0, 0, 0); __builtin_amdgcn_s_setprio(0); } while (0)
; #define PG8_WAIT_V(n) asm volatile("s_waitcnt vmcnt(" #n ")" ::: "memory")
; #define PG8_WAIT_L(n) asm volatile("s_waitcnt lgkmcnt(" #n ")" ::: "memory")
; #define PG8_BAR __builtin_amdgcn_s_barrier()
; #define PG8_SCHED __builtin_amdgcn_sched_barrier(0)
; template <class Epi, class Sched, bool ALIGN_EPI = false, bool SP2 = false>
; __device__ __forceinline__ void gemm_phase(PG8_LAS unsigned char* lds, const Gemm g, const Sched& S, const Epi& E, const int tid) {
;     ...
;             PG8_LDB(B0, 1, 0); PG8_LDB(B1, 1, 1); PG8_SCHED; PG8_LDA(At, 1, 0); PG8_STAGE(PG8_SA(0, 1), a2 + hstepA, voffA);
;             PG8_WAIT_V(8); PG8_WAIT_L(0); PG8_BAR; PG8_MMA(0, 0, At, B0); PG8_MMA(0, 1, At, B1); PG8_BAR; PG8_SCHED;
;             PG8_LDA(At, 1, 1); PG8_STAGE(PG8_SB(1, 0), b3, voffB); PG8_STAGE(PG8_SB(1, 1), b3 + hstepB, voffB); PG8_STAGE(PG8_SA(1, 0), a3, voffA);
;             PG8_WAIT_V(8); PG8_WAIT_L(0); PG8_BAR; PG8_MMA(1, 0, At, B0); PG8_MMA(1, 1, At, B1); PG8_BAR; PG8_SCHED;
	v_add_u32_e32 v145, 0x18000, v154
	ds_read_b128 v[156:159], v145
	ds_read_b128 v[160:163], v145 offset:1024
	ds_read_b128 v[164:167], v145 offset:2048
	ds_read_b128 v[168:171], v145 offset:3072
	v_add_u32_e32 v145, 0x1c000, v154
	ds_read_b128 v[172:175], v145
	ds_read_b128 v[176:179], v145 offset:1024
	ds_read_b128 v[180:183], v145 offset:2048
	ds_read_b128 v[184:187], v145 offset:3072
	ds_read_b128 v[188:191], v155 offset:32768
	ds_read_b128 v[192:195], v155 offset:33792
	ds_read_b128 v[196:199], v155 offset:34816
	ds_read_b128 v[200:203], v155 offset:35840
	ds_read_b128 v[204:207], v155 offset:36864
	ds_read_b128 v[208:211], v155 offset:37888
	ds_read_b128 v[212:215], v155 offset:38912
	ds_read_b128 v[216:219], v155 offset:39936
	s_add_u32 s28, s42, 0x80000
	s_addc_u32 s29, s43, 0
	s_mov_b32 m0, s51
	s_nop 0
	global_load_lds_dwordx4 v149, s[28:29]
	s_nop 0
	s_mov_b32 m0, s54
	s_nop 0
	global_load_lds_dwordx4 v151, s[28:29]
	s_waitcnt vmcnt(8)
	s_waitcnt lgkmcnt(0)
	s_barrier
	s_setprio 1
	v_mfma_f32_16x16x32_bf16 v[126:129], v[156:159], v[188:191], v[126:129]
	v_mfma_f32_16x16x32_bf16 v[126:129], v[160:163], v[192:195], v[126:129]
	v_mfma_f32_16x16x32_bf16 v[122:125], v[164:167], v[188:191], v[122:125]
	v_mfma_f32_16x16x32_bf16 v[122:125], v[168:171], v[192:195], v[122:125]
	v_mfma_f32_16x16x32_bf16 v[110:113], v[156:159], v[196:199], v[110:113]
	v_mfma_f32_16x16x32_bf16 v[110:113], v[160:163], v[200:203], v[110:113]
	v_mfma_f32_16x16x32_bf16 v[106:109], v[164:167], v[196:199], v[106:109]
	v_mfma_f32_16x16x32_bf16 v[106:109], v[168:171], v[200:203], v[106:109]
	v_mfma_f32_16x16x32_bf16 v[94:97], v[156:159], v[204:207], v[94:97]
	v_mfma_f32_16x16x32_bf16 v[94:97], v[160:163], v[208:211], v[94:97]
	v_mfma_f32_16x16x32_bf16 v[90:93], v[164:167], v[204:207], v[90:93]
	v_mfma_f32_16x16x32_bf16 v[90:93], v[168:171], v[208:211], v[90:93]
	v_mfma_f32_16x16x32_bf16 v[78:81], v[156:159], v[212:215], v[78:81]
	v_mfma_f32_16x16x32_bf16 v[78:81], v[160:163], v[216:219], v[78:81]
	v_mfma_f32_16x16x32_bf16 v[74:77], v[164:167], v[212:215], v[74:77]
	v_mfma_f32_16x16x32_bf16 v[74:77], v[168:171], v[216:219], v[74:77]
	v_mfma_f32_16x16x32_bf16 v[118:121], v[172:175], v[188:191], v[118:121]
	v_mfma_f32_16x16x32_bf16 v[118:121], v[176:179], v[192:195], v[118:121]
	v_mfma_f32_16x16x32_bf16 v[114:117], v[180:183], v[188:191], v[114:117]
	v_mfma_f32_16x16x32_bf16 v[114:117], v[184:187], v[192:195], v[114:117]
	v_mfma_f32_16x16x32_bf16 v[102:105], v[172:175], v[196:199], v[102:105]
	v_mfma_f32_16x16x32_bf16 v[102:105], v[176:179], v[200:203], v[102:105]
	v_mfma_f32_16x16x32_bf16 v[98:101], v[180:183], v[196:199], v[98:101]
	v_mfma_f32_16x16x32_bf16 v[98:101], v[184:187], v[200:203], v[98:101]
	v_mfma_f32_16x16x32_bf16 v[86:89], v[172:175], v[204:207], v[86:89]
	v_mfma_f32_16x16x32_bf16 v[86:89], v[176:179], v[208:211], v[86:89]
	v_mfma_f32_16x16x32_bf16 v[82:85], v[180:183], v[204:207], v[82:85]
	v_mfma_f32_16x16x32_bf16 v[82:85], v[184:187], v[208:211], v[82:85]
	v_mfma_f32_16x16x32_bf16 v[70:73], v[172:175], v[212:215], v[70:73]
	v_mfma_f32_16x16x32_bf16 v[70:73], v[176:179], v[216:219], v[70:73]
	v_mfma_f32_16x16x32_bf16 v[66:69], v[180:183], v[212:215], v[66:69]
	v_mfma_f32_16x16x32_bf16 v[66:69], v[184:187], v[216:219], v[66:69]
	s_setprio 0
	s_barrier
	ds_read_b128 v[188:191], v155 offset:49152
	ds_read_b128 v[192:195], v155 offset:50176
	ds_read_b128 v[196:199], v155 offset:51200
	ds_read_b128 v[200:203], v155 offset:52224
	ds_read_b128 v[204:207], v155 offset:53248
	ds_read_b128 v[208:211], v155 offset:54272
	ds_read_b128 v[212:215], v155 offset:55296
	ds_read_b128 v[216:219], v155 offset:56320
	s_mov_b32 m0, s55
	s_nop 0
	global_load_lds_dwordx4 v150, s[40:41]
	s_add_u32 s28, s30, 0x80080
	s_mov_b32 m0, s56
	s_nop 0
	global_load_lds_dwordx4 v152, s[40:41]
	s_addc_u32 s29, s31, 0
	s_mov_b32 m0, s64
	s_nop 0
	global_load_lds_dwordx4 v150, s[28:29]
	s_nop 0
	s_mov_b32 m0, s65
	s_nop 0
	global_load_lds_dwordx4 v152, s[28:29]
	s_nop 0
	s_mov_b32 m0, s57
	s_nop 0
	global_load_lds_dwordx4 v149, s[38:39]
	s_nop 0
	s_mov_b32 m0, s61
	s_nop 0
	global_load_lds_dwordx4 v151, s[38:39]
	s_waitcnt vmcnt(8)
	s_waitcnt lgkmcnt(0)
	s_barrier
	s_setprio 1
	v_mfma_f32_16x16x32_bf16 v[62:65], v[156:159], v[188:191], v[62:65]
	v_mfma_f32_16x16x32_bf16 v[62:65], v[160:163], v[192:195], v[62:65]
	v_mfma_f32_16x16x32_bf16 v[58:61], v[164:167], v[188:191], v[58:61]
	v_mfma_f32_16x16x32_bf16 v[58:61], v[168:171], v[192:195], v[58:61]
	v_mfma_f32_16x16x32_bf16 v[46:49], v[156:159], v[196:199], v[46:49]
	v_mfma_f32_16x16x32_bf16 v[46:49], v[160:163], v[200:203], v[46:49]
	v_mfma_f32_16x16x32_bf16 v[42:45], v[164:167], v[196:199], v[42:45]
	v_mfma_f32_16x16x32_bf16 v[42:45], v[168:171], v[200:203], v[42:45]
	v_mfma_f32_16x16x32_bf16 v[30:33], v[156:159], v[204:207], v[30:33]
	v_mfma_f32_16x16x32_bf16 v[30:33], v[160:163], v[208:211], v[30:33]
	v_mfma_f32_16x16x32_bf16 v[26:29], v[164:167], v[204:207], v[26:29]
	v_mfma_f32_16x16x32_bf16 v[26:29], v[168:171], v[208:211], v[26:29]
	v_mfma_f32_16x16x32_bf16 v[14:17], v[156:159], v[212:215], v[14:17]
	v_mfma_f32_16x16x32_bf16 v[14:17], v[160:163], v[216:219], v[14:17]
	v_mfma_f32_16x16x32_bf16 v[10:13], v[164:167], v[212:215], v[10:13]
	v_mfma_f32_16x16x32_bf16 v[10:13], v[168:171], v[216:219], v[10:13]
	v_mfma_f32_16x16x32_bf16 v[54:57], v[172:175], v[188:191], v[54:57]
	v_mfma_f32_16x16x32_bf16 v[54:57], v[176:179], v[192:195], v[54:57]
	v_mfma_f32_16x16x32_bf16 v[50:53], v[180:183], v[188:191], v[50:53]
	v_mfma_f32_16x16x32_bf16 v[50:53], v[184:187], v[192:195], v[50:53]
	v_mfma_f32_16x16x32_bf16 v[38:41], v[172:175], v[196:199], v[38:41]
	v_mfma_f32_16x16x32_bf16 v[38:41], v[176:179], v[200:203], v[38:41]
	v_mfma_f32_16x16x32_bf16 v[34:37], v[180:183], v[196:199], v[34:37]
	v_mfma_f32_16x16x32_bf16 v[34:37], v[184:187], v[200:203], v[34:37]
	v_mfma_f32_16x16x32_bf16 v[22:25], v[172:175], v[204:207], v[22:25]
	v_mfma_f32_16x16x32_bf16 v[22:25], v[176:179], v[208:211], v[22:25]
	v_mfma_f32_16x16x32_bf16 v[18:21], v[180:183], v[204:207], v[18:21]
	v_mfma_f32_16x16x32_bf16 v[18:21], v[184:187], v[208:211], v[18:21]
	v_mfma_f32_16x16x32_bf16 v[6:9], v[172:175], v[212:215], v[6:9]
	v_mfma_f32_16x16x32_bf16 v[6:9], v[176:179], v[216:219], v[6:9]
	v_mfma_f32_16x16x32_bf16 v[2:5], v[180:183], v[212:215], v[2:5]
	v_mfma_f32_16x16x32_bf16 v[2:5], v[184:187], v[216:219], v[2:5]
	s_setprio 0
	s_barrier
	s_add_i32 s59, s59, 2
	s_add_u32 s96, s96, 0x100
	s_addc_u32 s97, s97, 0
	s_cmp_gt_u32 s59, 29
	s_mov_b64 s[28:29], s[34:35]
	s_cbranch_scc1 .LBB0_383

; #define PG8_LDA(dst, b, h) do { _Pragma("unroll") for (int m = 0; m < 4; ++m) _Pragma("unroll") for (int k = 0; k < 2; ++k) dst[m][k] = *(const PG8_LAS bf16x8*)(lds + PG8_SA(b, h) + aoff + m * 2048 + k * 1024); } while (0)
; #define PG8_LDB(dst, b, h) do { _Pragma("unroll") for (int n = 0; n < 2; ++n) _Pragma("unroll") for (int k = 0; k < 2; ++k) dst[n][k] = *(const PG8_LAS bf16x8*)(lds + PG8_SB(b, h) + boff + n * 2048 + k * 1024); } while (0)
; #define PG8_MMA(ai, bj, At, Bt) do { __builtin_amdgcn_s_setprio(1); _Pragma("unroll") for (int m = 0; m < 4; ++m) _Pragma("unroll") for (int n = 0; n < 2; ++n) _Pragma("unroll") for (int k = 0; k < 2; ++k) \
;         acc[ai][bj][m][n] = __builtin_amdgcn_mfma_f32_16x16x32_bf16(Bt[n][k], At[m][k], acc[ai][bj][m][n], 0, 0, 0); __builtin_amdgcn_s_setprio(0); } while (0)
; #define PG8_WAIT_V(n) asm volatile("s_waitcnt vmcnt(" #n ")" ::: "memory")
; #define PG8_WAIT_L(n) asm volatile("s_waitcnt lgkmcnt(" #n ")" ::: "memory")
; #define PG8_BAR __builtin_amdgcn_s_barrier()
; #define PG8_SCHED __builtin_amdgcn_sched_barrier(0)
; template <class Epi, class Sched, bool ALIGN_EPI = false, bool SP2 = false>
; __device__ __forceinline__ void gemm_phase(PG8_LAS unsigned char* lds, const Gemm g, const Sched& S, const Epi& E, const int tid) {
;     ...
;             PG8_LDB(B0, 0, 0); PG8_LDB(B1, 0, 1); PG8_SCHED; PG8_LDA(At, 0, 0); PG8_STAGE(PG8_SA(1, 1), a1 + hstepA, voffA);
;             PG8_WAIT_V(8); PG8_WAIT_L(0); PG8_BAR; PG8_MMA(0, 0, At, B0); PG8_MMA(0, 1, At, B1); PG8_BAR; PG8_SCHED;
;             PG8_LDA(At, 0, 1); PG8_STAGE(PG8_SB(0, 0), b2, voffB); PG8_STAGE(PG8_SB(0, 1), b2 + hstepB, voffB); PG8_STAGE(PG8_SA(0, 0), a2, voffA);
;             PG8_WAIT_V(8); PG8_WAIT_L(0); PG8_BAR; PG8_MMA(1, 0, At, B0); PG8_MMA(1, 1, At, B1); PG8_BAR; PG8_SCHED;
.LBB0_462:
	v_add_u32_e32 v142, 0x10000, v181
	v_add_u32_e32 v158, 0x14000, v181
	ds_read_b128 v[130:133], v142
	ds_read_b128 v[134:137], v142 offset:1024
	ds_read_b128 v[138:141], v142 offset:2048
	ds_read_b128 v[142:145], v142 offset:3072
	ds_read_b128 v[146:149], v158
	ds_read_b128 v[150:153], v158 offset:1024
	ds_read_b128 v[154:157], v158 offset:2048
	ds_read_b128 v[158:161], v158 offset:3072
	s_cmpk_eq_i32 s67, 0x54
	s_cselect_b32 s26, s6, s64
	s_cselect_b32 s27, s7, s65
	s_cselect_b32 s24, s18, s11
	s_cselect_b32 s25, s19, s59
	s_add_u32 s22, s26, 0x8000
	s_addc_u32 s23, s27, 0
	ds_read_b128 v[162:165], v182
	ds_read_b128 v[166:169], v182 offset:1024
	ds_read_b128 v[170:173], v182 offset:2048
	ds_read_b128 v[184:187], v182 offset:3072
	ds_read_b128 v[188:191], v182 offset:4096
	ds_read_b128 v[192:195], v182 offset:5120
	ds_read_b128 v[196:199], v182 offset:6144
	ds_read_b128 v[200:203], v182 offset:7168
	s_mov_b32 m0, s50
	s_nop 0
	global_load_lds_dwordx4 v0, s[20:21]
	s_nop 0
	s_mov_b32 m0, s54
	s_nop 0
	global_load_lds_dwordx4 v177, s[20:21]
	s_waitcnt vmcnt(8)
	s_waitcnt lgkmcnt(0)
	s_barrier
	s_setprio 1
	v_mfma_f32_16x16x32_bf16 v[126:129], v[130:133], v[162:165], v[126:129]
	v_mfma_f32_16x16x32_bf16 v[126:129], v[134:137], v[166:169], v[126:129]
	v_mfma_f32_16x16x32_bf16 v[122:125], v[138:141], v[162:165], v[122:125]
	v_mfma_f32_16x16x32_bf16 v[122:125], v[142:145], v[166:169], v[122:125]
	v_mfma_f32_16x16x32_bf16 v[110:113], v[130:133], v[170:173], v[110:113]
	v_mfma_f32_16x16x32_bf16 v[110:113], v[134:137], v[184:187], v[110:113]
	v_mfma_f32_16x16x32_bf16 v[106:109], v[138:141], v[170:173], v[106:109]
	v_mfma_f32_16x16x32_bf16 v[106:109], v[142:145], v[184:187], v[106:109]
	v_mfma_f32_16x16x32_bf16 v[94:97], v[130:133], v[188:191], v[94:97]
	v_mfma_f32_16x16x32_bf16 v[94:97], v[134:137], v[192:195], v[94:97]
	v_mfma_f32_16x16x32_bf16 v[90:93], v[138:141], v[188:191], v[90:93]
	v_mfma_f32_16x16x32_bf16 v[90:93], v[142:145], v[192:195], v[90:93]
	v_mfma_f32_16x16x32_bf16 v[78:81], v[130:133], v[196:199], v[78:81]
	v_mfma_f32_16x16x32_bf16 v[78:81], v[134:137], v[200:203], v[78:81]
	v_mfma_f32_16x16x32_bf16 v[74:77], v[138:141], v[196:199], v[74:77]
	v_mfma_f32_16x16x32_bf16 v[74:77], v[142:145], v[200:203], v[74:77]
	v_mfma_f32_16x16x32_bf16 v[118:121], v[146:149], v[162:165], v[118:121]
	v_mfma_f32_16x16x32_bf16 v[118:121], v[150:153], v[166:169], v[118:121]
	v_mfma_f32_16x16x32_bf16 v[114:117], v[154:157], v[162:165], v[114:117]
	v_mfma_f32_16x16x32_bf16 v[114:117], v[158:161], v[166:169], v[114:117]
	v_mfma_f32_16x16x32_bf16 v[102:105], v[146:149], v[170:173], v[102:105]
	v_mfma_f32_16x16x32_bf16 v[102:105], v[150:153], v[184:187], v[102:105]
	v_mfma_f32_16x16x32_bf16 v[98:101], v[154:157], v[170:173], v[98:101]
	v_mfma_f32_16x16x32_bf16 v[98:101], v[158:161], v[184:187], v[98:101]
	v_mfma_f32_16x16x32_bf16 v[86:89], v[146:149], v[188:191], v[86:89]
	v_mfma_f32_16x16x32_bf16 v[86:89], v[150:153], v[192:195], v[86:89]
	v_mfma_f32_16x16x32_bf16 v[82:85], v[154:157], v[188:191], v[82:85]
	v_mfma_f32_16x16x32_bf16 v[82:85], v[158:161], v[192:195], v[82:85]
	v_mfma_f32_16x16x32_bf16 v[70:73], v[146:149], v[196:199], v[70:73]
	v_mfma_f32_16x16x32_bf16 v[70:73], v[150:153], v[200:203], v[70:73]
	v_mfma_f32_16x16x32_bf16 v[66:69], v[154:157], v[196:199], v[66:69]
	v_mfma_f32_16x16x32_bf16 v[66:69], v[158:161], v[200:203], v[66:69]
	s_setprio 0
	s_barrier
	ds_read_b128 v[162:165], v182 offset:16384
	ds_read_b128 v[166:169], v182 offset:17408
	ds_read_b128 v[170:173], v182 offset:18432
	ds_read_b128 v[184:187], v182 offset:19456
	ds_read_b128 v[188:191], v182 offset:20480
	ds_read_b128 v[192:195], v182 offset:21504
	ds_read_b128 v[196:199], v182 offset:22528
	ds_read_b128 v[200:203], v182 offset:23552
	s_mov_b32 m0, s35
	s_nop 0
	global_load_lds_dwordx4 v176, s[24:25]
	s_add_u32 s90, s24, 0x4000
	s_mov_b32 m0, s37
	s_nop 0
	global_load_lds_dwordx4 v178, s[24:25]
	s_addc_u32 s91, s25, 0
	s_mov_b32 m0, s38
	s_nop 0
	global_load_lds_dwordx4 v176, s[90:91]
	s_nop 0
	s_mov_b32 m0, s39
	s_nop 0
	global_load_lds_dwordx4 v178, s[90:91]
	s_nop 0
	s_mov_b32 m0, s10
	s_nop 0
	global_load_lds_dwordx4 v0, s[26:27]
	s_nop 0
	s_mov_b32 m0, s40
	s_nop 0
	global_load_lds_dwordx4 v177, s[26:27]
	s_waitcnt vmcnt(8)
	s_waitcnt lgkmcnt(0)
	s_barrier
	s_setprio 1
	v_mfma_f32_16x16x32_bf16 v[62:65], v[130:133], v[162:165], v[62:65]
	v_mfma_f32_16x16x32_bf16 v[62:65], v[134:137], v[166:169], v[62:65]
	v_mfma_f32_16x16x32_bf16 v[58:61], v[138:141], v[162:165], v[58:61]
	v_mfma_f32_16x16x32_bf16 v[58:61], v[142:145], v[166:169], v[58:61]
	v_mfma_f32_16x16x32_bf16 v[46:49], v[130:133], v[170:173], v[46:49]
	v_mfma_f32_16x16x32_bf16 v[46:49], v[134:137], v[184:187], v[46:49]
	v_mfma_f32_16x16x32_bf16 v[42:45], v[138:141], v[170:173], v[42:45]
	v_mfma_f32_16x16x32_bf16 v[42:45], v[142:145], v[184:187], v[42:45]
	v_mfma_f32_16x16x32_bf16 v[30:33], v[130:133], v[188:191], v[30:33]
	v_mfma_f32_16x16x32_bf16 v[30:33], v[134:137], v[192:195], v[30:33]
	v_mfma_f32_16x16x32_bf16 v[26:29], v[138:141], v[188:191], v[26:29]
	v_mfma_f32_16x16x32_bf16 v[26:29], v[142:145], v[192:195], v[26:29]
	v_mfma_f32_16x16x32_bf16 v[14:17], v[130:133], v[196:199], v[14:17]
	v_mfma_f32_16x16x32_bf16 v[14:17], v[134:137], v[200:203], v[14:17]
	v_mfma_f32_16x16x32_bf16 v[10:13], v[138:141], v[196:199], v[10:13]
	v_mfma_f32_16x16x32_bf16 v[10:13], v[142:145], v[200:203], v[10:13]
	v_mfma_f32_16x16x32_bf16 v[54:57], v[146:149], v[162:165], v[54:57]
	v_mfma_f32_16x16x32_bf16 v[54:57], v[150:153], v[166:169], v[54:57]
	v_mfma_f32_16x16x32_bf16 v[50:53], v[154:157], v[162:165], v[50:53]
	v_mfma_f32_16x16x32_bf16 v[50:53], v[158:161], v[166:169], v[50:53]
	v_mfma_f32_16x16x32_bf16 v[38:41], v[146:149], v[170:173], v[38:41]
	v_mfma_f32_16x16x32_bf16 v[38:41], v[150:153], v[184:187], v[38:41]
	v_mfma_f32_16x16x32_bf16 v[34:37], v[154:157], v[170:173], v[34:37]
	v_mfma_f32_16x16x32_bf16 v[34:37], v[158:161], v[184:187], v[34:37]
	v_mfma_f32_16x16x32_bf16 v[22:25], v[146:149], v[188:191], v[22:25]
	v_mfma_f32_16x16x32_bf16 v[22:25], v[150:153], v[192:195], v[22:25]
	v_mfma_f32_16x16x32_bf16 v[18:21], v[154:157], v[188:191], v[18:21]
	v_mfma_f32_16x16x32_bf16 v[18:21], v[158:161], v[192:195], v[18:21]
	v_mfma_f32_16x16x32_bf16 v[6:9], v[146:149], v[196:199], v[6:9]
	v_mfma_f32_16x16x32_bf16 v[6:9], v[150:153], v[200:203], v[6:9]
	v_mfma_f32_16x16x32_bf16 v[2:5], v[154:157], v[196:199], v[2:5]
	v_mfma_f32_16x16x32_bf16 v[2:5], v[158:161], v[200:203], v[2:5]
	s_setprio 0
	s_barrier
; #define PG8_LDA(dst, b, h) do { _Pragma("unroll") for (int m = 0; m < 4; ++m) _Pragma("unroll") for (int k = 0; k < 2; ++k) dst[m][k] = *(const PG8_LAS bf16x8*)(lds + PG8_SA(b, h) + aoff + m * 2048 + k * 1024); } while (0)
; #define PG8_LDB(dst, b, h) do { _Pragma("unroll") for (int n = 0; n < 2; ++n) _Pragma("unroll") for (int k = 0; k < 2; ++k) dst[n][k] = *(const PG8_LAS bf16x8*)(lds + PG8_SB(b, h) + boff + n * 2048 + k * 1024); } while (0)
; #define PG8_MMA(ai, bj, At, Bt) do { __builtin_amdgcn_s_setprio(1); _Pragma("unroll") for (int m = 0; m < 4; ++m) _Pragma("unroll") for (int n = 0; n < 2; ++n) _Pragma("unroll") for (int k = 0; k < 2; ++k) \
;         acc[ai][bj][m][n] = __builtin_amdgcn_mfma_f32_16x16x32_bf16(Bt[n][k], At[m][k], acc[ai][bj][m][n], 0, 0, 0); __builtin_amdgcn_s_setprio(0); } while (0)
; #define PG8_WAIT_V(n) asm volatile("s_waitcnt vmcnt(" #n ")" ::: "memory")
; #define PG8_WAIT_L(n) asm volatile("s_waitcnt lgkmcnt(" #n ")" ::: "memory")
; #define PG8_BAR __builtin_amdgcn_s_barrier()
; #define PG8_SCHED __builtin_amdgcn_sched_barrier(0)
; template <class Epi, class Sched, bool ALIGN_EPI = false, bool SP2 = false>
; __device__ __forceinline__ void gemm_phase(PG8_LAS unsigned char* lds, const Gemm g, const Sched& S, const Epi& E, const int tid) {
;     ...
;             PG8_LDB(B0, 1, 0); PG8_LDB(B1, 1, 1); PG8_SCHED; PG8_LDA(At, 1, 0); PG8_STAGE(PG8_SA(0, 1), a2 + hstepA, voffA);
;             PG8_WAIT_V(8); PG8_WAIT_L(0); PG8_BAR; PG8_MMA(0, 0, At, B0); PG8_MMA(0, 1, At, B1); PG8_BAR; PG8_SCHED;
;             PG8_LDA(At, 1, 1); PG8_STAGE(PG8_SB(1, 0), b3, voffB); PG8_STAGE(PG8_SB(1, 1), b3 + hstepB, voffB); PG8_STAGE(PG8_SA(1, 0), a3, voffA);
;             PG8_WAIT_V(8); PG8_WAIT_L(0); PG8_BAR; PG8_MMA(1, 0, At, B0); PG8_MMA(1, 1, At, B1); PG8_BAR; PG8_SCHED;
	v_add_u32_e32 v142, 0x18000, v181
	v_add_u32_e32 v158, 0x1c000, v181
	ds_read_b128 v[130:133], v142
	ds_read_b128 v[134:137], v142 offset:1024
	ds_read_b128 v[138:141], v142 offset:2048
	ds_read_b128 v[142:145], v142 offset:3072
	ds_read_b128 v[146:149], v158
	ds_read_b128 v[150:153], v158 offset:1024
	ds_read_b128 v[154:157], v158 offset:2048
	ds_read_b128 v[158:161], v158 offset:3072
	ds_read_b128 v[162:165], v182 offset:32768
	ds_read_b128 v[166:169], v182 offset:33792
	ds_read_b128 v[170:173], v182 offset:34816
	ds_read_b128 v[184:187], v182 offset:35840
	ds_read_b128 v[188:191], v182 offset:36864
	ds_read_b128 v[192:195], v182 offset:37888
	ds_read_b128 v[196:199], v182 offset:38912
	ds_read_b128 v[200:203], v182 offset:39936
	s_add_u32 s26, s26, 0x4000
	s_addc_u32 s27, s27, 0
	s_mov_b32 m0, s41
	s_nop 0
	global_load_lds_dwordx4 v0, s[26:27]
	s_nop 0
	s_mov_b32 m0, s42
	s_nop 0
	global_load_lds_dwordx4 v177, s[26:27]
	s_waitcnt vmcnt(8)
	s_waitcnt lgkmcnt(0)
	s_barrier
	s_setprio 1
	v_mfma_f32_16x16x32_bf16 v[126:129], v[130:133], v[162:165], v[126:129]
	v_mfma_f32_16x16x32_bf16 v[126:129], v[134:137], v[166:169], v[126:129]
	v_mfma_f32_16x16x32_bf16 v[122:125], v[138:141], v[162:165], v[122:125]
	v_mfma_f32_16x16x32_bf16 v[122:125], v[142:145], v[166:169], v[122:125]
	v_mfma_f32_16x16x32_bf16 v[110:113], v[130:133], v[170:173], v[110:113]
	v_mfma_f32_16x16x32_bf16 v[110:113], v[134:137], v[184:187], v[110:113]
	v_mfma_f32_16x16x32_bf16 v[106:109], v[138:141], v[170:173], v[106:109]
	v_mfma_f32_16x16x32_bf16 v[106:109], v[142:145], v[184:187], v[106:109]
	v_mfma_f32_16x16x32_bf16 v[94:97], v[130:133], v[188:191], v[94:97]
	v_mfma_f32_16x16x32_bf16 v[94:97], v[134:137], v[192:195], v[94:97]
	v_mfma_f32_16x16x32_bf16 v[90:93], v[138:141], v[188:191], v[90:93]
	v_mfma_f32_16x16x32_bf16 v[90:93], v[142:145], v[192:195], v[90:93]
	v_mfma_f32_16x16x32_bf16 v[78:81], v[130:133], v[196:199], v[78:81]
	v_mfma_f32_16x16x32_bf16 v[78:81], v[134:137], v[200:203], v[78:81]
	v_mfma_f32_16x16x32_bf16 v[74:77], v[138:141], v[196:199], v[74:77]
	v_mfma_f32_16x16x32_bf16 v[74:77], v[142:145], v[200:203], v[74:77]
	v_mfma_f32_16x16x32_bf16 v[118:121], v[146:149], v[162:165], v[118:121]
	v_mfma_f32_16x16x32_bf16 v[118:121], v[150:153], v[166:169], v[118:121]
	v_mfma_f32_16x16x32_bf16 v[114:117], v[154:157], v[162:165], v[114:117]
	v_mfma_f32_16x16x32_bf16 v[114:117], v[158:161], v[166:169], v[114:117]
	v_mfma_f32_16x16x32_bf16 v[102:105], v[146:149], v[170:173], v[102:105]
	v_mfma_f32_16x16x32_bf16 v[102:105], v[150:153], v[184:187], v[102:105]
	v_mfma_f32_16x16x32_bf16 v[98:101], v[154:157], v[170:173], v[98:101]
	v_mfma_f32_16x16x32_bf16 v[98:101], v[158:161], v[184:187], v[98:101]
	v_mfma_f32_16x16x32_bf16 v[86:89], v[146:149], v[188:191], v[86:89]
	v_mfma_f32_16x16x32_bf16 v[86:89], v[150:153], v[192:195], v[86:89]
	v_mfma_f32_16x16x32_bf16 v[82:85], v[154:157], v[188:191], v[82:85]
	v_mfma_f32_16x16x32_bf16 v[82:85], v[158:161], v[192:195], v[82:85]
	v_mfma_f32_16x16x32_bf16 v[70:73], v[146:149], v[196:199], v[70:73]
	v_mfma_f32_16x16x32_bf16 v[70:73], v[150:153], v[200:203], v[70:73]
	v_mfma_f32_16x16x32_bf16 v[66:69], v[154:157], v[196:199], v[66:69]
	v_mfma_f32_16x16x32_bf16 v[66:69], v[158:161], v[200:203], v[66:69]
	s_setprio 0
	s_barrier
	ds_read_b128 v[162:165], v182 offset:49152
	ds_read_b128 v[166:169], v182 offset:50176
	ds_read_b128 v[170:173], v182 offset:51200
	ds_read_b128 v[184:187], v182 offset:52224
	ds_read_b128 v[188:191], v182 offset:53248
	ds_read_b128 v[192:195], v182 offset:54272
	ds_read_b128 v[196:199], v182 offset:55296
	ds_read_b128 v[200:203], v182 offset:56320
	s_add_u32 s26, s24, 0x8000
	s_addc_u32 s27, s25, 0
	s_mov_b32 m0, s44
	s_nop 0
	global_load_lds_dwordx4 v176, s[26:27]
	s_add_u32 s24, s24, 0xc000
	s_mov_b32 m0, s45
	s_nop 0
	global_load_lds_dwordx4 v178, s[26:27]
	s_addc_u32 s25, s25, 0
	s_mov_b32 m0, s48
	s_nop 0
	global_load_lds_dwordx4 v176, s[24:25]
	s_nop 0
	s_mov_b32 m0, s49
	s_nop 0
	global_load_lds_dwordx4 v178, s[24:25]
	s_mov_b32 m0, s46
	s_nop 0
	global_load_lds_dwordx4 v0, s[22:23]
	s_nop 0
	s_mov_b32 m0, s47
	s_nop 0
	global_load_lds_dwordx4 v177, s[22:23]
	s_waitcnt vmcnt(8)
	s_waitcnt lgkmcnt(0)
	s_barrier
	s_setprio 1
	v_mfma_f32_16x16x32_bf16 v[62:65], v[130:133], v[162:165], v[62:65]
	v_mfma_f32_16x16x32_bf16 v[62:65], v[134:137], v[166:169], v[62:65]
	v_mfma_f32_16x16x32_bf16 v[58:61], v[138:141], v[162:165], v[58:61]
	v_mfma_f32_16x16x32_bf16 v[58:61], v[142:145], v[166:169], v[58:61]
	v_mfma_f32_16x16x32_bf16 v[46:49], v[130:133], v[170:173], v[46:49]
	v_mfma_f32_16x16x32_bf16 v[46:49], v[134:137], v[184:187], v[46:49]
	v_mfma_f32_16x16x32_bf16 v[42:45], v[138:141], v[170:173], v[42:45]
	v_mfma_f32_16x16x32_bf16 v[42:45], v[142:145], v[184:187], v[42:45]
	v_mfma_f32_16x16x32_bf16 v[30:33], v[130:133], v[188:191], v[30:33]
	v_mfma_f32_16x16x32_bf16 v[30:33], v[134:137], v[192:195], v[30:33]
	v_mfma_f32_16x16x32_bf16 v[26:29], v[138:141], v[188:191], v[26:29]
	v_mfma_f32_16x16x32_bf16 v[26:29], v[142:145], v[192:195], v[26:29]
	v_mfma_f32_16x16x32_bf16 v[14:17], v[130:133], v[196:199], v[14:17]
	v_mfma_f32_16x16x32_bf16 v[14:17], v[134:137], v[200:203], v[14:17]
	v_mfma_f32_16x16x32_bf16 v[10:13], v[138:141], v[196:199], v[10:13]
	v_mfma_f32_16x16x32_bf16 v[10:13], v[142:145], v[200:203], v[10:13]
	v_mfma_f32_16x16x32_bf16 v[54:57], v[146:149], v[162:165], v[54:57]
	v_mfma_f32_16x16x32_bf16 v[54:57], v[150:153], v[166:169], v[54:57]
	v_mfma_f32_16x16x32_bf16 v[50:53], v[154:157], v[162:165], v[50:53]
	v_mfma_f32_16x16x32_bf16 v[50:53], v[158:161], v[166:169], v[50:53]
	v_mfma_f32_16x16x32_bf16 v[38:41], v[146:149], v[170:173], v[38:41]
	v_mfma_f32_16x16x32_bf16 v[38:41], v[150:153], v[184:187], v[38:41]
	v_mfma_f32_16x16x32_bf16 v[34:37], v[154:157], v[170:173], v[34:37]
	v_mfma_f32_16x16x32_bf16 v[34:37], v[158:161], v[184:187], v[34:37]
	v_mfma_f32_16x16x32_bf16 v[22:25], v[146:149], v[188:191], v[22:25]
	v_mfma_f32_16x16x32_bf16 v[22:25], v[150:153], v[192:195], v[22:25]
	v_mfma_f32_16x16x32_bf16 v[18:21], v[154:157], v[188:191], v[18:21]
	v_mfma_f32_16x16x32_bf16 v[18:21], v[158:161], v[192:195], v[18:21]
	v_mfma_f32_16x16x32_bf16 v[6:9], v[146:149], v[196:199], v[6:9]
	v_mfma_f32_16x16x32_bf16 v[6:9], v[150:153], v[200:203], v[6:9]
	v_mfma_f32_16x16x32_bf16 v[2:5], v[154:157], v[196:199], v[2:5]
	v_mfma_f32_16x16x32_bf16 v[2:5], v[158:161], v[200:203], v[2:5]
	s_setprio 0
	s_barrier
	s_add_i32 s67, s67, 2
	s_add_u32 s11, s11, 0x10000
	s_addc_u32 s59, s59, 0
	s_add_u32 s64, s64, 0x10000
	s_addc_u32 s65, s65, 0
	s_add_u32 s20, s20, 0x10000
	s_addc_u32 s21, s21, 0
	s_cmpk_gt_u32 s67, 0x55
	s_cbranch_scc0 .LBB0_462
	s_and_b64 vcc, exec, s[16:17]
	s_cbranch_vccz .LBB0_465
	s_barrier

; #define PG8_LDA(dst, b, h) do { _Pragma("unroll") for (int m = 0; m < 4; ++m) _Pragma("unroll") for (int k = 0; k < 2; ++k) dst[m][k] = *(const PG8_LAS bf16x8*)(lds + PG8_SA(b, h) + aoff + m * 2048 + k * 1024); } while (0)
; #define PG8_LDB(dst, b, h) do { _Pragma("unroll") for (int n = 0; n < 2; ++n) _Pragma("unroll") for (int k = 0; k < 2; ++k) dst[n][k] = *(const PG8_LAS bf16x8*)(lds + PG8_SB(b, h) + boff + n * 2048 + k * 1024); } while (0)
; #define PG8_MMA(ai, bj, At, Bt) do { __builtin_amdgcn_s_setprio(1); _Pragma("unroll") for (int m = 0; m < 4; ++m) _Pragma("unroll") for (int n = 0; n < 2; ++n) _Pragma("unroll") for (int k = 0; k < 2; ++k) \
;         acc[ai][bj][m][n] = __builtin_amdgcn_mfma_f32_16x16x32_bf16(Bt[n][k], At[m][k], acc[ai][bj][m][n], 0, 0, 0); __builtin_amdgcn_s_setprio(0); } while (0)
; #define PG8_WAIT_V(n) asm volatile("s_waitcnt vmcnt(" #n ")" ::: "memory")
; #define PG8_WAIT_L(n) asm volatile("s_waitcnt lgkmcnt(" #n ")" ::: "memory")
; #define PG8_BAR __builtin_amdgcn_s_barrier()
; #define PG8_SCHED __builtin_amdgcn_sched_barrier(0)
;     __device__ __forceinline__ void a_ready(const Unit& u) const {
;         if (u.fill && tid < 256) {
;             const f32x4* p = (const f32x4*)(ssq + (size_t)(u.pm * BM + tid) * 32); float s = 0.f;
; #pragma unroll
;             for (int j = 0; j < 8; ++j) { const f32x4 a = p[j]; s += (a[0] + a[1]) + (a[2] + a[3]); }
;             tab[u.slot * 256 + tid] = __builtin_amdgcn_rsqf(s * inv_ncol + eps);
;         }
; template <class Epi, class Sched, bool ALIGN_EPI = false, bool SP2 = false>
; __device__ __forceinline__ void gemm_phase(PG8_LAS unsigned char* lds, const Gemm g, const Sched& S, const Epi& E, const int tid) {
;     ...
;             PG8_LDB(B0, 0, 0); PG8_LDB(B1, 0, 1); PG8_SCHED; PG8_LDA(At, 0, 0); PG8_STAGE(PG8_SA(1, 1), a1 + hstepA, voffA);
;             PG8_WAIT_V(8); PG8_WAIT_L(0); PG8_BAR; PG8_MMA(0, 0, At, B0); PG8_MMA(0, 1, At, B1); PG8_BAR; PG8_SCHED;
;             PG8_LDA(At, 0, 1); PG8_STAGE(PG8_SB(0, 0), b2, voffB); PG8_STAGE(PG8_SB(0, 1), b2 + hstepB, voffB); PG8_STAGE(PG8_SA(0, 0), a2, voffA);
;             PG8_WAIT_V(8); PG8_WAIT_L(0); PG8_BAR; PG8_MMA(1, 0, At, B0); PG8_MMA(1, 1, At, B1); PG8_BAR; PG8_SCHED;
.LBB0_546:
	s_or_b64 exec, exec, s[34:35]
	v_add_u32_e32 v133, 0x10000, v144
	ds_read_b128 v[146:149], v133
	ds_read_b128 v[150:153], v133 offset:1024
	ds_read_b128 v[154:157], v133 offset:2048
	ds_read_b128 v[158:161], v133 offset:3072
	v_add_u32_e32 v133, 0x14000, v144
	s_add_u32 s34, s28, 0x100
	ds_read_b128 v[162:165], v133
	ds_read_b128 v[166:169], v133 offset:1024
	ds_read_b128 v[170:173], v133 offset:2048
	ds_read_b128 v[174:177], v133 offset:3072
	s_addc_u32 s35, s29, 0
	s_and_b64 s[30:31], s[30:31], exec
	s_cselect_b32 s42, s95, s34
	s_cselect_b32 s43, s21, s35
	s_cselect_b32 s31, s19, s59
	s_cselect_b32 s30, s96, s97
	s_add_u32 s38, s42, 0x80
	s_addc_u32 s39, s43, 0
	s_add_u32 s40, s30, 0x80
	s_addc_u32 s41, s31, 0
	ds_read_b128 v[178:181], v145
	ds_read_b128 v[182:185], v145 offset:1024
	ds_read_b128 v[186:189], v145 offset:2048
	ds_read_b128 v[190:193], v145 offset:3072
	ds_read_b128 v[194:197], v145 offset:4096
	ds_read_b128 v[198:201], v145 offset:5120
	ds_read_b128 v[202:205], v145 offset:6144
	ds_read_b128 v[206:209], v145 offset:7168
	s_add_u32 s28, s28, 0x80080
	s_addc_u32 s29, s29, 0
	s_mov_b32 m0, s70
	s_nop 0
	global_load_lds_dwordx4 v136, s[28:29]
	s_nop 0
	s_mov_b32 m0, s78
	s_nop 0
	global_load_lds_dwordx4 v138, s[28:29]
	s_waitcnt vmcnt(8)
	s_waitcnt lgkmcnt(0)
	s_barrier
	s_setprio 1
	v_mfma_f32_16x16x32_bf16 v[126:129], v[146:149], v[178:181], v[126:129]
	v_mfma_f32_16x16x32_bf16 v[126:129], v[150:153], v[182:185], v[126:129]
	v_mfma_f32_16x16x32_bf16 v[122:125], v[154:157], v[178:181], v[122:125]
	v_mfma_f32_16x16x32_bf16 v[122:125], v[158:161], v[182:185], v[122:125]
	v_mfma_f32_16x16x32_bf16 v[118:121], v[146:149], v[186:189], v[118:121]
	v_mfma_f32_16x16x32_bf16 v[118:121], v[150:153], v[190:193], v[118:121]
	v_mfma_f32_16x16x32_bf16 v[110:113], v[154:157], v[186:189], v[110:113]
	v_mfma_f32_16x16x32_bf16 v[110:113], v[158:161], v[190:193], v[110:113]
	v_mfma_f32_16x16x32_bf16 v[102:105], v[146:149], v[194:197], v[102:105]
	v_mfma_f32_16x16x32_bf16 v[102:105], v[150:153], v[198:201], v[102:105]
	v_mfma_f32_16x16x32_bf16 v[94:97], v[154:157], v[194:197], v[94:97]
	v_mfma_f32_16x16x32_bf16 v[94:97], v[158:161], v[198:201], v[94:97]
	v_mfma_f32_16x16x32_bf16 v[86:89], v[146:149], v[202:205], v[86:89]
	v_mfma_f32_16x16x32_bf16 v[86:89], v[150:153], v[206:209], v[86:89]
	v_mfma_f32_16x16x32_bf16 v[78:81], v[154:157], v[202:205], v[78:81]
	v_mfma_f32_16x16x32_bf16 v[78:81], v[158:161], v[206:209], v[78:81]
	v_mfma_f32_16x16x32_bf16 v[114:117], v[162:165], v[178:181], v[114:117]
	v_mfma_f32_16x16x32_bf16 v[114:117], v[166:169], v[182:185], v[114:117]
	v_mfma_f32_16x16x32_bf16 v[106:109], v[170:173], v[178:181], v[106:109]
	v_mfma_f32_16x16x32_bf16 v[106:109], v[174:177], v[182:185], v[106:109]
	v_mfma_f32_16x16x32_bf16 v[98:101], v[162:165], v[186:189], v[98:101]
	v_mfma_f32_16x16x32_bf16 v[98:101], v[166:169], v[190:193], v[98:101]
	v_mfma_f32_16x16x32_bf16 v[90:93], v[170:173], v[186:189], v[90:93]
	v_mfma_f32_16x16x32_bf16 v[90:93], v[174:177], v[190:193], v[90:93]
	v_mfma_f32_16x16x32_bf16 v[82:85], v[162:165], v[194:197], v[82:85]
	v_mfma_f32_16x16x32_bf16 v[82:85], v[166:169], v[198:201], v[82:85]
	v_mfma_f32_16x16x32_bf16 v[74:77], v[170:173], v[194:197], v[74:77]
	v_mfma_f32_16x16x32_bf16 v[74:77], v[174:177], v[198:201], v[74:77]
	v_mfma_f32_16x16x32_bf16 v[70:73], v[162:165], v[202:205], v[70:73]
	v_mfma_f32_16x16x32_bf16 v[70:73], v[166:169], v[206:209], v[70:73]
	v_mfma_f32_16x16x32_bf16 v[66:69], v[170:173], v[202:205], v[66:69]
	v_mfma_f32_16x16x32_bf16 v[66:69], v[174:177], v[206:209], v[66:69]
	s_setprio 0
	s_barrier
	ds_read_b128 v[178:181], v145 offset:16384
	ds_read_b128 v[182:185], v145 offset:17408
	ds_read_b128 v[186:189], v145 offset:18432
	ds_read_b128 v[190:193], v145 offset:19456
	ds_read_b128 v[194:197], v145 offset:20480
	ds_read_b128 v[198:201], v145 offset:21504
	ds_read_b128 v[202:205], v145 offset:22528
	ds_read_b128 v[206:209], v145 offset:23552
	s_mov_b32 m0, s9
	s_nop 0
	global_load_lds_dwordx4 v137, s[30:31]
	s_add_u32 s28, s30, 0x80000
	s_mov_b32 m0, s49
	s_nop 0
	global_load_lds_dwordx4 v139, s[30:31]
	s_addc_u32 s29, s31, 0
	s_mov_b32 m0, s50
	s_nop 0
	global_load_lds_dwordx4 v137, s[28:29]
	s_nop 0
	s_mov_b32 m0, s51
	s_nop 0
	global_load_lds_dwordx4 v139, s[28:29]
	s_nop 0
	s_mov_b32 m0, s10
	s_nop 0
	global_load_lds_dwordx4 v136, s[42:43]
	s_nop 0
	s_mov_b32 m0, s54
	s_nop 0
	global_load_lds_dwordx4 v138, s[42:43]
	s_waitcnt vmcnt(8)
	s_waitcnt lgkmcnt(0)
	s_barrier
	s_setprio 1
	v_mfma_f32_16x16x32_bf16 v[62:65], v[146:149], v[178:181], v[62:65]
	v_mfma_f32_16x16x32_bf16 v[62:65], v[150:153], v[182:185], v[62:65]
	v_mfma_f32_16x16x32_bf16 v[58:61], v[154:157], v[178:181], v[58:61]
	v_mfma_f32_16x16x32_bf16 v[58:61], v[158:161], v[182:185], v[58:61]
	v_mfma_f32_16x16x32_bf16 v[54:57], v[146:149], v[186:189], v[54:57]
	v_mfma_f32_16x16x32_bf16 v[54:57], v[150:153], v[190:193], v[54:57]
	v_mfma_f32_16x16x32_bf16 v[46:49], v[154:157], v[186:189], v[46:49]
	v_mfma_f32_16x16x32_bf16 v[46:49], v[158:161], v[190:193], v[46:49]
	v_mfma_f32_16x16x32_bf16 v[38:41], v[146:149], v[194:197], v[38:41]
	v_mfma_f32_16x16x32_bf16 v[38:41], v[150:153], v[198:201], v[38:41]
	v_mfma_f32_16x16x32_bf16 v[30:33], v[154:157], v[194:197], v[30:33]
	v_mfma_f32_16x16x32_bf16 v[30:33], v[158:161], v[198:201], v[30:33]
	v_mfma_f32_16x16x32_bf16 v[22:25], v[146:149], v[202:205], v[22:25]
	v_mfma_f32_16x16x32_bf16 v[22:25], v[150:153], v[206:209], v[22:25]
	v_mfma_f32_16x16x32_bf16 v[14:17], v[154:157], v[202:205], v[14:17]
	v_mfma_f32_16x16x32_bf16 v[14:17], v[158:161], v[206:209], v[14:17]
	v_mfma_f32_16x16x32_bf16 v[50:53], v[162:165], v[178:181], v[50:53]
	v_mfma_f32_16x16x32_bf16 v[50:53], v[166:169], v[182:185], v[50:53]
	v_mfma_f32_16x16x32_bf16 v[42:45], v[170:173], v[178:181], v[42:45]
	v_mfma_f32_16x16x32_bf16 v[42:45], v[174:177], v[182:185], v[42:45]
	v_mfma_f32_16x16x32_bf16 v[34:37], v[162:165], v[186:189], v[34:37]
	v_mfma_f32_16x16x32_bf16 v[34:37], v[166:169], v[190:193], v[34:37]
	v_mfma_f32_16x16x32_bf16 v[26:29], v[170:173], v[186:189], v[26:29]
	v_mfma_f32_16x16x32_bf16 v[26:29], v[174:177], v[190:193], v[26:29]
	v_mfma_f32_16x16x32_bf16 v[18:21], v[162:165], v[194:197], v[18:21]
	v_mfma_f32_16x16x32_bf16 v[18:21], v[166:169], v[198:201], v[18:21]
	v_mfma_f32_16x16x32_bf16 v[10:13], v[170:173], v[194:197], v[10:13]
	v_mfma_f32_16x16x32_bf16 v[10:13], v[174:177], v[198:201], v[10:13]
	v_mfma_f32_16x16x32_bf16 v[6:9], v[162:165], v[202:205], v[6:9]
	v_mfma_f32_16x16x32_bf16 v[6:9], v[166:169], v[206:209], v[6:9]
	v_mfma_f32_16x16x32_bf16 v[2:5], v[170:173], v[202:205], v[2:5]
	v_mfma_f32_16x16x32_bf16 v[2:5], v[174:177], v[206:209], v[2:5]
	s_setprio 0
	s_barrier
; #define PG8_LDA(dst, b, h) do { _Pragma("unroll") for (int m = 0; m < 4; ++m) _Pragma("unroll") for (int k = 0; k < 2; ++k) dst[m][k] = *(const PG8_LAS bf16x8*)(lds + PG8_SA(b, h) + aoff + m * 2048 + k * 1024); } while (0)
; #define PG8_LDB(dst, b, h) do { _Pragma("unroll") for (int n = 0; n < 2; ++n) _Pragma("unroll") for (int k = 0; k < 2; ++k) dst[n][k] = *(const PG8_LAS bf16x8*)(lds + PG8_SB(b, h) + boff + n * 2048 + k * 1024); } while (0)
; #define PG8_MMA(ai, bj, At, Bt) do { __builtin_amdgcn_s_setprio(1); _Pragma("unroll") for (int m = 0; m < 4; ++m) _Pragma("unroll") for (int n = 0; n < 2; ++n) _Pragma("unroll") for (int k = 0; k < 2; ++k) \
;         acc[ai][bj][m][n] = __builtin_amdgcn_mfma_f32_16x16x32_bf16(Bt[n][k], At[m][k], acc[ai][bj][m][n], 0, 0, 0); __builtin_amdgcn_s_setprio(0); } while (0)
; #define PG8_WAIT_V(n) asm volatile("s_waitcnt vmcnt(" #n ")" ::: "memory")
; #define PG8_WAIT_L(n) asm volatile("s_waitcnt lgkmcnt(" #n ")" ::: "memory")
; #define PG8_BAR __builtin_amdgcn_s_barrier()
; #define PG8_SCHED __builtin_amdgcn_sched_barrier(0)
; template <class Epi, class Sched, bool ALIGN_EPI = false, bool SP2 = false>
; __device__ __forceinline__ void gemm_phase(PG8_LAS unsigned char* lds, const Gemm g, const Sched& S, const Epi& E, const int tid) {
;     ...
;             PG8_LDB(B0, 1, 0); PG8_LDB(B1, 1, 1); PG8_SCHED; PG8_LDA(At, 1, 0); PG8_STAGE(PG8_SA(0, 1), a2 + hstepA, voffA);
;             PG8_WAIT_V(8); PG8_WAIT_L(0); PG8_BAR; PG8_MMA(0, 0, At, B0); PG8_MMA(0, 1, At, B1); PG8_BAR; PG8_SCHED;
;             PG8_LDA(At, 1, 1); PG8_STAGE(PG8_SB(1, 0), b3, voffB); PG8_STAGE(PG8_SB(1, 1), b3 + hstepB, voffB); PG8_STAGE(PG8_SA(1, 0), a3, voffA);
;             PG8_WAIT_V(8); PG8_WAIT_L(0); PG8_BAR; PG8_MMA(1, 0, At, B0); PG8_MMA(1, 1, At, B1); PG8_BAR; PG8_SCHED;
	v_add_u32_e32 v133, 0x18000, v144
	ds_read_b128 v[146:149], v133
	ds_read_b128 v[150:153], v133 offset:1024
	ds_read_b128 v[154:157], v133 offset:2048
	ds_read_b128 v[158:161], v133 offset:3072
	v_add_u32_e32 v133, 0x1c000, v144
	ds_read_b128 v[162:165], v133
	ds_read_b128 v[166:169], v133 offset:1024
	ds_read_b128 v[170:173], v133 offset:2048
	ds_read_b128 v[174:177], v133 offset:3072
	ds_read_b128 v[178:181], v145 offset:32768
	ds_read_b128 v[182:185], v145 offset:33792
	ds_read_b128 v[186:189], v145 offset:34816
	ds_read_b128 v[190:193], v145 offset:35840
	ds_read_b128 v[194:197], v145 offset:36864
	ds_read_b128 v[198:201], v145 offset:37888
	ds_read_b128 v[202:205], v145 offset:38912
	ds_read_b128 v[206:209], v145 offset:39936
	s_add_u32 s28, s42, 0x80000
	s_addc_u32 s29, s43, 0
	s_mov_b32 m0, s55
	s_nop 0
	global_load_lds_dwordx4 v136, s[28:29]
	s_nop 0
	s_mov_b32 m0, s56
	s_nop 0
	global_load_lds_dwordx4 v138, s[28:29]
	s_waitcnt vmcnt(8)
	s_waitcnt lgkmcnt(0)
	s_barrier
	s_setprio 1
	v_mfma_f32_16x16x32_bf16 v[126:129], v[146:149], v[178:181], v[126:129]
	v_mfma_f32_16x16x32_bf16 v[126:129], v[150:153], v[182:185], v[126:129]
	v_mfma_f32_16x16x32_bf16 v[122:125], v[154:157], v[178:181], v[122:125]
	v_mfma_f32_16x16x32_bf16 v[122:125], v[158:161], v[182:185], v[122:125]
	v_mfma_f32_16x16x32_bf16 v[118:121], v[146:149], v[186:189], v[118:121]
	v_mfma_f32_16x16x32_bf16 v[118:121], v[150:153], v[190:193], v[118:121]
	v_mfma_f32_16x16x32_bf16 v[110:113], v[154:157], v[186:189], v[110:113]
	v_mfma_f32_16x16x32_bf16 v[110:113], v[158:161], v[190:193], v[110:113]
	v_mfma_f32_16x16x32_bf16 v[102:105], v[146:149], v[194:197], v[102:105]
	v_mfma_f32_16x16x32_bf16 v[102:105], v[150:153], v[198:201], v[102:105]
	v_mfma_f32_16x16x32_bf16 v[94:97], v[154:157], v[194:197], v[94:97]
	v_mfma_f32_16x16x32_bf16 v[94:97], v[158:161], v[198:201], v[94:97]
	v_mfma_f32_16x16x32_bf16 v[86:89], v[146:149], v[202:205], v[86:89]
	v_mfma_f32_16x16x32_bf16 v[86:89], v[150:153], v[206:209], v[86:89]
	v_mfma_f32_16x16x32_bf16 v[78:81], v[154:157], v[202:205], v[78:81]
	v_mfma_f32_16x16x32_bf16 v[78:81], v[158:161], v[206:209], v[78:81]
	v_mfma_f32_16x16x32_bf16 v[114:117], v[162:165], v[178:181], v[114:117]
	v_mfma_f32_16x16x32_bf16 v[114:117], v[166:169], v[182:185], v[114:117]
	v_mfma_f32_16x16x32_bf16 v[106:109], v[170:173], v[178:181], v[106:109]
	v_mfma_f32_16x16x32_bf16 v[106:109], v[174:177], v[182:185], v[106:109]
	v_mfma_f32_16x16x32_bf16 v[98:101], v[162:165], v[186:189], v[98:101]
	v_mfma_f32_16x16x32_bf16 v[98:101], v[166:169], v[190:193], v[98:101]
	v_mfma_f32_16x16x32_bf16 v[90:93], v[170:173], v[186:189], v[90:93]
	v_mfma_f32_16x16x32_bf16 v[90:93], v[174:177], v[190:193], v[90:93]
	v_mfma_f32_16x16x32_bf16 v[82:85], v[162:165], v[194:197], v[82:85]
	v_mfma_f32_16x16x32_bf16 v[82:85], v[166:169], v[198:201], v[82:85]
	v_mfma_f32_16x16x32_bf16 v[74:77], v[170:173], v[194:197], v[74:77]
	v_mfma_f32_16x16x32_bf16 v[74:77], v[174:177], v[198:201], v[74:77]
	v_mfma_f32_16x16x32_bf16 v[70:73], v[162:165], v[202:205], v[70:73]
	v_mfma_f32_16x16x32_bf16 v[70:73], v[166:169], v[206:209], v[70:73]
	v_mfma_f32_16x16x32_bf16 v[66:69], v[170:173], v[202:205], v[66:69]
	v_mfma_f32_16x16x32_bf16 v[66:69], v[174:177], v[206:209], v[66:69]
	s_setprio 0
	s_barrier
	ds_read_b128 v[178:181], v145 offset:49152
	ds_read_b128 v[182:185], v145 offset:50176
	ds_read_b128 v[186:189], v145 offset:51200
	ds_read_b128 v[190:193], v145 offset:52224
	ds_read_b128 v[194:197], v145 offset:53248
	ds_read_b128 v[198:201], v145 offset:54272
	ds_read_b128 v[202:205], v145 offset:55296
	ds_read_b128 v[206:209], v145 offset:56320
	s_mov_b32 m0, s57
	s_nop 0
	global_load_lds_dwordx4 v137, s[40:41]
	s_add_u32 s28, s30, 0x80080
	s_mov_b32 m0, s58
	s_nop 0
	global_load_lds_dwordx4 v139, s[40:41]
	s_addc_u32 s29, s31, 0
	s_mov_b32 m0, s65
	s_nop 0
	global_load_lds_dwordx4 v137, s[28:29]
	s_nop 0
	s_mov_b32 m0, s69
	s_nop 0
	global_load_lds_dwordx4 v139, s[28:29]
	s_nop 0
	s_mov_b32 m0, s61
	s_nop 0
	global_load_lds_dwordx4 v136, s[38:39]
	s_nop 0
	s_mov_b32 m0, s64
	s_nop 0
	global_load_lds_dwordx4 v138, s[38:39]
	s_waitcnt vmcnt(8)
	s_waitcnt lgkmcnt(0)
	s_barrier
	s_setprio 1
	v_mfma_f32_16x16x32_bf16 v[62:65], v[146:149], v[178:181], v[62:65]
	v_mfma_f32_16x16x32_bf16 v[62:65], v[150:153], v[182:185], v[62:65]
	v_mfma_f32_16x16x32_bf16 v[58:61], v[154:157], v[178:181], v[58:61]
	v_mfma_f32_16x16x32_bf16 v[58:61], v[158:161], v[182:185], v[58:61]
	v_mfma_f32_16x16x32_bf16 v[54:57], v[146:149], v[186:189], v[54:57]
	v_mfma_f32_16x16x32_bf16 v[54:57], v[150:153], v[190:193], v[54:57]
	v_mfma_f32_16x16x32_bf16 v[46:49], v[154:157], v[186:189], v[46:49]
	v_mfma_f32_16x16x32_bf16 v[46:49], v[158:161], v[190:193], v[46:49]
	v_mfma_f32_16x16x32_bf16 v[38:41], v[146:149], v[194:197], v[38:41]
	v_mfma_f32_16x16x32_bf16 v[38:41], v[150:153], v[198:201], v[38:41]
	v_mfma_f32_16x16x32_bf16 v[30:33], v[154:157], v[194:197], v[30:33]
	v_mfma_f32_16x16x32_bf16 v[30:33], v[158:161], v[198:201], v[30:33]
	v_mfma_f32_16x16x32_bf16 v[22:25], v[146:149], v[202:205], v[22:25]
	v_mfma_f32_16x16x32_bf16 v[22:25], v[150:153], v[206:209], v[22:25]
	v_mfma_f32_16x16x32_bf16 v[14:17], v[154:157], v[202:205], v[14:17]
	v_mfma_f32_16x16x32_bf16 v[14:17], v[158:161], v[206:209], v[14:17]
	v_mfma_f32_16x16x32_bf16 v[50:53], v[162:165], v[178:181], v[50:53]
	v_mfma_f32_16x16x32_bf16 v[50:53], v[166:169], v[182:185], v[50:53]
	v_mfma_f32_16x16x32_bf16 v[42:45], v[170:173], v[178:181], v[42:45]
	v_mfma_f32_16x16x32_bf16 v[42:45], v[174:177], v[182:185], v[42:45]
	v_mfma_f32_16x16x32_bf16 v[34:37], v[162:165], v[186:189], v[34:37]
	v_mfma_f32_16x16x32_bf16 v[34:37], v[166:169], v[190:193], v[34:37]
	v_mfma_f32_16x16x32_bf16 v[26:29], v[170:173], v[186:189], v[26:29]
	v_mfma_f32_16x16x32_bf16 v[26:29], v[174:177], v[190:193], v[26:29]
	v_mfma_f32_16x16x32_bf16 v[18:21], v[162:165], v[194:197], v[18:21]
	v_mfma_f32_16x16x32_bf16 v[18:21], v[166:169], v[198:201], v[18:21]
	v_mfma_f32_16x16x32_bf16 v[10:13], v[170:173], v[194:197], v[10:13]
	v_mfma_f32_16x16x32_bf16 v[10:13], v[174:177], v[198:201], v[10:13]
	v_mfma_f32_16x16x32_bf16 v[6:9], v[162:165], v[202:205], v[6:9]
	v_mfma_f32_16x16x32_bf16 v[6:9], v[166:169], v[206:209], v[6:9]
	v_mfma_f32_16x16x32_bf16 v[2:5], v[170:173], v[202:205], v[2:5]
	v_mfma_f32_16x16x32_bf16 v[2:5], v[174:177], v[206:209], v[2:5]
	s_setprio 0
	s_barrier
	s_add_i32 s67, s67, 2
	s_add_u32 s97, s97, 0x100
	s_addc_u32 s59, s59, 0
	s_cmp_gt_u32 s67, 29
	s_mov_b64 s[28:29], s[34:35]
	s_cbranch_scc1 .LBB0_549

; #define PG8_LDA(dst, b, h) do { _Pragma("unroll") for (int m = 0; m < 4; ++m) _Pragma("unroll") for (int k = 0; k < 2; ++k) dst[m][k] = *(const PG8_LAS bf16x8*)(lds + PG8_SA(b, h) + aoff + m * 2048 + k * 1024); } while (0)
; #define PG8_LDB(dst, b, h) do { _Pragma("unroll") for (int n = 0; n < 2; ++n) _Pragma("unroll") for (int k = 0; k < 2; ++k) dst[n][k] = *(const PG8_LAS bf16x8*)(lds + PG8_SB(b, h) + boff + n * 2048 + k * 1024); } while (0)
; #define PG8_MMA(ai, bj, At, Bt) do { __builtin_amdgcn_s_setprio(1); _Pragma("unroll") for (int m = 0; m < 4; ++m) _Pragma("unroll") for (int n = 0; n < 2; ++n) _Pragma("unroll") for (int k = 0; k < 2; ++k) \
;         acc[ai][bj][m][n] = __builtin_amdgcn_mfma_f32_16x16x32_bf16(Bt[n][k], At[m][k], acc[ai][bj][m][n], 0, 0, 0); __builtin_amdgcn_s_setprio(0); } while (0)
; #define PG8_WAIT_V(n) asm volatile("s_waitcnt vmcnt(" #n ")" ::: "memory")
; #define PG8_WAIT_L(n) asm volatile("s_waitcnt lgkmcnt(" #n ")" ::: "memory")
; #define PG8_BAR __builtin_amdgcn_s_barrier()
; #define PG8_SCHED __builtin_amdgcn_sched_barrier(0)
; template <class Epi, class Sched, bool ALIGN_EPI = false, bool SP2 = false>
; __device__ __forceinline__ void gemm_phase(PG8_LAS unsigned char* lds, const Gemm g, const Sched& S, const Epi& E, const int tid) {
;     ...
;             PG8_LDB(B0, 0, 0); PG8_LDB(B1, 0, 1); PG8_SCHED; PG8_LDA(At, 0, 0); PG8_STAGE(PG8_SA(1, 1), a1 + hstepA, voffA);
;             PG8_WAIT_V(8); PG8_WAIT_L(0); PG8_BAR; PG8_MMA(0, 0, At, B0); PG8_MMA(0, 1, At, B1); PG8_BAR; PG8_SCHED;
;             PG8_LDA(At, 0, 1); PG8_STAGE(PG8_SB(0, 0), b2, voffB); PG8_STAGE(PG8_SB(0, 1), b2 + hstepB, voffB); PG8_STAGE(PG8_SA(0, 0), a2, voffA);
;             PG8_WAIT_V(8); PG8_WAIT_L(0); PG8_BAR; PG8_MMA(1, 0, At, B0); PG8_MMA(1, 1, At, B1); PG8_BAR; PG8_SCHED;
.LBB0_813:
	v_add_u32_e32 v0, 0x10000, v135
	ds_read_b128 v[138:141], v0
	ds_read_b128 v[142:145], v0 offset:1024
	ds_read_b128 v[146:149], v0 offset:2048
	ds_read_b128 v[150:153], v0 offset:3072
	v_add_u32_e32 v0, 0x14000, v135
	ds_read_b128 v[154:157], v0
	ds_read_b128 v[158:161], v0 offset:1024
	ds_read_b128 v[162:165], v0 offset:2048
	ds_read_b128 v[166:169], v0 offset:3072
	s_add_u32 s4, s18, 0x100
	s_addc_u32 s5, s19, 0
	s_cmp_eq_u32 s61, 12
	s_cselect_b32 s24, s14, s4
	s_cselect_b32 s25, s15, s5
	s_cselect_b32 s22, s57, s58
	s_cselect_b32 s23, s13, s59
	s_add_u32 s20, s24, 0x80
	s_addc_u32 s21, s25, 0
	ds_read_b128 v[170:173], v136
	ds_read_b128 v[174:177], v136 offset:1024
	ds_read_b128 v[178:181], v136 offset:2048
	ds_read_b128 v[182:185], v136 offset:3072
	ds_read_b128 v[186:189], v136 offset:4096
	ds_read_b128 v[190:193], v136 offset:5120
	ds_read_b128 v[194:197], v136 offset:6144
	ds_read_b128 v[198:201], v136 offset:7168
	s_add_u32 s18, s18, 0xc0080
	s_addc_u32 s19, s19, 0
	s_mov_b32 m0, s49
	s_nop 0
	global_load_lds_dwordx4 v131, s[18:19]
	s_nop 0
	s_mov_b32 m0, s50
	s_nop 0
	global_load_lds_dwordx4 v133, s[18:19]
	s_waitcnt vmcnt(8)
	s_waitcnt lgkmcnt(0)
	s_barrier
	s_setprio 1
	v_mfma_f32_16x16x32_bf16 v[126:129], v[138:141], v[170:173], v[126:129]
	v_mfma_f32_16x16x32_bf16 v[126:129], v[142:145], v[174:177], v[126:129]
	v_mfma_f32_16x16x32_bf16 v[122:125], v[146:149], v[170:173], v[122:125]
	v_mfma_f32_16x16x32_bf16 v[122:125], v[150:153], v[174:177], v[122:125]
	v_mfma_f32_16x16x32_bf16 v[118:121], v[138:141], v[178:181], v[118:121]
	v_mfma_f32_16x16x32_bf16 v[118:121], v[142:145], v[182:185], v[118:121]
	v_mfma_f32_16x16x32_bf16 v[114:117], v[146:149], v[178:181], v[114:117]
	v_mfma_f32_16x16x32_bf16 v[114:117], v[150:153], v[182:185], v[114:117]
	v_mfma_f32_16x16x32_bf16 v[102:105], v[138:141], v[186:189], v[102:105]
	v_mfma_f32_16x16x32_bf16 v[102:105], v[142:145], v[190:193], v[102:105]
	v_mfma_f32_16x16x32_bf16 v[98:101], v[146:149], v[186:189], v[98:101]
	v_mfma_f32_16x16x32_bf16 v[98:101], v[150:153], v[190:193], v[98:101]
	v_mfma_f32_16x16x32_bf16 v[86:89], v[138:141], v[194:197], v[86:89]
	v_mfma_f32_16x16x32_bf16 v[86:89], v[142:145], v[198:201], v[86:89]
	v_mfma_f32_16x16x32_bf16 v[82:85], v[146:149], v[194:197], v[82:85]
	v_mfma_f32_16x16x32_bf16 v[82:85], v[150:153], v[198:201], v[82:85]
	v_mfma_f32_16x16x32_bf16 v[110:113], v[154:157], v[170:173], v[110:113]
	v_mfma_f32_16x16x32_bf16 v[110:113], v[158:161], v[174:177], v[110:113]
	v_mfma_f32_16x16x32_bf16 v[106:109], v[162:165], v[170:173], v[106:109]
	v_mfma_f32_16x16x32_bf16 v[106:109], v[166:169], v[174:177], v[106:109]
	v_mfma_f32_16x16x32_bf16 v[94:97], v[154:157], v[178:181], v[94:97]
	v_mfma_f32_16x16x32_bf16 v[94:97], v[158:161], v[182:185], v[94:97]
	v_mfma_f32_16x16x32_bf16 v[90:93], v[162:165], v[178:181], v[90:93]
	v_mfma_f32_16x16x32_bf16 v[90:93], v[166:169], v[182:185], v[90:93]
	v_mfma_f32_16x16x32_bf16 v[78:81], v[154:157], v[186:189], v[78:81]
	v_mfma_f32_16x16x32_bf16 v[78:81], v[158:161], v[190:193], v[78:81]
	v_mfma_f32_16x16x32_bf16 v[74:77], v[162:165], v[186:189], v[74:77]
	v_mfma_f32_16x16x32_bf16 v[74:77], v[166:169], v[190:193], v[74:77]
	v_mfma_f32_16x16x32_bf16 v[70:73], v[154:157], v[194:197], v[70:73]
	v_mfma_f32_16x16x32_bf16 v[70:73], v[158:161], v[198:201], v[70:73]
	v_mfma_f32_16x16x32_bf16 v[66:69], v[162:165], v[194:197], v[66:69]
	v_mfma_f32_16x16x32_bf16 v[66:69], v[166:169], v[198:201], v[66:69]
	s_setprio 0
	s_barrier
	ds_read_b128 v[170:173], v136 offset:16384
	ds_read_b128 v[174:177], v136 offset:17408
	ds_read_b128 v[178:181], v136 offset:18432
	ds_read_b128 v[182:185], v136 offset:19456
	ds_read_b128 v[186:189], v136 offset:20480
	ds_read_b128 v[190:193], v136 offset:21504
	ds_read_b128 v[194:197], v136 offset:22528
	ds_read_b128 v[198:201], v136 offset:23552
	s_mov_b32 m0, s31
	s_nop 0
	global_load_lds_dwordx4 v132, s[22:23]
	s_nop 0
	s_mov_b32 m0, s34
	s_nop 0
	global_load_lds_dwordx4 v134, s[22:23]
	s_add_u32 s18, s22, 0x40000
	s_addc_u32 s19, s23, 0
	s_mov_b32 m0, s35
	s_nop 0
	global_load_lds_dwordx4 v132, s[18:19]
	s_nop 0
	s_mov_b32 m0, s37
	s_nop 0
	global_load_lds_dwordx4 v134, s[18:19]
	s_mov_b32 m0, s10
	s_nop 0
	global_load_lds_dwordx4 v131, s[24:25]
	s_nop 0
	s_mov_b32 m0, s38
	s_nop 0
	global_load_lds_dwordx4 v133, s[24:25]
	s_waitcnt vmcnt(8)
	s_waitcnt lgkmcnt(0)
	s_barrier
	s_setprio 1
	v_mfma_f32_16x16x32_bf16 v[62:65], v[138:141], v[170:173], v[62:65]
	v_mfma_f32_16x16x32_bf16 v[62:65], v[142:145], v[174:177], v[62:65]
	v_mfma_f32_16x16x32_bf16 v[58:61], v[146:149], v[170:173], v[58:61]
	v_mfma_f32_16x16x32_bf16 v[58:61], v[150:153], v[174:177], v[58:61]
	v_mfma_f32_16x16x32_bf16 v[54:57], v[138:141], v[178:181], v[54:57]
	v_mfma_f32_16x16x32_bf16 v[54:57], v[142:145], v[182:185], v[54:57]
	v_mfma_f32_16x16x32_bf16 v[50:53], v[146:149], v[178:181], v[50:53]
	v_mfma_f32_16x16x32_bf16 v[50:53], v[150:153], v[182:185], v[50:53]
	v_mfma_f32_16x16x32_bf16 v[38:41], v[138:141], v[186:189], v[38:41]
	v_mfma_f32_16x16x32_bf16 v[38:41], v[142:145], v[190:193], v[38:41]
	v_mfma_f32_16x16x32_bf16 v[34:37], v[146:149], v[186:189], v[34:37]
	v_mfma_f32_16x16x32_bf16 v[34:37], v[150:153], v[190:193], v[34:37]
	v_mfma_f32_16x16x32_bf16 v[22:25], v[138:141], v[194:197], v[22:25]
	v_mfma_f32_16x16x32_bf16 v[22:25], v[142:145], v[198:201], v[22:25]
	v_mfma_f32_16x16x32_bf16 v[18:21], v[146:149], v[194:197], v[18:21]
	v_mfma_f32_16x16x32_bf16 v[18:21], v[150:153], v[198:201], v[18:21]
	v_mfma_f32_16x16x32_bf16 v[46:49], v[154:157], v[170:173], v[46:49]
	v_mfma_f32_16x16x32_bf16 v[46:49], v[158:161], v[174:177], v[46:49]
	v_mfma_f32_16x16x32_bf16 v[42:45], v[162:165], v[170:173], v[42:45]
	v_mfma_f32_16x16x32_bf16 v[42:45], v[166:169], v[174:177], v[42:45]
	v_mfma_f32_16x16x32_bf16 v[30:33], v[154:157], v[178:181], v[30:33]
	v_mfma_f32_16x16x32_bf16 v[30:33], v[158:161], v[182:185], v[30:33]
	v_mfma_f32_16x16x32_bf16 v[26:29], v[162:165], v[178:181], v[26:29]
	v_mfma_f32_16x16x32_bf16 v[26:29], v[166:169], v[182:185], v[26:29]
	v_mfma_f32_16x16x32_bf16 v[14:17], v[154:157], v[186:189], v[14:17]
	v_mfma_f32_16x16x32_bf16 v[14:17], v[158:161], v[190:193], v[14:17]
	v_mfma_f32_16x16x32_bf16 v[10:13], v[162:165], v[186:189], v[10:13]
	v_mfma_f32_16x16x32_bf16 v[10:13], v[166:169], v[190:193], v[10:13]
	v_mfma_f32_16x16x32_bf16 v[6:9], v[154:157], v[194:197], v[6:9]
	v_mfma_f32_16x16x32_bf16 v[6:9], v[158:161], v[198:201], v[6:9]
	v_mfma_f32_16x16x32_bf16 v[2:5], v[162:165], v[194:197], v[2:5]
	v_mfma_f32_16x16x32_bf16 v[2:5], v[166:169], v[198:201], v[2:5]
	s_setprio 0
	s_barrier
; #define PG8_LDA(dst, b, h) do { _Pragma("unroll") for (int m = 0; m < 4; ++m) _Pragma("unroll") for (int k = 0; k < 2; ++k) dst[m][k] = *(const PG8_LAS bf16x8*)(lds + PG8_SA(b, h) + aoff + m * 2048 + k * 1024); } while (0)
; #define PG8_LDB(dst, b, h) do { _Pragma("unroll") for (int n = 0; n < 2; ++n) _Pragma("unroll") for (int k = 0; k < 2; ++k) dst[n][k] = *(const PG8_LAS bf16x8*)(lds + PG8_SB(b, h) + boff + n * 2048 + k * 1024); } while (0)
; #define PG8_MMA(ai, bj, At, Bt) do { __builtin_amdgcn_s_setprio(1); _Pragma("unroll") for (int m = 0; m < 4; ++m) _Pragma("unroll") for (int n = 0; n < 2; ++n) _Pragma("unroll") for (int k = 0; k < 2; ++k) \
;         acc[ai][bj][m][n] = __builtin_amdgcn_mfma_f32_16x16x32_bf16(Bt[n][k], At[m][k], acc[ai][bj][m][n], 0, 0, 0); __builtin_amdgcn_s_setprio(0); } while (0)
; #define PG8_WAIT_V(n) asm volatile("s_waitcnt vmcnt(" #n ")" ::: "memory")
; #define PG8_WAIT_L(n) asm volatile("s_waitcnt lgkmcnt(" #n ")" ::: "memory")
; #define PG8_BAR __builtin_amdgcn_s_barrier()
; #define PG8_SCHED __builtin_amdgcn_sched_barrier(0)
; template <class Epi, class Sched, bool ALIGN_EPI = false, bool SP2 = false>
; __device__ __forceinline__ void gemm_phase(PG8_LAS unsigned char* lds, const Gemm g, const Sched& S, const Epi& E, const int tid) {
;     ...
;             PG8_LDB(B0, 1, 0); PG8_LDB(B1, 1, 1); PG8_SCHED; PG8_LDA(At, 1, 0); PG8_STAGE(PG8_SA(0, 1), a2 + hstepA, voffA);
;             PG8_WAIT_V(8); PG8_WAIT_L(0); PG8_BAR; PG8_MMA(0, 0, At, B0); PG8_MMA(0, 1, At, B1); PG8_BAR; PG8_SCHED;
;             PG8_LDA(At, 1, 1); PG8_STAGE(PG8_SB(1, 0), b3, voffB); PG8_STAGE(PG8_SB(1, 1), b3 + hstepB, voffB); PG8_STAGE(PG8_SA(1, 0), a3, voffA);
;             PG8_WAIT_V(8); PG8_WAIT_L(0); PG8_BAR; PG8_MMA(1, 0, At, B0); PG8_MMA(1, 1, At, B1); PG8_BAR; PG8_SCHED;
	v_add_u32_e32 v0, 0x18000, v135
	ds_read_b128 v[138:141], v0
	ds_read_b128 v[142:145], v0 offset:1024
	ds_read_b128 v[146:149], v0 offset:2048
	ds_read_b128 v[150:153], v0 offset:3072
	v_add_u32_e32 v0, 0x1c000, v135
	ds_read_b128 v[154:157], v0
	ds_read_b128 v[158:161], v0 offset:1024
	ds_read_b128 v[162:165], v0 offset:2048
	ds_read_b128 v[166:169], v0 offset:3072
	ds_read_b128 v[170:173], v136 offset:32768
	ds_read_b128 v[174:177], v136 offset:33792
	ds_read_b128 v[178:181], v136 offset:34816
	ds_read_b128 v[182:185], v136 offset:35840
	ds_read_b128 v[186:189], v136 offset:36864
	ds_read_b128 v[190:193], v136 offset:37888
	ds_read_b128 v[194:197], v136 offset:38912
	ds_read_b128 v[198:201], v136 offset:39936
	s_add_u32 s18, s24, 0xc0000
	s_addc_u32 s19, s25, 0
	s_mov_b32 m0, s39
	s_nop 0
	global_load_lds_dwordx4 v131, s[18:19]
	s_nop 0
	s_mov_b32 m0, s40
	s_nop 0
	global_load_lds_dwordx4 v133, s[18:19]
	s_waitcnt vmcnt(8)
	s_waitcnt lgkmcnt(0)
	s_barrier
	s_setprio 1
	v_mfma_f32_16x16x32_bf16 v[126:129], v[138:141], v[170:173], v[126:129]
	v_mfma_f32_16x16x32_bf16 v[126:129], v[142:145], v[174:177], v[126:129]
	v_mfma_f32_16x16x32_bf16 v[122:125], v[146:149], v[170:173], v[122:125]
	v_mfma_f32_16x16x32_bf16 v[122:125], v[150:153], v[174:177], v[122:125]
	v_mfma_f32_16x16x32_bf16 v[118:121], v[138:141], v[178:181], v[118:121]
	v_mfma_f32_16x16x32_bf16 v[118:121], v[142:145], v[182:185], v[118:121]
	v_mfma_f32_16x16x32_bf16 v[114:117], v[146:149], v[178:181], v[114:117]
	v_mfma_f32_16x16x32_bf16 v[114:117], v[150:153], v[182:185], v[114:117]
	v_mfma_f32_16x16x32_bf16 v[102:105], v[138:141], v[186:189], v[102:105]
	v_mfma_f32_16x16x32_bf16 v[102:105], v[142:145], v[190:193], v[102:105]
	v_mfma_f32_16x16x32_bf16 v[98:101], v[146:149], v[186:189], v[98:101]
	v_mfma_f32_16x16x32_bf16 v[98:101], v[150:153], v[190:193], v[98:101]
	v_mfma_f32_16x16x32_bf16 v[86:89], v[138:141], v[194:197], v[86:89]
	v_mfma_f32_16x16x32_bf16 v[86:89], v[142:145], v[198:201], v[86:89]
	v_mfma_f32_16x16x32_bf16 v[82:85], v[146:149], v[194:197], v[82:85]
	v_mfma_f32_16x16x32_bf16 v[82:85], v[150:153], v[198:201], v[82:85]
	v_mfma_f32_16x16x32_bf16 v[110:113], v[154:157], v[170:173], v[110:113]
	v_mfma_f32_16x16x32_bf16 v[110:113], v[158:161], v[174:177], v[110:113]
	v_mfma_f32_16x16x32_bf16 v[106:109], v[162:165], v[170:173], v[106:109]
	v_mfma_f32_16x16x32_bf16 v[106:109], v[166:169], v[174:177], v[106:109]
	v_mfma_f32_16x16x32_bf16 v[94:97], v[154:157], v[178:181], v[94:97]
	v_mfma_f32_16x16x32_bf16 v[94:97], v[158:161], v[182:185], v[94:97]
	v_mfma_f32_16x16x32_bf16 v[90:93], v[162:165], v[178:181], v[90:93]
	v_mfma_f32_16x16x32_bf16 v[90:93], v[166:169], v[182:185], v[90:93]
	v_mfma_f32_16x16x32_bf16 v[78:81], v[154:157], v[186:189], v[78:81]
	v_mfma_f32_16x16x32_bf16 v[78:81], v[158:161], v[190:193], v[78:81]
	v_mfma_f32_16x16x32_bf16 v[74:77], v[162:165], v[186:189], v[74:77]
	v_mfma_f32_16x16x32_bf16 v[74:77], v[166:169], v[190:193], v[74:77]
	v_mfma_f32_16x16x32_bf16 v[70:73], v[154:157], v[194:197], v[70:73]
	v_mfma_f32_16x16x32_bf16 v[70:73], v[158:161], v[198:201], v[70:73]
	v_mfma_f32_16x16x32_bf16 v[66:69], v[162:165], v[194:197], v[66:69]
	v_mfma_f32_16x16x32_bf16 v[66:69], v[166:169], v[198:201], v[66:69]
	s_setprio 0
	s_barrier
	ds_read_b128 v[170:173], v136 offset:49152
	ds_read_b128 v[174:177], v136 offset:50176
	ds_read_b128 v[178:181], v136 offset:51200
	ds_read_b128 v[182:185], v136 offset:52224
	ds_read_b128 v[186:189], v136 offset:53248
	ds_read_b128 v[190:193], v136 offset:54272
	ds_read_b128 v[194:197], v136 offset:55296
	ds_read_b128 v[198:201], v136 offset:56320
	s_add_u32 s18, s22, 0x80
	s_addc_u32 s19, s23, 0
	s_mov_b32 m0, s43
	s_nop 0
	global_load_lds_dwordx4 v132, s[18:19]
	s_nop 0
	s_mov_b32 m0, s44
	s_nop 0
	global_load_lds_dwordx4 v134, s[18:19]
	s_add_u32 s18, s22, 0x40080
	s_addc_u32 s19, s23, 0
	s_mov_b32 m0, s47
	s_nop 0
	global_load_lds_dwordx4 v132, s[18:19]
	s_nop 0
	s_mov_b32 m0, s48
	s_nop 0
	global_load_lds_dwordx4 v134, s[18:19]
	s_mov_b32 m0, s45
	s_nop 0
	global_load_lds_dwordx4 v131, s[20:21]
	s_nop 0
	s_mov_b32 m0, s46
	s_nop 0
	global_load_lds_dwordx4 v133, s[20:21]
	s_waitcnt vmcnt(8)
	s_waitcnt lgkmcnt(0)
	s_barrier
	s_setprio 1
	v_mfma_f32_16x16x32_bf16 v[62:65], v[138:141], v[170:173], v[62:65]
	v_mfma_f32_16x16x32_bf16 v[62:65], v[142:145], v[174:177], v[62:65]
	v_mfma_f32_16x16x32_bf16 v[58:61], v[146:149], v[170:173], v[58:61]
	v_mfma_f32_16x16x32_bf16 v[58:61], v[150:153], v[174:177], v[58:61]
	v_mfma_f32_16x16x32_bf16 v[54:57], v[138:141], v[178:181], v[54:57]
	v_mfma_f32_16x16x32_bf16 v[54:57], v[142:145], v[182:185], v[54:57]
	v_mfma_f32_16x16x32_bf16 v[50:53], v[146:149], v[178:181], v[50:53]
	v_mfma_f32_16x16x32_bf16 v[50:53], v[150:153], v[182:185], v[50:53]
	v_mfma_f32_16x16x32_bf16 v[38:41], v[138:141], v[186:189], v[38:41]
	v_mfma_f32_16x16x32_bf16 v[38:41], v[142:145], v[190:193], v[38:41]
	v_mfma_f32_16x16x32_bf16 v[34:37], v[146:149], v[186:189], v[34:37]
	v_mfma_f32_16x16x32_bf16 v[34:37], v[150:153], v[190:193], v[34:37]
	v_mfma_f32_16x16x32_bf16 v[22:25], v[138:141], v[194:197], v[22:25]
	v_mfma_f32_16x16x32_bf16 v[22:25], v[142:145], v[198:201], v[22:25]
	v_mfma_f32_16x16x32_bf16 v[18:21], v[146:149], v[194:197], v[18:21]
	v_mfma_f32_16x16x32_bf16 v[18:21], v[150:153], v[198:201], v[18:21]
	v_mfma_f32_16x16x32_bf16 v[46:49], v[154:157], v[170:173], v[46:49]
	v_mfma_f32_16x16x32_bf16 v[46:49], v[158:161], v[174:177], v[46:49]
	v_mfma_f32_16x16x32_bf16 v[42:45], v[162:165], v[170:173], v[42:45]
	v_mfma_f32_16x16x32_bf16 v[42:45], v[166:169], v[174:177], v[42:45]
	v_mfma_f32_16x16x32_bf16 v[30:33], v[154:157], v[178:181], v[30:33]
	v_mfma_f32_16x16x32_bf16 v[30:33], v[158:161], v[182:185], v[30:33]
	v_mfma_f32_16x16x32_bf16 v[26:29], v[162:165], v[178:181], v[26:29]
	v_mfma_f32_16x16x32_bf16 v[26:29], v[166:169], v[182:185], v[26:29]
	v_mfma_f32_16x16x32_bf16 v[14:17], v[154:157], v[186:189], v[14:17]
	v_mfma_f32_16x16x32_bf16 v[14:17], v[158:161], v[190:193], v[14:17]
	v_mfma_f32_16x16x32_bf16 v[10:13], v[162:165], v[186:189], v[10:13]
	v_mfma_f32_16x16x32_bf16 v[10:13], v[166:169], v[190:193], v[10:13]
	v_mfma_f32_16x16x32_bf16 v[6:9], v[154:157], v[194:197], v[6:9]
	v_mfma_f32_16x16x32_bf16 v[6:9], v[158:161], v[198:201], v[6:9]
	v_mfma_f32_16x16x32_bf16 v[2:5], v[162:165], v[194:197], v[2:5]
	v_mfma_f32_16x16x32_bf16 v[2:5], v[166:169], v[198:201], v[2:5]
	s_setprio 0
	s_barrier
	s_add_i32 s61, s61, 2
	s_add_u32 s58, s58, 0x100
	s_addc_u32 s59, s59, 0
	s_cmp_gt_u32 s61, 13
	s_mov_b64 s[18:19], s[4:5]
	s_cbranch_scc0 .LBB0_813
	s_and_b64 vcc, exec, s[8:9]
	s_cbranch_vccz .LBB0_816
	s_barrier

; #define PG8_LDA(dst, b, h) do { _Pragma("unroll") for (int m = 0; m < 4; ++m) _Pragma("unroll") for (int k = 0; k < 2; ++k) dst[m][k] = *(const PG8_LAS bf16x8*)(lds + PG8_SA(b, h) + aoff + m * 2048 + k * 1024); } while (0)
; #define PG8_LDB(dst, b, h) do { _Pragma("unroll") for (int n = 0; n < 2; ++n) _Pragma("unroll") for (int k = 0; k < 2; ++k) dst[n][k] = *(const PG8_LAS bf16x8*)(lds + PG8_SB(b, h) + boff + n * 2048 + k * 1024); } while (0)
; #define PG8_MMA(ai, bj, At, Bt) do { __builtin_amdgcn_s_setprio(1); _Pragma("unroll") for (int m = 0; m < 4; ++m) _Pragma("unroll") for (int n = 0; n < 2; ++n) _Pragma("unroll") for (int k = 0; k < 2; ++k) \
;         acc[ai][bj][m][n] = __builtin_amdgcn_mfma_f32_16x16x32_bf16(Bt[n][k], At[m][k], acc[ai][bj][m][n], 0, 0, 0); __builtin_amdgcn_s_setprio(0); } while (0)
; #define PG8_WAIT_V(n) asm volatile("s_waitcnt vmcnt(" #n ")" ::: "memory")
; #define PG8_WAIT_L(n) asm volatile("s_waitcnt lgkmcnt(" #n ")" ::: "memory")
; #define PG8_BAR __builtin_amdgcn_s_barrier()
; #define PG8_SCHED __builtin_amdgcn_sched_barrier(0)
;     __device__ __forceinline__ void a_ready(const Unit& u) const {
;         if (u.fill && tid < 256) {
;             const f32x4* p = (const f32x4*)(ssq + (size_t)(u.pm * BM + tid) * 32); float s = 0.f;
; #pragma unroll
;             for (int j = 0; j < 8; ++j) { const f32x4 a = p[j]; s += (a[0] + a[1]) + (a[2] + a[3]); }
;             tab[u.slot * 256 + tid] = __builtin_amdgcn_rsqf(s * inv_ncol + eps);
;         }
; template <class Epi, class Sched, bool ALIGN_EPI = false, bool SP2 = false>
; __device__ __forceinline__ void gemm_phase(PG8_LAS unsigned char* lds, const Gemm g, const Sched& S, const Epi& E, const int tid) {
;     ...
;             PG8_LDB(B0, 0, 0); PG8_LDB(B1, 0, 1); PG8_SCHED; PG8_LDA(At, 0, 0); PG8_STAGE(PG8_SA(1, 1), a1 + hstepA, voffA);
;             PG8_WAIT_V(8); PG8_WAIT_L(0); PG8_BAR; PG8_MMA(0, 0, At, B0); PG8_MMA(0, 1, At, B1); PG8_BAR; PG8_SCHED;
;             PG8_LDA(At, 0, 1); PG8_STAGE(PG8_SB(0, 0), b2, voffB); PG8_STAGE(PG8_SB(0, 1), b2 + hstepB, voffB); PG8_STAGE(PG8_SA(0, 0), a2, voffA);
;             PG8_WAIT_V(8); PG8_WAIT_L(0); PG8_BAR; PG8_MMA(1, 0, At, B0); PG8_MMA(1, 1, At, B1); PG8_BAR; PG8_SCHED;
.LBB0_899:
	s_or_b64 exec, exec, s[42:43]
	v_add_u32_e32 v144, 0x10000, v200
	v_add_u32_e32 v160, 0x14000, v200
	s_add_u32 s42, s34, 0x100
	ds_read_b128 v[132:135], v144
	ds_read_b128 v[136:139], v144 offset:1024
	ds_read_b128 v[140:143], v144 offset:2048
	ds_read_b128 v[144:147], v144 offset:3072
	ds_read_b128 v[148:151], v160
	ds_read_b128 v[152:155], v160 offset:1024
	ds_read_b128 v[156:159], v160 offset:2048
	ds_read_b128 v[160:163], v160 offset:3072
	s_addc_u32 s43, s35, 0
	s_and_b64 s[40:41], s[40:41], exec
	s_cselect_b32 s48, vcc_lo, s42
	s_cselect_b32 s49, s21, s43
	s_cselect_b32 s41, s23, s67
	s_cselect_b32 s40, vcc_hi, s59
	s_add_u32 s44, s48, 0x80
	s_addc_u32 s45, s49, 0
	s_add_u32 s46, s40, 0x80
	s_addc_u32 s47, s41, 0
	ds_read_b128 v[164:167], v201
	ds_read_b128 v[168:171], v201 offset:1024
	ds_read_b128 v[172:175], v201 offset:2048
	ds_read_b128 v[176:179], v201 offset:3072
	ds_read_b128 v[180:183], v201 offset:4096
	ds_read_b128 v[184:187], v201 offset:5120
	ds_read_b128 v[202:205], v201 offset:6144
	ds_read_b128 v[206:209], v201 offset:7168
	s_add_u32 s34, s34, 0x80080
	s_addc_u32 s35, s35, 0
	s_mov_b32 m0, s96
	s_nop 0
	global_load_lds_dwordx4 v192, s[34:35]
	s_nop 0
	s_mov_b32 m0, s97
	s_nop 0
	global_load_lds_dwordx4 v194, s[34:35]
	s_waitcnt vmcnt(8)
	s_waitcnt lgkmcnt(0)
	s_barrier
	s_setprio 1
	v_mfma_f32_16x16x32_bf16 v[126:129], v[132:135], v[164:167], v[126:129]
	v_mfma_f32_16x16x32_bf16 v[126:129], v[136:139], v[168:171], v[126:129]
	v_mfma_f32_16x16x32_bf16 v[122:125], v[140:143], v[164:167], v[122:125]
	v_mfma_f32_16x16x32_bf16 v[122:125], v[144:147], v[168:171], v[122:125]
	v_mfma_f32_16x16x32_bf16 v[118:121], v[132:135], v[172:175], v[118:121]
	v_mfma_f32_16x16x32_bf16 v[118:121], v[136:139], v[176:179], v[118:121]
	v_mfma_f32_16x16x32_bf16 v[114:117], v[140:143], v[172:175], v[114:117]
	v_mfma_f32_16x16x32_bf16 v[114:117], v[144:147], v[176:179], v[114:117]
	v_mfma_f32_16x16x32_bf16 v[94:97], v[132:135], v[180:183], v[94:97]
	v_mfma_f32_16x16x32_bf16 v[94:97], v[136:139], v[184:187], v[94:97]
	v_mfma_f32_16x16x32_bf16 v[90:93], v[140:143], v[180:183], v[90:93]
	v_mfma_f32_16x16x32_bf16 v[90:93], v[144:147], v[184:187], v[90:93]
	v_mfma_f32_16x16x32_bf16 v[78:81], v[132:135], v[202:205], v[78:81]
	v_mfma_f32_16x16x32_bf16 v[78:81], v[136:139], v[206:209], v[78:81]
	v_mfma_f32_16x16x32_bf16 v[74:77], v[140:143], v[202:205], v[74:77]
	v_mfma_f32_16x16x32_bf16 v[74:77], v[144:147], v[206:209], v[74:77]
	v_mfma_f32_16x16x32_bf16 v[110:113], v[148:151], v[164:167], v[110:113]
	v_mfma_f32_16x16x32_bf16 v[110:113], v[152:155], v[168:171], v[110:113]
	v_mfma_f32_16x16x32_bf16 v[106:109], v[156:159], v[164:167], v[106:109]
	v_mfma_f32_16x16x32_bf16 v[106:109], v[160:163], v[168:171], v[106:109]
	v_mfma_f32_16x16x32_bf16 v[102:105], v[148:151], v[172:175], v[102:105]
	v_mfma_f32_16x16x32_bf16 v[102:105], v[152:155], v[176:179], v[102:105]
	v_mfma_f32_16x16x32_bf16 v[98:101], v[156:159], v[172:175], v[98:101]
	v_mfma_f32_16x16x32_bf16 v[98:101], v[160:163], v[176:179], v[98:101]
	v_mfma_f32_16x16x32_bf16 v[86:89], v[148:151], v[180:183], v[86:89]
	v_mfma_f32_16x16x32_bf16 v[86:89], v[152:155], v[184:187], v[86:89]
	v_mfma_f32_16x16x32_bf16 v[82:85], v[156:159], v[180:183], v[82:85]
	v_mfma_f32_16x16x32_bf16 v[82:85], v[160:163], v[184:187], v[82:85]
	v_mfma_f32_16x16x32_bf16 v[70:73], v[148:151], v[202:205], v[70:73]
	v_mfma_f32_16x16x32_bf16 v[70:73], v[152:155], v[206:209], v[70:73]
	v_mfma_f32_16x16x32_bf16 v[66:69], v[156:159], v[202:205], v[66:69]
	v_mfma_f32_16x16x32_bf16 v[66:69], v[160:163], v[206:209], v[66:69]
	s_setprio 0
	s_barrier
	ds_read_b128 v[164:167], v201 offset:16384
	ds_read_b128 v[168:171], v201 offset:17408
	ds_read_b128 v[172:175], v201 offset:18432
	ds_read_b128 v[176:179], v201 offset:19456
	ds_read_b128 v[180:183], v201 offset:20480
	ds_read_b128 v[184:187], v201 offset:21504
	ds_read_b128 v[202:205], v201 offset:22528
	ds_read_b128 v[206:209], v201 offset:23552
	s_mov_b32 m0, s29
	s_nop 0
	global_load_lds_dwordx4 v193, s[40:41]
	s_nop 0
	s_mov_b32 m0, s31
	s_nop 0
	global_load_lds_dwordx4 v195, s[40:41]
	s_add_u32 s34, s40, 0x80000
	s_addc_u32 s35, s41, 0
	s_mov_b32 m0, s54
	s_nop 0
	global_load_lds_dwordx4 v193, s[34:35]
	s_nop 0
	s_mov_b32 m0, s55
	s_nop 0
	global_load_lds_dwordx4 v195, s[34:35]
	s_mov_b32 m0, s10
	s_nop 0
	global_load_lds_dwordx4 v192, s[48:49]
	s_nop 0
	s_mov_b32 m0, s56
	s_nop 0
	global_load_lds_dwordx4 v194, s[48:49]
	s_waitcnt vmcnt(8)
	s_waitcnt lgkmcnt(0)
	s_barrier
	s_setprio 1
	v_mfma_f32_16x16x32_bf16 v[62:65], v[132:135], v[164:167], v[62:65]
	v_mfma_f32_16x16x32_bf16 v[62:65], v[136:139], v[168:171], v[62:65]
	v_mfma_f32_16x16x32_bf16 v[58:61], v[140:143], v[164:167], v[58:61]
	v_mfma_f32_16x16x32_bf16 v[58:61], v[144:147], v[168:171], v[58:61]
	v_mfma_f32_16x16x32_bf16 v[46:49], v[132:135], v[172:175], v[46:49]
	v_mfma_f32_16x16x32_bf16 v[46:49], v[136:139], v[176:179], v[46:49]
	v_mfma_f32_16x16x32_bf16 v[42:45], v[140:143], v[172:175], v[42:45]
	v_mfma_f32_16x16x32_bf16 v[42:45], v[144:147], v[176:179], v[42:45]
	v_mfma_f32_16x16x32_bf16 v[30:33], v[132:135], v[180:183], v[30:33]
	v_mfma_f32_16x16x32_bf16 v[30:33], v[136:139], v[184:187], v[30:33]
	v_mfma_f32_16x16x32_bf16 v[26:29], v[140:143], v[180:183], v[26:29]
	v_mfma_f32_16x16x32_bf16 v[26:29], v[144:147], v[184:187], v[26:29]
	v_mfma_f32_16x16x32_bf16 v[14:17], v[132:135], v[202:205], v[14:17]
	v_mfma_f32_16x16x32_bf16 v[14:17], v[136:139], v[206:209], v[14:17]
	v_mfma_f32_16x16x32_bf16 v[10:13], v[140:143], v[202:205], v[10:13]
	v_mfma_f32_16x16x32_bf16 v[10:13], v[144:147], v[206:209], v[10:13]
	v_mfma_f32_16x16x32_bf16 v[54:57], v[148:151], v[164:167], v[54:57]
	v_mfma_f32_16x16x32_bf16 v[54:57], v[152:155], v[168:171], v[54:57]
	v_mfma_f32_16x16x32_bf16 v[50:53], v[156:159], v[164:167], v[50:53]
	v_mfma_f32_16x16x32_bf16 v[50:53], v[160:163], v[168:171], v[50:53]
	v_mfma_f32_16x16x32_bf16 v[38:41], v[148:151], v[172:175], v[38:41]
	v_mfma_f32_16x16x32_bf16 v[38:41], v[152:155], v[176:179], v[38:41]
	v_mfma_f32_16x16x32_bf16 v[34:37], v[156:159], v[172:175], v[34:37]
	v_mfma_f32_16x16x32_bf16 v[34:37], v[160:163], v[176:179], v[34:37]
	v_mfma_f32_16x16x32_bf16 v[22:25], v[148:151], v[180:183], v[22:25]
	v_mfma_f32_16x16x32_bf16 v[22:25], v[152:155], v[184:187], v[22:25]
	v_mfma_f32_16x16x32_bf16 v[18:21], v[156:159], v[180:183], v[18:21]
	v_mfma_f32_16x16x32_bf16 v[18:21], v[160:163], v[184:187], v[18:21]
	v_mfma_f32_16x16x32_bf16 v[6:9], v[148:151], v[202:205], v[6:9]
	v_mfma_f32_16x16x32_bf16 v[6:9], v[152:155], v[206:209], v[6:9]
	v_mfma_f32_16x16x32_bf16 v[2:5], v[156:159], v[202:205], v[2:5]
	v_mfma_f32_16x16x32_bf16 v[2:5], v[160:163], v[206:209], v[2:5]
	s_setprio 0
	s_barrier
; #define PG8_LDA(dst, b, h) do { _Pragma("unroll") for (int m = 0; m < 4; ++m) _Pragma("unroll") for (int k = 0; k < 2; ++k) dst[m][k] = *(const PG8_LAS bf16x8*)(lds + PG8_SA(b, h) + aoff + m * 2048 + k * 1024); } while (0)
; #define PG8_LDB(dst, b, h) do { _Pragma("unroll") for (int n = 0; n < 2; ++n) _Pragma("unroll") for (int k = 0; k < 2; ++k) dst[n][k] = *(const PG8_LAS bf16x8*)(lds + PG8_SB(b, h) + boff + n * 2048 + k * 1024); } while (0)
; #define PG8_MMA(ai, bj, At, Bt) do { __builtin_amdgcn_s_setprio(1); _Pragma("unroll") for (int m = 0; m < 4; ++m) _Pragma("unroll") for (int n = 0; n < 2; ++n) _Pragma("unroll") for (int k = 0; k < 2; ++k) \
;         acc[ai][bj][m][n] = __builtin_amdgcn_mfma_f32_16x16x32_bf16(Bt[n][k], At[m][k], acc[ai][bj][m][n], 0, 0, 0); __builtin_amdgcn_s_setprio(0); } while (0)
; #define PG8_WAIT_V(n) asm volatile("s_waitcnt vmcnt(" #n ")" ::: "memory")
; #define PG8_WAIT_L(n) asm volatile("s_waitcnt lgkmcnt(" #n ")" ::: "memory")
; #define PG8_BAR __builtin_amdgcn_s_barrier()
; #define PG8_SCHED __builtin_amdgcn_sched_barrier(0)
; template <class Epi, class Sched, bool ALIGN_EPI = false, bool SP2 = false>
; __device__ __forceinline__ void gemm_phase(PG8_LAS unsigned char* lds, const Gemm g, const Sched& S, const Epi& E, const int tid) {
;     ...
;             PG8_LDB(B0, 1, 0); PG8_LDB(B1, 1, 1); PG8_SCHED; PG8_LDA(At, 1, 0); PG8_STAGE(PG8_SA(0, 1), a2 + hstepA, voffA);
;             PG8_WAIT_V(8); PG8_WAIT_L(0); PG8_BAR; PG8_MMA(0, 0, At, B0); PG8_MMA(0, 1, At, B1); PG8_BAR; PG8_SCHED;
;             PG8_LDA(At, 1, 1); PG8_STAGE(PG8_SB(1, 0), b3, voffB); PG8_STAGE(PG8_SB(1, 1), b3 + hstepB, voffB); PG8_STAGE(PG8_SA(1, 0), a3, voffA);
;             PG8_WAIT_V(8); PG8_WAIT_L(0); PG8_BAR; PG8_MMA(1, 0, At, B0); PG8_MMA(1, 1, At, B1); PG8_BAR; PG8_SCHED;
	v_add_u32_e32 v144, 0x18000, v200
	v_add_u32_e32 v160, 0x1c000, v200
	ds_read_b128 v[132:135], v144
	ds_read_b128 v[136:139], v144 offset:1024
	ds_read_b128 v[140:143], v144 offset:2048
	ds_read_b128 v[144:147], v144 offset:3072
	ds_read_b128 v[148:151], v160
	ds_read_b128 v[152:155], v160 offset:1024
	ds_read_b128 v[156:159], v160 offset:2048
	ds_read_b128 v[160:163], v160 offset:3072
	ds_read_b128 v[164:167], v201 offset:32768
	ds_read_b128 v[168:171], v201 offset:33792
	ds_read_b128 v[172:175], v201 offset:34816
	ds_read_b128 v[176:179], v201 offset:35840
	ds_read_b128 v[180:183], v201 offset:36864
	ds_read_b128 v[184:187], v201 offset:37888
	ds_read_b128 v[202:205], v201 offset:38912
	ds_read_b128 v[206:209], v201 offset:39936
	s_add_u32 s34, s48, 0x80000
	s_addc_u32 s35, s49, 0
	s_mov_b32 m0, s57
	s_nop 0
	global_load_lds_dwordx4 v192, s[34:35]
	s_nop 0
	s_mov_b32 m0, s64
	s_nop 0
	global_load_lds_dwordx4 v194, s[34:35]
	s_waitcnt vmcnt(8)
	s_waitcnt lgkmcnt(0)
	s_barrier
	s_setprio 1
	v_mfma_f32_16x16x32_bf16 v[126:129], v[132:135], v[164:167], v[126:129]
	v_mfma_f32_16x16x32_bf16 v[126:129], v[136:139], v[168:171], v[126:129]
	v_mfma_f32_16x16x32_bf16 v[122:125], v[140:143], v[164:167], v[122:125]
	v_mfma_f32_16x16x32_bf16 v[122:125], v[144:147], v[168:171], v[122:125]
	v_mfma_f32_16x16x32_bf16 v[118:121], v[132:135], v[172:175], v[118:121]
	v_mfma_f32_16x16x32_bf16 v[118:121], v[136:139], v[176:179], v[118:121]
	v_mfma_f32_16x16x32_bf16 v[114:117], v[140:143], v[172:175], v[114:117]
	v_mfma_f32_16x16x32_bf16 v[114:117], v[144:147], v[176:179], v[114:117]
	v_mfma_f32_16x16x32_bf16 v[94:97], v[132:135], v[180:183], v[94:97]
	v_mfma_f32_16x16x32_bf16 v[94:97], v[136:139], v[184:187], v[94:97]
	v_mfma_f32_16x16x32_bf16 v[90:93], v[140:143], v[180:183], v[90:93]
	v_mfma_f32_16x16x32_bf16 v[90:93], v[144:147], v[184:187], v[90:93]
	v_mfma_f32_16x16x32_bf16 v[78:81], v[132:135], v[202:205], v[78:81]
	v_mfma_f32_16x16x32_bf16 v[78:81], v[136:139], v[206:209], v[78:81]
	v_mfma_f32_16x16x32_bf16 v[74:77], v[140:143], v[202:205], v[74:77]
	v_mfma_f32_16x16x32_bf16 v[74:77], v[144:147], v[206:209], v[74:77]
	v_mfma_f32_16x16x32_bf16 v[110:113], v[148:151], v[164:167], v[110:113]
	v_mfma_f32_16x16x32_bf16 v[110:113], v[152:155], v[168:171], v[110:113]
	v_mfma_f32_16x16x32_bf16 v[106:109], v[156:159], v[164:167], v[106:109]
	v_mfma_f32_16x16x32_bf16 v[106:109], v[160:163], v[168:171], v[106:109]
	v_mfma_f32_16x16x32_bf16 v[102:105], v[148:151], v[172:175], v[102:105]
	v_mfma_f32_16x16x32_bf16 v[102:105], v[152:155], v[176:179], v[102:105]
	v_mfma_f32_16x16x32_bf16 v[98:101], v[156:159], v[172:175], v[98:101]
	v_mfma_f32_16x16x32_bf16 v[98:101], v[160:163], v[176:179], v[98:101]
	v_mfma_f32_16x16x32_bf16 v[86:89], v[148:151], v[180:183], v[86:89]
	v_mfma_f32_16x16x32_bf16 v[86:89], v[152:155], v[184:187], v[86:89]
	v_mfma_f32_16x16x32_bf16 v[82:85], v[156:159], v[180:183], v[82:85]
	v_mfma_f32_16x16x32_bf16 v[82:85], v[160:163], v[184:187], v[82:85]
	v_mfma_f32_16x16x32_bf16 v[70:73], v[148:151], v[202:205], v[70:73]
	v_mfma_f32_16x16x32_bf16 v[70:73], v[152:155], v[206:209], v[70:73]
	v_mfma_f32_16x16x32_bf16 v[66:69], v[156:159], v[202:205], v[66:69]
	v_mfma_f32_16x16x32_bf16 v[66:69], v[160:163], v[206:209], v[66:69]
	s_setprio 0
	s_barrier
	ds_read_b128 v[164:167], v201 offset:49152
	ds_read_b128 v[168:171], v201 offset:50176
	ds_read_b128 v[172:175], v201 offset:51200
	ds_read_b128 v[176:179], v201 offset:52224
	ds_read_b128 v[180:183], v201 offset:53248
	ds_read_b128 v[184:187], v201 offset:54272
	ds_read_b128 v[202:205], v201 offset:55296
	ds_read_b128 v[206:209], v201 offset:56320
	s_mov_b32 m0, s87
	s_nop 0
	global_load_lds_dwordx4 v193, s[46:47]
	s_nop 0
	s_mov_b32 m0, s89
	s_nop 0
	global_load_lds_dwordx4 v195, s[46:47]
	s_add_u32 s34, s40, 0x80080
	s_addc_u32 s35, s41, 0
	s_mov_b32 m0, s83
	s_nop 0
	global_load_lds_dwordx4 v193, s[34:35]
	s_nop 0
	s_mov_b32 m0, s95
	s_nop 0
	global_load_lds_dwordx4 v195, s[34:35]
	s_mov_b32 m0, s90
	s_nop 0
	global_load_lds_dwordx4 v192, s[44:45]
	s_nop 0
	s_mov_b32 m0, s91
	s_nop 0
	global_load_lds_dwordx4 v194, s[44:45]
	s_waitcnt vmcnt(8)
	s_waitcnt lgkmcnt(0)
	s_barrier
	s_setprio 1
	v_mfma_f32_16x16x32_bf16 v[62:65], v[132:135], v[164:167], v[62:65]
	v_mfma_f32_16x16x32_bf16 v[62:65], v[136:139], v[168:171], v[62:65]
	v_mfma_f32_16x16x32_bf16 v[58:61], v[140:143], v[164:167], v[58:61]
	v_mfma_f32_16x16x32_bf16 v[58:61], v[144:147], v[168:171], v[58:61]
	v_mfma_f32_16x16x32_bf16 v[46:49], v[132:135], v[172:175], v[46:49]
	v_mfma_f32_16x16x32_bf16 v[46:49], v[136:139], v[176:179], v[46:49]
	v_mfma_f32_16x16x32_bf16 v[42:45], v[140:143], v[172:175], v[42:45]
	v_mfma_f32_16x16x32_bf16 v[42:45], v[144:147], v[176:179], v[42:45]
	v_mfma_f32_16x16x32_bf16 v[30:33], v[132:135], v[180:183], v[30:33]
	v_mfma_f32_16x16x32_bf16 v[30:33], v[136:139], v[184:187], v[30:33]
	v_mfma_f32_16x16x32_bf16 v[26:29], v[140:143], v[180:183], v[26:29]
	v_mfma_f32_16x16x32_bf16 v[26:29], v[144:147], v[184:187], v[26:29]
	v_mfma_f32_16x16x32_bf16 v[14:17], v[132:135], v[202:205], v[14:17]
	v_mfma_f32_16x16x32_bf16 v[14:17], v[136:139], v[206:209], v[14:17]
	v_mfma_f32_16x16x32_bf16 v[10:13], v[140:143], v[202:205], v[10:13]
	v_mfma_f32_16x16x32_bf16 v[10:13], v[144:147], v[206:209], v[10:13]
	v_mfma_f32_16x16x32_bf16 v[54:57], v[148:151], v[164:167], v[54:57]
	v_mfma_f32_16x16x32_bf16 v[54:57], v[152:155], v[168:171], v[54:57]
	v_mfma_f32_16x16x32_bf16 v[50:53], v[156:159], v[164:167], v[50:53]
	v_mfma_f32_16x16x32_bf16 v[50:53], v[160:163], v[168:171], v[50:53]
	v_mfma_f32_16x16x32_bf16 v[38:41], v[148:151], v[172:175], v[38:41]
	v_mfma_f32_16x16x32_bf16 v[38:41], v[152:155], v[176:179], v[38:41]
	v_mfma_f32_16x16x32_bf16 v[34:37], v[156:159], v[172:175], v[34:37]
	v_mfma_f32_16x16x32_bf16 v[34:37], v[160:163], v[176:179], v[34:37]
	v_mfma_f32_16x16x32_bf16 v[22:25], v[148:151], v[180:183], v[22:25]
	v_mfma_f32_16x16x32_bf16 v[22:25], v[152:155], v[184:187], v[22:25]
	v_mfma_f32_16x16x32_bf16 v[18:21], v[156:159], v[180:183], v[18:21]
	v_mfma_f32_16x16x32_bf16 v[18:21], v[160:163], v[184:187], v[18:21]
	v_mfma_f32_16x16x32_bf16 v[6:9], v[148:151], v[202:205], v[6:9]
	v_mfma_f32_16x16x32_bf16 v[6:9], v[152:155], v[206:209], v[6:9]
	v_mfma_f32_16x16x32_bf16 v[2:5], v[156:159], v[202:205], v[2:5]
	v_mfma_f32_16x16x32_bf16 v[2:5], v[160:163], v[206:209], v[2:5]
	s_setprio 0
	s_barrier
	s_add_i32 s11, s11, 2
	s_add_u32 s59, s59, 0x100
	s_addc_u32 s67, s67, 0
	s_cmp_gt_u32 s11, 29
	s_mov_b64 s[34:35], s[42:43]
	s_cbranch_scc1 .LBB0_902

; #define PG8_LDA(dst, b, h) do { _Pragma("unroll") for (int m = 0; m < 4; ++m) _Pragma("unroll") for (int k = 0; k < 2; ++k) dst[m][k] = *(const PG8_LAS bf16x8*)(lds + PG8_SA(b, h) + aoff + m * 2048 + k * 1024); } while (0)
; #define PG8_LDB(dst, b, h) do { _Pragma("unroll") for (int n = 0; n < 2; ++n) _Pragma("unroll") for (int k = 0; k < 2; ++k) dst[n][k] = *(const PG8_LAS bf16x8*)(lds + PG8_SB(b, h) + boff + n * 2048 + k * 1024); } while (0)
; #define PG8_MMA(ai, bj, At, Bt) do { __builtin_amdgcn_s_setprio(1); _Pragma("unroll") for (int m = 0; m < 4; ++m) _Pragma("unroll") for (int n = 0; n < 2; ++n) _Pragma("unroll") for (int k = 0; k < 2; ++k) \
;         acc[ai][bj][m][n] = __builtin_amdgcn_mfma_f32_16x16x32_bf16(Bt[n][k], At[m][k], acc[ai][bj][m][n], 0, 0, 0); __builtin_amdgcn_s_setprio(0); } while (0)
; #define PG8_WAIT_V(n) asm volatile("s_waitcnt vmcnt(" #n ")" ::: "memory")
; #define PG8_WAIT_L(n) asm volatile("s_waitcnt lgkmcnt(" #n ")" ::: "memory")
; #define PG8_BAR __builtin_amdgcn_s_barrier()
; #define PG8_SCHED __builtin_amdgcn_sched_barrier(0)
; template <class Epi, class Sched, bool ALIGN_EPI = false, bool SP2 = false>
; __device__ __forceinline__ void gemm_phase(PG8_LAS unsigned char* lds, const Gemm g, const Sched& S, const Epi& E, const int tid) {
;     ...
;             PG8_LDB(B0, 0, 0); PG8_LDB(B1, 0, 1); PG8_SCHED; PG8_LDA(At, 0, 0); PG8_STAGE(PG8_SA(1, 1), a1 + hstepA, voffA);
;             PG8_WAIT_V(8); PG8_WAIT_L(0); PG8_BAR; PG8_MMA(0, 0, At, B0); PG8_MMA(0, 1, At, B1); PG8_BAR; PG8_SCHED;
;             PG8_LDA(At, 0, 1); PG8_STAGE(PG8_SB(0, 0), b2, voffB); PG8_STAGE(PG8_SB(0, 1), b2 + hstepB, voffB); PG8_STAGE(PG8_SA(0, 0), a2, voffA);
;             PG8_WAIT_V(8); PG8_WAIT_L(0); PG8_BAR; PG8_MMA(1, 0, At, B0); PG8_MMA(1, 1, At, B1); PG8_BAR; PG8_SCHED;
.LBB0_986:
	v_add_u32_e32 v142, 0x10000, v181
	v_add_u32_e32 v158, 0x14000, v181
	ds_read_b128 v[130:133], v142
	ds_read_b128 v[134:137], v142 offset:1024
	ds_read_b128 v[138:141], v142 offset:2048
	ds_read_b128 v[142:145], v142 offset:3072
	ds_read_b128 v[146:149], v158
	ds_read_b128 v[150:153], v158 offset:1024
	ds_read_b128 v[154:157], v158 offset:2048
	ds_read_b128 v[158:161], v158 offset:3072
	s_cmp_eq_u32 s83, 28
	s_cselect_b32 s38, s21, s67
	s_cselect_b32 s39, s11, s78
	s_cselect_b32 s34, s27, s58
	s_cselect_b32 s35, s19, s59
	s_add_u32 s30, s38, 0x80
	s_addc_u32 s31, s39, 0
	ds_read_b128 v[162:165], v182
	ds_read_b128 v[166:169], v182 offset:1024
	ds_read_b128 v[170:173], v182 offset:2048
	ds_read_b128 v[184:187], v182 offset:3072
	ds_read_b128 v[188:191], v182 offset:4096
	ds_read_b128 v[192:195], v182 offset:5120
	ds_read_b128 v[196:199], v182 offset:6144
	ds_read_b128 v[200:203], v182 offset:7168
	s_mov_b32 m0, s61
	s_nop 0
	global_load_lds_dwordx4 v0, s[28:29]
	s_nop 0
	s_mov_b32 m0, s65
	s_nop 0
	global_load_lds_dwordx4 v177, s[28:29]
	s_waitcnt vmcnt(8)
	s_waitcnt lgkmcnt(0)
	s_barrier
	s_setprio 1
	v_mfma_f32_16x16x32_bf16 v[126:129], v[130:133], v[162:165], v[126:129]
	v_mfma_f32_16x16x32_bf16 v[126:129], v[134:137], v[166:169], v[126:129]
	v_mfma_f32_16x16x32_bf16 v[122:125], v[138:141], v[162:165], v[122:125]
	v_mfma_f32_16x16x32_bf16 v[122:125], v[142:145], v[166:169], v[122:125]
	v_mfma_f32_16x16x32_bf16 v[110:113], v[130:133], v[170:173], v[110:113]
	v_mfma_f32_16x16x32_bf16 v[110:113], v[134:137], v[184:187], v[110:113]
	v_mfma_f32_16x16x32_bf16 v[106:109], v[138:141], v[170:173], v[106:109]
	v_mfma_f32_16x16x32_bf16 v[106:109], v[142:145], v[184:187], v[106:109]
	v_mfma_f32_16x16x32_bf16 v[94:97], v[130:133], v[188:191], v[94:97]
	v_mfma_f32_16x16x32_bf16 v[94:97], v[134:137], v[192:195], v[94:97]
	v_mfma_f32_16x16x32_bf16 v[90:93], v[138:141], v[188:191], v[90:93]
	v_mfma_f32_16x16x32_bf16 v[90:93], v[142:145], v[192:195], v[90:93]
	v_mfma_f32_16x16x32_bf16 v[78:81], v[130:133], v[196:199], v[78:81]
	v_mfma_f32_16x16x32_bf16 v[78:81], v[134:137], v[200:203], v[78:81]
	v_mfma_f32_16x16x32_bf16 v[74:77], v[138:141], v[196:199], v[74:77]
	v_mfma_f32_16x16x32_bf16 v[74:77], v[142:145], v[200:203], v[74:77]
	v_mfma_f32_16x16x32_bf16 v[118:121], v[146:149], v[162:165], v[118:121]
	v_mfma_f32_16x16x32_bf16 v[118:121], v[150:153], v[166:169], v[118:121]
	v_mfma_f32_16x16x32_bf16 v[114:117], v[154:157], v[162:165], v[114:117]
	v_mfma_f32_16x16x32_bf16 v[114:117], v[158:161], v[166:169], v[114:117]
	v_mfma_f32_16x16x32_bf16 v[102:105], v[146:149], v[170:173], v[102:105]
	v_mfma_f32_16x16x32_bf16 v[102:105], v[150:153], v[184:187], v[102:105]
	v_mfma_f32_16x16x32_bf16 v[98:101], v[154:157], v[170:173], v[98:101]
	v_mfma_f32_16x16x32_bf16 v[98:101], v[158:161], v[184:187], v[98:101]
	v_mfma_f32_16x16x32_bf16 v[86:89], v[146:149], v[188:191], v[86:89]
	v_mfma_f32_16x16x32_bf16 v[86:89], v[150:153], v[192:195], v[86:89]
	v_mfma_f32_16x16x32_bf16 v[82:85], v[154:157], v[188:191], v[82:85]
	v_mfma_f32_16x16x32_bf16 v[82:85], v[158:161], v[192:195], v[82:85]
	v_mfma_f32_16x16x32_bf16 v[70:73], v[146:149], v[196:199], v[70:73]
	v_mfma_f32_16x16x32_bf16 v[70:73], v[150:153], v[200:203], v[70:73]
	v_mfma_f32_16x16x32_bf16 v[66:69], v[154:157], v[196:199], v[66:69]
	v_mfma_f32_16x16x32_bf16 v[66:69], v[158:161], v[200:203], v[66:69]
	s_setprio 0
	s_barrier
	ds_read_b128 v[162:165], v182 offset:16384
	ds_read_b128 v[166:169], v182 offset:17408
	ds_read_b128 v[170:173], v182 offset:18432
	ds_read_b128 v[184:187], v182 offset:19456
	ds_read_b128 v[188:191], v182 offset:20480
	ds_read_b128 v[192:195], v182 offset:21504
	ds_read_b128 v[196:199], v182 offset:22528
	ds_read_b128 v[200:203], v182 offset:23552
	s_mov_b32 m0, s7
	s_nop 0
	global_load_lds_dwordx4 v176, s[34:35]
	s_add_u32 s90, s34, 0x80000
	s_mov_b32 m0, s43
	s_nop 0
	global_load_lds_dwordx4 v178, s[34:35]
	s_addc_u32 s91, s35, 0
	s_mov_b32 m0, s44
	s_nop 0
	global_load_lds_dwordx4 v176, s[90:91]
	s_nop 0
	s_mov_b32 m0, s45
	s_nop 0
	global_load_lds_dwordx4 v178, s[90:91]
	s_nop 0
	s_mov_b32 m0, s10
	s_nop 0
	global_load_lds_dwordx4 v0, s[38:39]
	s_nop 0
	s_mov_b32 m0, s46
	s_nop 0
	global_load_lds_dwordx4 v177, s[38:39]
	s_waitcnt vmcnt(8)
	s_waitcnt lgkmcnt(0)
	s_barrier
	s_setprio 1
	v_mfma_f32_16x16x32_bf16 v[62:65], v[130:133], v[162:165], v[62:65]
	v_mfma_f32_16x16x32_bf16 v[62:65], v[134:137], v[166:169], v[62:65]
	v_mfma_f32_16x16x32_bf16 v[58:61], v[138:141], v[162:165], v[58:61]
	v_mfma_f32_16x16x32_bf16 v[58:61], v[142:145], v[166:169], v[58:61]
	v_mfma_f32_16x16x32_bf16 v[46:49], v[130:133], v[170:173], v[46:49]
	v_mfma_f32_16x16x32_bf16 v[46:49], v[134:137], v[184:187], v[46:49]
	v_mfma_f32_16x16x32_bf16 v[42:45], v[138:141], v[170:173], v[42:45]
	v_mfma_f32_16x16x32_bf16 v[42:45], v[142:145], v[184:187], v[42:45]
	v_mfma_f32_16x16x32_bf16 v[30:33], v[130:133], v[188:191], v[30:33]
	v_mfma_f32_16x16x32_bf16 v[30:33], v[134:137], v[192:195], v[30:33]
	v_mfma_f32_16x16x32_bf16 v[26:29], v[138:141], v[188:191], v[26:29]
	v_mfma_f32_16x16x32_bf16 v[26:29], v[142:145], v[192:195], v[26:29]
	v_mfma_f32_16x16x32_bf16 v[14:17], v[130:133], v[196:199], v[14:17]
	v_mfma_f32_16x16x32_bf16 v[14:17], v[134:137], v[200:203], v[14:17]
	v_mfma_f32_16x16x32_bf16 v[10:13], v[138:141], v[196:199], v[10:13]
	v_mfma_f32_16x16x32_bf16 v[10:13], v[142:145], v[200:203], v[10:13]
	v_mfma_f32_16x16x32_bf16 v[54:57], v[146:149], v[162:165], v[54:57]
	v_mfma_f32_16x16x32_bf16 v[54:57], v[150:153], v[166:169], v[54:57]
	v_mfma_f32_16x16x32_bf16 v[50:53], v[154:157], v[162:165], v[50:53]
	v_mfma_f32_16x16x32_bf16 v[50:53], v[158:161], v[166:169], v[50:53]
	v_mfma_f32_16x16x32_bf16 v[38:41], v[146:149], v[170:173], v[38:41]
	v_mfma_f32_16x16x32_bf16 v[38:41], v[150:153], v[184:187], v[38:41]
	v_mfma_f32_16x16x32_bf16 v[34:37], v[154:157], v[170:173], v[34:37]
	v_mfma_f32_16x16x32_bf16 v[34:37], v[158:161], v[184:187], v[34:37]
	v_mfma_f32_16x16x32_bf16 v[22:25], v[146:149], v[188:191], v[22:25]
	v_mfma_f32_16x16x32_bf16 v[22:25], v[150:153], v[192:195], v[22:25]
	v_mfma_f32_16x16x32_bf16 v[18:21], v[154:157], v[188:191], v[18:21]
	v_mfma_f32_16x16x32_bf16 v[18:21], v[158:161], v[192:195], v[18:21]
	v_mfma_f32_16x16x32_bf16 v[6:9], v[146:149], v[196:199], v[6:9]
	v_mfma_f32_16x16x32_bf16 v[6:9], v[150:153], v[200:203], v[6:9]
	v_mfma_f32_16x16x32_bf16 v[2:5], v[154:157], v[196:199], v[2:5]
	v_mfma_f32_16x16x32_bf16 v[2:5], v[158:161], v[200:203], v[2:5]
	s_setprio 0
	s_barrier
; #define PG8_LDA(dst, b, h) do { _Pragma("unroll") for (int m = 0; m < 4; ++m) _Pragma("unroll") for (int k = 0; k < 2; ++k) dst[m][k] = *(const PG8_LAS bf16x8*)(lds + PG8_SA(b, h) + aoff + m * 2048 + k * 1024); } while (0)
; #define PG8_LDB(dst, b, h) do { _Pragma("unroll") for (int n = 0; n < 2; ++n) _Pragma("unroll") for (int k = 0; k < 2; ++k) dst[n][k] = *(const PG8_LAS bf16x8*)(lds + PG8_SB(b, h) + boff + n * 2048 + k * 1024); } while (0)
; #define PG8_MMA(ai, bj, At, Bt) do { __builtin_amdgcn_s_setprio(1); _Pragma("unroll") for (int m = 0; m < 4; ++m) _Pragma("unroll") for (int n = 0; n < 2; ++n) _Pragma("unroll") for (int k = 0; k < 2; ++k) \
;         acc[ai][bj][m][n] = __builtin_amdgcn_mfma_f32_16x16x32_bf16(Bt[n][k], At[m][k], acc[ai][bj][m][n], 0, 0, 0); __builtin_amdgcn_s_setprio(0); } while (0)
; #define PG8_WAIT_V(n) asm volatile("s_waitcnt vmcnt(" #n ")" ::: "memory")
; #define PG8_WAIT_L(n) asm volatile("s_waitcnt lgkmcnt(" #n ")" ::: "memory")
; #define PG8_BAR __builtin_amdgcn_s_barrier()
; #define PG8_SCHED __builtin_amdgcn_sched_barrier(0)
; template <class Epi, class Sched, bool ALIGN_EPI = false, bool SP2 = false>
; __device__ __forceinline__ void gemm_phase(PG8_LAS unsigned char* lds, const Gemm g, const Sched& S, const Epi& E, const int tid) {
;     ...
;             PG8_LDB(B0, 1, 0); PG8_LDB(B1, 1, 1); PG8_SCHED; PG8_LDA(At, 1, 0); PG8_STAGE(PG8_SA(0, 1), a2 + hstepA, voffA);
;             PG8_WAIT_V(8); PG8_WAIT_L(0); PG8_BAR; PG8_MMA(0, 0, At, B0); PG8_MMA(0, 1, At, B1); PG8_BAR; PG8_SCHED;
;             PG8_LDA(At, 1, 1); PG8_STAGE(PG8_SB(1, 0), b3, voffB); PG8_STAGE(PG8_SB(1, 1), b3 + hstepB, voffB); PG8_STAGE(PG8_SA(1, 0), a3, voffA);
;             PG8_WAIT_V(8); PG8_WAIT_L(0); PG8_BAR; PG8_MMA(1, 0, At, B0); PG8_MMA(1, 1, At, B1); PG8_BAR; PG8_SCHED;
	v_add_u32_e32 v142, 0x18000, v181
	v_add_u32_e32 v158, 0x1c000, v181
	ds_read_b128 v[130:133], v142
	ds_read_b128 v[134:137], v142 offset:1024
	ds_read_b128 v[138:141], v142 offset:2048
	ds_read_b128 v[142:145], v142 offset:3072
	ds_read_b128 v[146:149], v158
	ds_read_b128 v[150:153], v158 offset:1024
	ds_read_b128 v[154:157], v158 offset:2048
	ds_read_b128 v[158:161], v158 offset:3072
	ds_read_b128 v[162:165], v182 offset:32768
	ds_read_b128 v[166:169], v182 offset:33792
	ds_read_b128 v[170:173], v182 offset:34816
	ds_read_b128 v[184:187], v182 offset:35840
	ds_read_b128 v[188:191], v182 offset:36864
	ds_read_b128 v[192:195], v182 offset:37888
	ds_read_b128 v[196:199], v182 offset:38912
	ds_read_b128 v[200:203], v182 offset:39936
	s_add_u32 s38, s38, 0x80000
	s_addc_u32 s39, s39, 0
	s_mov_b32 m0, s47
	s_nop 0
	global_load_lds_dwordx4 v0, s[38:39]
	s_nop 0
	s_mov_b32 m0, s48
	s_nop 0
	global_load_lds_dwordx4 v177, s[38:39]
	s_waitcnt vmcnt(8)
	s_waitcnt lgkmcnt(0)
	s_barrier
	s_setprio 1
	v_mfma_f32_16x16x32_bf16 v[126:129], v[130:133], v[162:165], v[126:129]
	v_mfma_f32_16x16x32_bf16 v[126:129], v[134:137], v[166:169], v[126:129]
	v_mfma_f32_16x16x32_bf16 v[122:125], v[138:141], v[162:165], v[122:125]
	v_mfma_f32_16x16x32_bf16 v[122:125], v[142:145], v[166:169], v[122:125]
	v_mfma_f32_16x16x32_bf16 v[110:113], v[130:133], v[170:173], v[110:113]
	v_mfma_f32_16x16x32_bf16 v[110:113], v[134:137], v[184:187], v[110:113]
	v_mfma_f32_16x16x32_bf16 v[106:109], v[138:141], v[170:173], v[106:109]
	v_mfma_f32_16x16x32_bf16 v[106:109], v[142:145], v[184:187], v[106:109]
	v_mfma_f32_16x16x32_bf16 v[94:97], v[130:133], v[188:191], v[94:97]
	v_mfma_f32_16x16x32_bf16 v[94:97], v[134:137], v[192:195], v[94:97]
	v_mfma_f32_16x16x32_bf16 v[90:93], v[138:141], v[188:191], v[90:93]
	v_mfma_f32_16x16x32_bf16 v[90:93], v[142:145], v[192:195], v[90:93]
	v_mfma_f32_16x16x32_bf16 v[78:81], v[130:133], v[196:199], v[78:81]
	v_mfma_f32_16x16x32_bf16 v[78:81], v[134:137], v[200:203], v[78:81]
	v_mfma_f32_16x16x32_bf16 v[74:77], v[138:141], v[196:199], v[74:77]
	v_mfma_f32_16x16x32_bf16 v[74:77], v[142:145], v[200:203], v[74:77]
	v_mfma_f32_16x16x32_bf16 v[118:121], v[146:149], v[162:165], v[118:121]
	v_mfma_f32_16x16x32_bf16 v[118:121], v[150:153], v[166:169], v[118:121]
	v_mfma_f32_16x16x32_bf16 v[114:117], v[154:157], v[162:165], v[114:117]
	v_mfma_f32_16x16x32_bf16 v[114:117], v[158:161], v[166:169], v[114:117]
	v_mfma_f32_16x16x32_bf16 v[102:105], v[146:149], v[170:173], v[102:105]
	v_mfma_f32_16x16x32_bf16 v[102:105], v[150:153], v[184:187], v[102:105]
	v_mfma_f32_16x16x32_bf16 v[98:101], v[154:157], v[170:173], v[98:101]
	v_mfma_f32_16x16x32_bf16 v[98:101], v[158:161], v[184:187], v[98:101]
	v_mfma_f32_16x16x32_bf16 v[86:89], v[146:149], v[188:191], v[86:89]
	v_mfma_f32_16x16x32_bf16 v[86:89], v[150:153], v[192:195], v[86:89]
	v_mfma_f32_16x16x32_bf16 v[82:85], v[154:157], v[188:191], v[82:85]
	v_mfma_f32_16x16x32_bf16 v[82:85], v[158:161], v[192:195], v[82:85]
	v_mfma_f32_16x16x32_bf16 v[70:73], v[146:149], v[196:199], v[70:73]
	v_mfma_f32_16x16x32_bf16 v[70:73], v[150:153], v[200:203], v[70:73]
	v_mfma_f32_16x16x32_bf16 v[66:69], v[154:157], v[196:199], v[66:69]
	v_mfma_f32_16x16x32_bf16 v[66:69], v[158:161], v[200:203], v[66:69]
	s_setprio 0
	s_barrier
	ds_read_b128 v[162:165], v182 offset:49152
	ds_read_b128 v[166:169], v182 offset:50176
	ds_read_b128 v[170:173], v182 offset:51200
	ds_read_b128 v[184:187], v182 offset:52224
	ds_read_b128 v[188:191], v182 offset:53248
	ds_read_b128 v[192:195], v182 offset:54272
	ds_read_b128 v[196:199], v182 offset:55296
	ds_read_b128 v[200:203], v182 offset:56320
	s_add_u32 s38, s34, 0x80
	s_addc_u32 s39, s35, 0
	s_mov_b32 m0, s50
	s_nop 0
	global_load_lds_dwordx4 v176, s[38:39]
	s_add_u32 s34, s34, 0x80080
	s_mov_b32 m0, s51
	s_nop 0
	global_load_lds_dwordx4 v178, s[38:39]
	s_addc_u32 s35, s35, 0
	s_mov_b32 m0, s56
	s_nop 0
	global_load_lds_dwordx4 v176, s[34:35]
	s_nop 0
	s_mov_b32 m0, s57
	s_nop 0
	global_load_lds_dwordx4 v178, s[34:35]
	s_mov_b32 m0, s54
	s_nop 0
	global_load_lds_dwordx4 v0, s[30:31]
	s_nop 0
	s_mov_b32 m0, s55
	s_nop 0
	global_load_lds_dwordx4 v177, s[30:31]
	s_waitcnt vmcnt(8)
	s_waitcnt lgkmcnt(0)
	s_barrier
	s_setprio 1
	v_mfma_f32_16x16x32_bf16 v[62:65], v[130:133], v[162:165], v[62:65]
	v_mfma_f32_16x16x32_bf16 v[62:65], v[134:137], v[166:169], v[62:65]
	v_mfma_f32_16x16x32_bf16 v[58:61], v[138:141], v[162:165], v[58:61]
	v_mfma_f32_16x16x32_bf16 v[58:61], v[142:145], v[166:169], v[58:61]
	v_mfma_f32_16x16x32_bf16 v[46:49], v[130:133], v[170:173], v[46:49]
	v_mfma_f32_16x16x32_bf16 v[46:49], v[134:137], v[184:187], v[46:49]
	v_mfma_f32_16x16x32_bf16 v[42:45], v[138:141], v[170:173], v[42:45]
	v_mfma_f32_16x16x32_bf16 v[42:45], v[142:145], v[184:187], v[42:45]
	v_mfma_f32_16x16x32_bf16 v[30:33], v[130:133], v[188:191], v[30:33]
	v_mfma_f32_16x16x32_bf16 v[30:33], v[134:137], v[192:195], v[30:33]
	v_mfma_f32_16x16x32_bf16 v[26:29], v[138:141], v[188:191], v[26:29]
	v_mfma_f32_16x16x32_bf16 v[26:29], v[142:145], v[192:195], v[26:29]
	v_mfma_f32_16x16x32_bf16 v[14:17], v[130:133], v[196:199], v[14:17]
	v_mfma_f32_16x16x32_bf16 v[14:17], v[134:137], v[200:203], v[14:17]
	v_mfma_f32_16x16x32_bf16 v[10:13], v[138:141], v[196:199], v[10:13]
	v_mfma_f32_16x16x32_bf16 v[10:13], v[142:145], v[200:203], v[10:13]
	v_mfma_f32_16x16x32_bf16 v[54:57], v[146:149], v[162:165], v[54:57]
	v_mfma_f32_16x16x32_bf16 v[54:57], v[150:153], v[166:169], v[54:57]
	v_mfma_f32_16x16x32_bf16 v[50:53], v[154:157], v[162:165], v[50:53]
	v_mfma_f32_16x16x32_bf16 v[50:53], v[158:161], v[166:169], v[50:53]
	v_mfma_f32_16x16x32_bf16 v[38:41], v[146:149], v[170:173], v[38:41]
	v_mfma_f32_16x16x32_bf16 v[38:41], v[150:153], v[184:187], v[38:41]
	v_mfma_f32_16x16x32_bf16 v[34:37], v[154:157], v[170:173], v[34:37]
	v_mfma_f32_16x16x32_bf16 v[34:37], v[158:161], v[184:187], v[34:37]
	v_mfma_f32_16x16x32_bf16 v[22:25], v[146:149], v[188:191], v[22:25]
	v_mfma_f32_16x16x32_bf16 v[22:25], v[150:153], v[192:195], v[22:25]
	v_mfma_f32_16x16x32_bf16 v[18:21], v[154:157], v[188:191], v[18:21]
	v_mfma_f32_16x16x32_bf16 v[18:21], v[158:161], v[192:195], v[18:21]
	v_mfma_f32_16x16x32_bf16 v[6:9], v[146:149], v[196:199], v[6:9]
	v_mfma_f32_16x16x32_bf16 v[6:9], v[150:153], v[200:203], v[6:9]
	v_mfma_f32_16x16x32_bf16 v[2:5], v[154:157], v[196:199], v[2:5]
	v_mfma_f32_16x16x32_bf16 v[2:5], v[158:161], v[200:203], v[2:5]
	s_setprio 0
	s_barrier
	s_add_i32 s83, s83, 2
	s_add_u32 s58, s58, 0x100
	s_addc_u32 s59, s59, 0
	s_add_u32 s67, s67, 0x100
	s_addc_u32 s78, s78, 0
	s_add_u32 s28, s28, 0x100
	s_addc_u32 s29, s29, 0
	s_cmp_gt_u32 s83, 29
	s_cbranch_scc0 .LBB0_986
	s_and_b64 vcc, exec, s[16:17]
	s_cbranch_vccz .LBB0_989
	s_barrier

; #define PG8_LDA(dst, b, h) do { _Pragma("unroll") for (int m = 0; m < 4; ++m) _Pragma("unroll") for (int k = 0; k < 2; ++k) dst[m][k] = *(const PG8_LAS bf16x8*)(lds + PG8_SA(b, h) + aoff + m * 2048 + k * 1024); } while (0)
; #define PG8_LDB(dst, b, h) do { _Pragma("unroll") for (int n = 0; n < 2; ++n) _Pragma("unroll") for (int k = 0; k < 2; ++k) dst[n][k] = *(const PG8_LAS bf16x8*)(lds + PG8_SB(b, h) + boff + n * 2048 + k * 1024); } while (0)
; #define PG8_MMA(ai, bj, At, Bt) do { __builtin_amdgcn_s_setprio(1); _Pragma("unroll") for (int m = 0; m < 4; ++m) _Pragma("unroll") for (int n = 0; n < 2; ++n) _Pragma("unroll") for (int k = 0; k < 2; ++k) \
;         acc[ai][bj][m][n] = __builtin_amdgcn_mfma_f32_16x16x32_bf16(Bt[n][k], At[m][k], acc[ai][bj][m][n], 0, 0, 0); __builtin_amdgcn_s_setprio(0); } while (0)
; #define PG8_WAIT_V(n) asm volatile("s_waitcnt vmcnt(" #n ")" ::: "memory")
; #define PG8_WAIT_L(n) asm volatile("s_waitcnt lgkmcnt(" #n ")" ::: "memory")
; #define PG8_BAR __builtin_amdgcn_s_barrier()
; #define PG8_SCHED __builtin_amdgcn_sched_barrier(0)
;     __device__ __forceinline__ void a_ready(const Unit& u) const {
;         if (u.fill && tid < 256) {
;             const f32x4* p = (const f32x4*)(ssq + (size_t)(u.pm * BM + tid) * 32); float s = 0.f;
; #pragma unroll
;             for (int j = 0; j < 8; ++j) { const f32x4 a = p[j]; s += (a[0] + a[1]) + (a[2] + a[3]); }
;             tab[u.slot * 256 + tid] = __builtin_amdgcn_rsqf(s * inv_ncol + eps);
;         }
; template <class Epi, class Sched, bool ALIGN_EPI = false, bool SP2 = false>
; __device__ __forceinline__ void gemm_phase(PG8_LAS unsigned char* lds, const Gemm g, const Sched& S, const Epi& E, const int tid) {
;     ...
;             PG8_LDB(B0, 0, 0); PG8_LDB(B1, 0, 1); PG8_SCHED; PG8_LDA(At, 0, 0); PG8_STAGE(PG8_SA(1, 1), a1 + hstepA, voffA);
;             PG8_WAIT_V(8); PG8_WAIT_L(0); PG8_BAR; PG8_MMA(0, 0, At, B0); PG8_MMA(0, 1, At, B1); PG8_BAR; PG8_SCHED;
;             PG8_LDA(At, 0, 1); PG8_STAGE(PG8_SB(0, 0), b2, voffB); PG8_STAGE(PG8_SB(0, 1), b2 + hstepB, voffB); PG8_STAGE(PG8_SA(0, 0), a2, voffA);
;             PG8_WAIT_V(8); PG8_WAIT_L(0); PG8_BAR; PG8_MMA(1, 0, At, B0); PG8_MMA(1, 1, At, B1); PG8_BAR; PG8_SCHED;
.LBB0_1070:
	s_or_b64 exec, exec, s[34:35]
	v_add_u32_e32 v145, 0x10000, v154
	ds_read_b128 v[156:159], v145
	ds_read_b128 v[160:163], v145 offset:1024
	ds_read_b128 v[164:167], v145 offset:2048
	ds_read_b128 v[168:171], v145 offset:3072
	v_add_u32_e32 v145, 0x14000, v154
	s_add_u32 s34, s26, 0x100
	ds_read_b128 v[172:175], v145
	ds_read_b128 v[176:179], v145 offset:1024
	ds_read_b128 v[180:183], v145 offset:2048
	ds_read_b128 v[184:187], v145 offset:3072
	s_addc_u32 s35, s27, 0
	s_and_b64 s[30:31], s[30:31], exec
	s_cselect_b32 s42, s91, s34
	s_cselect_b32 s43, s19, s35
	s_cselect_b32 s31, s17, s67
	s_cselect_b32 s30, s95, s59
	s_add_u32 s38, s42, 0x80
	s_addc_u32 s39, s43, 0
	s_add_u32 s40, s30, 0x80
	s_addc_u32 s41, s31, 0
	ds_read_b128 v[188:191], v155
	ds_read_b128 v[192:195], v155 offset:1024
	ds_read_b128 v[196:199], v155 offset:2048
	ds_read_b128 v[200:203], v155 offset:3072
	ds_read_b128 v[204:207], v155 offset:4096
	ds_read_b128 v[208:211], v155 offset:5120
	ds_read_b128 v[212:215], v155 offset:6144
	ds_read_b128 v[216:219], v155 offset:7168
	s_add_u32 s26, s26, 0x80080
	s_addc_u32 s27, s27, 0
	s_mov_b32 m0, s69
	s_nop 0
	global_load_lds_dwordx4 v149, s[26:27]
	s_nop 0
	s_mov_b32 m0, s58
	s_nop 0
	global_load_lds_dwordx4 v151, s[26:27]
	s_waitcnt vmcnt(8)
	s_waitcnt lgkmcnt(0)
	s_barrier
	s_setprio 1
	v_mfma_f32_16x16x32_bf16 v[126:129], v[156:159], v[188:191], v[126:129]
	v_mfma_f32_16x16x32_bf16 v[126:129], v[160:163], v[192:195], v[126:129]
	v_mfma_f32_16x16x32_bf16 v[122:125], v[164:167], v[188:191], v[122:125]
	v_mfma_f32_16x16x32_bf16 v[122:125], v[168:171], v[192:195], v[122:125]
	v_mfma_f32_16x16x32_bf16 v[110:113], v[156:159], v[196:199], v[110:113]
	v_mfma_f32_16x16x32_bf16 v[110:113], v[160:163], v[200:203], v[110:113]
	v_mfma_f32_16x16x32_bf16 v[106:109], v[164:167], v[196:199], v[106:109]
	v_mfma_f32_16x16x32_bf16 v[106:109], v[168:171], v[200:203], v[106:109]
	v_mfma_f32_16x16x32_bf16 v[94:97], v[156:159], v[204:207], v[94:97]
	v_mfma_f32_16x16x32_bf16 v[94:97], v[160:163], v[208:211], v[94:97]
	v_mfma_f32_16x16x32_bf16 v[90:93], v[164:167], v[204:207], v[90:93]
	v_mfma_f32_16x16x32_bf16 v[90:93], v[168:171], v[208:211], v[90:93]
	v_mfma_f32_16x16x32_bf16 v[78:81], v[156:159], v[212:215], v[78:81]
	v_mfma_f32_16x16x32_bf16 v[78:81], v[160:163], v[216:219], v[78:81]
	v_mfma_f32_16x16x32_bf16 v[74:77], v[164:167], v[212:215], v[74:77]
	v_mfma_f32_16x16x32_bf16 v[74:77], v[168:171], v[216:219], v[74:77]
	v_mfma_f32_16x16x32_bf16 v[118:121], v[172:175], v[188:191], v[118:121]
	v_mfma_f32_16x16x32_bf16 v[118:121], v[176:179], v[192:195], v[118:121]
	v_mfma_f32_16x16x32_bf16 v[114:117], v[180:183], v[188:191], v[114:117]
	v_mfma_f32_16x16x32_bf16 v[114:117], v[184:187], v[192:195], v[114:117]
	v_mfma_f32_16x16x32_bf16 v[102:105], v[172:175], v[196:199], v[102:105]
	v_mfma_f32_16x16x32_bf16 v[102:105], v[176:179], v[200:203], v[102:105]
	v_mfma_f32_16x16x32_bf16 v[98:101], v[180:183], v[196:199], v[98:101]
	v_mfma_f32_16x16x32_bf16 v[98:101], v[184:187], v[200:203], v[98:101]
	v_mfma_f32_16x16x32_bf16 v[86:89], v[172:175], v[204:207], v[86:89]
	v_mfma_f32_16x16x32_bf16 v[86:89], v[176:179], v[208:211], v[86:89]
	v_mfma_f32_16x16x32_bf16 v[82:85], v[180:183], v[204:207], v[82:85]
	v_mfma_f32_16x16x32_bf16 v[82:85], v[184:187], v[208:211], v[82:85]
	v_mfma_f32_16x16x32_bf16 v[70:73], v[172:175], v[212:215], v[70:73]
	v_mfma_f32_16x16x32_bf16 v[70:73], v[176:179], v[216:219], v[70:73]
	v_mfma_f32_16x16x32_bf16 v[66:69], v[180:183], v[212:215], v[66:69]
	v_mfma_f32_16x16x32_bf16 v[66:69], v[184:187], v[216:219], v[66:69]
	s_setprio 0
	s_barrier
	ds_read_b128 v[188:191], v155 offset:16384
	ds_read_b128 v[192:195], v155 offset:17408
	ds_read_b128 v[196:199], v155 offset:18432
	ds_read_b128 v[200:203], v155 offset:19456
	ds_read_b128 v[204:207], v155 offset:20480
	ds_read_b128 v[208:211], v155 offset:21504
	ds_read_b128 v[212:215], v155 offset:22528
	ds_read_b128 v[216:219], v155 offset:23552
	s_mov_b32 m0, s15
	s_nop 0
	global_load_lds_dwordx4 v150, s[30:31]
	s_nop 0
	s_mov_b32 m0, s25
	s_nop 0
	global_load_lds_dwordx4 v152, s[30:31]
	s_add_u32 s26, s30, 0x80000
	s_addc_u32 s27, s31, 0
	s_mov_b32 m0, s48
	s_nop 0
	global_load_lds_dwordx4 v150, s[26:27]
	s_nop 0
	s_mov_b32 m0, s49
	s_nop 0
	global_load_lds_dwordx4 v152, s[26:27]
	s_mov_b32 m0, s10
	s_nop 0
	global_load_lds_dwordx4 v149, s[42:43]
	s_nop 0
	s_mov_b32 m0, s50
	s_nop 0
	global_load_lds_dwordx4 v151, s[42:43]
	s_waitcnt vmcnt(8)
	s_waitcnt lgkmcnt(0)
	s_barrier
	s_setprio 1
	v_mfma_f32_16x16x32_bf16 v[62:65], v[156:159], v[188:191], v[62:65]
	v_mfma_f32_16x16x32_bf16 v[62:65], v[160:163], v[192:195], v[62:65]
	v_mfma_f32_16x16x32_bf16 v[58:61], v[164:167], v[188:191], v[58:61]
	v_mfma_f32_16x16x32_bf16 v[58:61], v[168:171], v[192:195], v[58:61]
	v_mfma_f32_16x16x32_bf16 v[46:49], v[156:159], v[196:199], v[46:49]
	v_mfma_f32_16x16x32_bf16 v[46:49], v[160:163], v[200:203], v[46:49]
	v_mfma_f32_16x16x32_bf16 v[42:45], v[164:167], v[196:199], v[42:45]
	v_mfma_f32_16x16x32_bf16 v[42:45], v[168:171], v[200:203], v[42:45]
	v_mfma_f32_16x16x32_bf16 v[30:33], v[156:159], v[204:207], v[30:33]
	v_mfma_f32_16x16x32_bf16 v[30:33], v[160:163], v[208:211], v[30:33]
	v_mfma_f32_16x16x32_bf16 v[26:29], v[164:167], v[204:207], v[26:29]
	v_mfma_f32_16x16x32_bf16 v[26:29], v[168:171], v[208:211], v[26:29]
	v_mfma_f32_16x16x32_bf16 v[14:17], v[156:159], v[212:215], v[14:17]
	v_mfma_f32_16x16x32_bf16 v[14:17], v[160:163], v[216:219], v[14:17]
	v_mfma_f32_16x16x32_bf16 v[10:13], v[164:167], v[212:215], v[10:13]
	v_mfma_f32_16x16x32_bf16 v[10:13], v[168:171], v[216:219], v[10:13]
	v_mfma_f32_16x16x32_bf16 v[54:57], v[172:175], v[188:191], v[54:57]
	v_mfma_f32_16x16x32_bf16 v[54:57], v[176:179], v[192:195], v[54:57]
	v_mfma_f32_16x16x32_bf16 v[50:53], v[180:183], v[188:191], v[50:53]
	v_mfma_f32_16x16x32_bf16 v[50:53], v[184:187], v[192:195], v[50:53]
	v_mfma_f32_16x16x32_bf16 v[38:41], v[172:175], v[196:199], v[38:41]
	v_mfma_f32_16x16x32_bf16 v[38:41], v[176:179], v[200:203], v[38:41]
	v_mfma_f32_16x16x32_bf16 v[34:37], v[180:183], v[196:199], v[34:37]
	v_mfma_f32_16x16x32_bf16 v[34:37], v[184:187], v[200:203], v[34:37]
	v_mfma_f32_16x16x32_bf16 v[22:25], v[172:175], v[204:207], v[22:25]
	v_mfma_f32_16x16x32_bf16 v[22:25], v[176:179], v[208:211], v[22:25]
	v_mfma_f32_16x16x32_bf16 v[18:21], v[180:183], v[204:207], v[18:21]
	v_mfma_f32_16x16x32_bf16 v[18:21], v[184:187], v[208:211], v[18:21]
	v_mfma_f32_16x16x32_bf16 v[6:9], v[172:175], v[212:215], v[6:9]
	v_mfma_f32_16x16x32_bf16 v[6:9], v[176:179], v[216:219], v[6:9]
	v_mfma_f32_16x16x32_bf16 v[2:5], v[180:183], v[212:215], v[2:5]
	v_mfma_f32_16x16x32_bf16 v[2:5], v[184:187], v[216:219], v[2:5]
	s_setprio 0
	s_barrier
; #define PG8_LDA(dst, b, h) do { _Pragma("unroll") for (int m = 0; m < 4; ++m) _Pragma("unroll") for (int k = 0; k < 2; ++k) dst[m][k] = *(const PG8_LAS bf16x8*)(lds + PG8_SA(b, h) + aoff + m * 2048 + k * 1024); } while (0)
; #define PG8_LDB(dst, b, h) do { _Pragma("unroll") for (int n = 0; n < 2; ++n) _Pragma("unroll") for (int k = 0; k < 2; ++k) dst[n][k] = *(const PG8_LAS bf16x8*)(lds + PG8_SB(b, h) + boff + n * 2048 + k * 1024); } while (0)
; #define PG8_MMA(ai, bj, At, Bt) do { __builtin_amdgcn_s_setprio(1); _Pragma("unroll") for (int m = 0; m < 4; ++m) _Pragma("unroll") for (int n = 0; n < 2; ++n) _Pragma("unroll") for (int k = 0; k < 2; ++k) \
;         acc[ai][bj][m][n] = __builtin_amdgcn_mfma_f32_16x16x32_bf16(Bt[n][k], At[m][k], acc[ai][bj][m][n], 0, 0, 0); __builtin_amdgcn_s_setprio(0); } while (0)
; #define PG8_WAIT_V(n) asm volatile("s_waitcnt vmcnt(" #n ")" ::: "memory")
; #define PG8_WAIT_L(n) asm volatile("s_waitcnt lgkmcnt(" #n ")" ::: "memory")
; #define PG8_BAR __builtin_amdgcn_s_barrier()
; #define PG8_SCHED __builtin_amdgcn_sched_barrier(0)
; template <class Epi, class Sched, bool ALIGN_EPI = false, bool SP2 = false>
; __device__ __forceinline__ void gemm_phase(PG8_LAS unsigned char* lds, const Gemm g, const Sched& S, const Epi& E, const int tid) {
;     ...
;             PG8_LDB(B0, 1, 0); PG8_LDB(B1, 1, 1); PG8_SCHED; PG8_LDA(At, 1, 0); PG8_STAGE(PG8_SA(0, 1), a2 + hstepA, voffA);
;             PG8_WAIT_V(8); PG8_WAIT_L(0); PG8_BAR; PG8_MMA(0, 0, At, B0); PG8_MMA(0, 1, At, B1); PG8_BAR; PG8_SCHED;
;             PG8_LDA(At, 1, 1); PG8_STAGE(PG8_SB(1, 0), b3, voffB); PG8_STAGE(PG8_SB(1, 1), b3 + hstepB, voffB); PG8_STAGE(PG8_SA(1, 0), a3, voffA);
;             PG8_WAIT_V(8); PG8_WAIT_L(0); PG8_BAR; PG8_MMA(1, 0, At, B0); PG8_MMA(1, 1, At, B1); PG8_BAR; PG8_SCHED;
	v_add_u32_e32 v145, 0x18000, v154
	ds_read_b128 v[156:159], v145
	ds_read_b128 v[160:163], v145 offset:1024
	ds_read_b128 v[164:167], v145 offset:2048
	ds_read_b128 v[168:171], v145 offset:3072
	v_add_u32_e32 v145, 0x1c000, v154
	ds_read_b128 v[172:175], v145
	ds_read_b128 v[176:179], v145 offset:1024
	ds_read_b128 v[180:183], v145 offset:2048
	ds_read_b128 v[184:187], v145 offset:3072
	ds_read_b128 v[188:191], v155 offset:32768
	ds_read_b128 v[192:195], v155 offset:33792
	ds_read_b128 v[196:199], v155 offset:34816
	ds_read_b128 v[200:203], v155 offset:35840
	ds_read_b128 v[204:207], v155 offset:36864
	ds_read_b128 v[208:211], v155 offset:37888
	ds_read_b128 v[212:215], v155 offset:38912
	ds_read_b128 v[216:219], v155 offset:39936
	s_add_u32 s26, s42, 0x80000
	s_addc_u32 s27, s43, 0
	s_mov_b32 m0, s51
	s_nop 0
	global_load_lds_dwordx4 v149, s[26:27]
	s_nop 0
	s_mov_b32 m0, s54
	s_nop 0
	global_load_lds_dwordx4 v151, s[26:27]
	s_waitcnt vmcnt(8)
	s_waitcnt lgkmcnt(0)
	s_barrier
	s_setprio 1
	v_mfma_f32_16x16x32_bf16 v[126:129], v[156:159], v[188:191], v[126:129]
	v_mfma_f32_16x16x32_bf16 v[126:129], v[160:163], v[192:195], v[126:129]
	v_mfma_f32_16x16x32_bf16 v[122:125], v[164:167], v[188:191], v[122:125]
	v_mfma_f32_16x16x32_bf16 v[122:125], v[168:171], v[192:195], v[122:125]
	v_mfma_f32_16x16x32_bf16 v[110:113], v[156:159], v[196:199], v[110:113]
	v_mfma_f32_16x16x32_bf16 v[110:113], v[160:163], v[200:203], v[110:113]
	v_mfma_f32_16x16x32_bf16 v[106:109], v[164:167], v[196:199], v[106:109]
	v_mfma_f32_16x16x32_bf16 v[106:109], v[168:171], v[200:203], v[106:109]
	v_mfma_f32_16x16x32_bf16 v[94:97], v[156:159], v[204:207], v[94:97]
	v_mfma_f32_16x16x32_bf16 v[94:97], v[160:163], v[208:211], v[94:97]
	v_mfma_f32_16x16x32_bf16 v[90:93], v[164:167], v[204:207], v[90:93]
	v_mfma_f32_16x16x32_bf16 v[90:93], v[168:171], v[208:211], v[90:93]
	v_mfma_f32_16x16x32_bf16 v[78:81], v[156:159], v[212:215], v[78:81]
	v_mfma_f32_16x16x32_bf16 v[78:81], v[160:163], v[216:219], v[78:81]
	v_mfma_f32_16x16x32_bf16 v[74:77], v[164:167], v[212:215], v[74:77]
	v_mfma_f32_16x16x32_bf16 v[74:77], v[168:171], v[216:219], v[74:77]
	v_mfma_f32_16x16x32_bf16 v[118:121], v[172:175], v[188:191], v[118:121]
	v_mfma_f32_16x16x32_bf16 v[118:121], v[176:179], v[192:195], v[118:121]
	v_mfma_f32_16x16x32_bf16 v[114:117], v[180:183], v[188:191], v[114:117]
	v_mfma_f32_16x16x32_bf16 v[114:117], v[184:187], v[192:195], v[114:117]
	v_mfma_f32_16x16x32_bf16 v[102:105], v[172:175], v[196:199], v[102:105]
	v_mfma_f32_16x16x32_bf16 v[102:105], v[176:179], v[200:203], v[102:105]
	v_mfma_f32_16x16x32_bf16 v[98:101], v[180:183], v[196:199], v[98:101]
	v_mfma_f32_16x16x32_bf16 v[98:101], v[184:187], v[200:203], v[98:101]
	v_mfma_f32_16x16x32_bf16 v[86:89], v[172:175], v[204:207], v[86:89]
	v_mfma_f32_16x16x32_bf16 v[86:89], v[176:179], v[208:211], v[86:89]
	v_mfma_f32_16x16x32_bf16 v[82:85], v[180:183], v[204:207], v[82:85]
	v_mfma_f32_16x16x32_bf16 v[82:85], v[184:187], v[208:211], v[82:85]
	v_mfma_f32_16x16x32_bf16 v[70:73], v[172:175], v[212:215], v[70:73]
	v_mfma_f32_16x16x32_bf16 v[70:73], v[176:179], v[216:219], v[70:73]
	v_mfma_f32_16x16x32_bf16 v[66:69], v[180:183], v[212:215], v[66:69]
	v_mfma_f32_16x16x32_bf16 v[66:69], v[184:187], v[216:219], v[66:69]
	s_setprio 0
	s_barrier
	ds_read_b128 v[188:191], v155 offset:49152
	ds_read_b128 v[192:195], v155 offset:50176
	ds_read_b128 v[196:199], v155 offset:51200
	ds_read_b128 v[200:203], v155 offset:52224
	ds_read_b128 v[204:207], v155 offset:53248
	ds_read_b128 v[208:211], v155 offset:54272
	ds_read_b128 v[212:215], v155 offset:55296
	ds_read_b128 v[216:219], v155 offset:56320
	s_mov_b32 m0, s55
	s_nop 0
	global_load_lds_dwordx4 v150, s[40:41]
	s_nop 0
	s_mov_b32 m0, s56
	s_nop 0
	global_load_lds_dwordx4 v152, s[40:41]
	s_add_u32 s26, s30, 0x80080
	s_addc_u32 s27, s31, 0
	s_mov_b32 m0, s64
	s_nop 0
	global_load_lds_dwordx4 v150, s[26:27]
	s_nop 0
	s_mov_b32 m0, s65
	s_nop 0
	global_load_lds_dwordx4 v152, s[26:27]
	s_mov_b32 m0, s57
	s_nop 0
	global_load_lds_dwordx4 v149, s[38:39]
	s_nop 0
	s_mov_b32 m0, s61
	s_nop 0
	global_load_lds_dwordx4 v151, s[38:39]
	s_waitcnt vmcnt(8)
	s_waitcnt lgkmcnt(0)
	s_barrier
	s_setprio 1
	v_mfma_f32_16x16x32_bf16 v[62:65], v[156:159], v[188:191], v[62:65]
	v_mfma_f32_16x16x32_bf16 v[62:65], v[160:163], v[192:195], v[62:65]
	v_mfma_f32_16x16x32_bf16 v[58:61], v[164:167], v[188:191], v[58:61]
	v_mfma_f32_16x16x32_bf16 v[58:61], v[168:171], v[192:195], v[58:61]
	v_mfma_f32_16x16x32_bf16 v[46:49], v[156:159], v[196:199], v[46:49]
	v_mfma_f32_16x16x32_bf16 v[46:49], v[160:163], v[200:203], v[46:49]
	v_mfma_f32_16x16x32_bf16 v[42:45], v[164:167], v[196:199], v[42:45]
	v_mfma_f32_16x16x32_bf16 v[42:45], v[168:171], v[200:203], v[42:45]
	v_mfma_f32_16x16x32_bf16 v[30:33], v[156:159], v[204:207], v[30:33]
	v_mfma_f32_16x16x32_bf16 v[30:33], v[160:163], v[208:211], v[30:33]
	v_mfma_f32_16x16x32_bf16 v[26:29], v[164:167], v[204:207], v[26:29]
	v_mfma_f32_16x16x32_bf16 v[26:29], v[168:171], v[208:211], v[26:29]
	v_mfma_f32_16x16x32_bf16 v[14:17], v[156:159], v[212:215], v[14:17]
	v_mfma_f32_16x16x32_bf16 v[14:17], v[160:163], v[216:219], v[14:17]
	v_mfma_f32_16x16x32_bf16 v[10:13], v[164:167], v[212:215], v[10:13]
	v_mfma_f32_16x16x32_bf16 v[10:13], v[168:171], v[216:219], v[10:13]
	v_mfma_f32_16x16x32_bf16 v[54:57], v[172:175], v[188:191], v[54:57]
	v_mfma_f32_16x16x32_bf16 v[54:57], v[176:179], v[192:195], v[54:57]
	v_mfma_f32_16x16x32_bf16 v[50:53], v[180:183], v[188:191], v[50:53]
	v_mfma_f32_16x16x32_bf16 v[50:53], v[184:187], v[192:195], v[50:53]
	v_mfma_f32_16x16x32_bf16 v[38:41], v[172:175], v[196:199], v[38:41]
	v_mfma_f32_16x16x32_bf16 v[38:41], v[176:179], v[200:203], v[38:41]
	v_mfma_f32_16x16x32_bf16 v[34:37], v[180:183], v[196:199], v[34:37]
	v_mfma_f32_16x16x32_bf16 v[34:37], v[184:187], v[200:203], v[34:37]
	v_mfma_f32_16x16x32_bf16 v[22:25], v[172:175], v[204:207], v[22:25]
	v_mfma_f32_16x16x32_bf16 v[22:25], v[176:179], v[208:211], v[22:25]
	v_mfma_f32_16x16x32_bf16 v[18:21], v[180:183], v[204:207], v[18:21]
	v_mfma_f32_16x16x32_bf16 v[18:21], v[184:187], v[208:211], v[18:21]
	v_mfma_f32_16x16x32_bf16 v[6:9], v[172:175], v[212:215], v[6:9]
	v_mfma_f32_16x16x32_bf16 v[6:9], v[176:179], v[216:219], v[6:9]
	v_mfma_f32_16x16x32_bf16 v[2:5], v[180:183], v[212:215], v[2:5]
	v_mfma_f32_16x16x32_bf16 v[2:5], v[184:187], v[216:219], v[2:5]
	s_setprio 0
	s_barrier
	s_add_i32 s11, s11, 2
	s_add_u32 s59, s59, 0x100
	s_addc_u32 s67, s67, 0
	s_cmp_gt_u32 s11, 29
	s_mov_b64 s[26:27], s[34:35]
	s_cbranch_scc1 .LBB0_1073

; #define PG8_LDA(dst, b, h) do { _Pragma("unroll") for (int m = 0; m < 4; ++m) _Pragma("unroll") for (int k = 0; k < 2; ++k) dst[m][k] = *(const PG8_LAS bf16x8*)(lds + PG8_SA(b, h) + aoff + m * 2048 + k * 1024); } while (0)
; #define PG8_LDB(dst, b, h) do { _Pragma("unroll") for (int n = 0; n < 2; ++n) _Pragma("unroll") for (int k = 0; k < 2; ++k) dst[n][k] = *(const PG8_LAS bf16x8*)(lds + PG8_SB(b, h) + boff + n * 2048 + k * 1024); } while (0)
; #define PG8_MMA(ai, bj, At, Bt) do { __builtin_amdgcn_s_setprio(1); _Pragma("unroll") for (int m = 0; m < 4; ++m) _Pragma("unroll") for (int n = 0; n < 2; ++n) _Pragma("unroll") for (int k = 0; k < 2; ++k) \
;         acc[ai][bj][m][n] = __builtin_amdgcn_mfma_f32_16x16x32_bf16(Bt[n][k], At[m][k], acc[ai][bj][m][n], 0, 0, 0); __builtin_amdgcn_s_setprio(0); } while (0)
; #define PG8_WAIT_V(n) asm volatile("s_waitcnt vmcnt(" #n ")" ::: "memory")
; #define PG8_WAIT_L(n) asm volatile("s_waitcnt lgkmcnt(" #n ")" ::: "memory")
; #define PG8_BAR __builtin_amdgcn_s_barrier()
; #define PG8_SCHED __builtin_amdgcn_sched_barrier(0)
; template <class Epi, class Sched, bool ALIGN_EPI = false, bool SP2 = false>
; __device__ __forceinline__ void gemm_phase(PG8_LAS unsigned char* lds, const Gemm g, const Sched& S, const Epi& E, const int tid) {
;     ...
;             PG8_LDB(B0, 0, 0); PG8_LDB(B1, 0, 1); PG8_SCHED; PG8_LDA(At, 0, 0); PG8_STAGE(PG8_SA(1, 1), a1 + hstepA, voffA);
;             PG8_WAIT_V(8); PG8_WAIT_L(0); PG8_BAR; PG8_MMA(0, 0, At, B0); PG8_MMA(0, 1, At, B1); PG8_BAR; PG8_SCHED;
;             PG8_LDA(At, 0, 1); PG8_STAGE(PG8_SB(0, 0), b2, voffB); PG8_STAGE(PG8_SB(0, 1), b2 + hstepB, voffB); PG8_STAGE(PG8_SA(0, 0), a2, voffA);
;             PG8_WAIT_V(8); PG8_WAIT_L(0); PG8_BAR; PG8_MMA(1, 0, At, B0); PG8_MMA(1, 1, At, B1); PG8_BAR; PG8_SCHED;
.LBB0_1151:
	v_add_u32_e32 v142, 0x10000, v185
	v_add_u32_e32 v158, 0x14000, v185
	ds_read_b128 v[122:125], v142
	ds_read_b128 v[130:133], v142 offset:1024
	ds_read_b128 v[138:141], v142 offset:2048
	ds_read_b128 v[142:145], v142 offset:3072
	ds_read_b128 v[146:149], v158
	ds_read_b128 v[150:153], v158 offset:1024
	ds_read_b128 v[154:157], v158 offset:2048
	ds_read_b128 v[158:161], v158 offset:3072
	s_cmpk_eq_i32 s89, 0x54
	s_cselect_b32 s34, s26, s83
	s_cselect_b32 s35, s27, s87
	s_cselect_b32 s30, s28, s59
	s_cselect_b32 s31, s29, s67
	s_add_u32 s8, s34, 0x8000
	s_addc_u32 s9, s35, 0
	ds_read_b128 v[162:165], v186
	ds_read_b128 v[166:169], v186 offset:1024
	ds_read_b128 v[170:173], v186 offset:2048
	ds_read_b128 v[174:177], v186 offset:3072
	ds_read_b128 v[188:191], v186 offset:4096
	ds_read_b128 v[192:195], v186 offset:5120
	ds_read_b128 v[196:199], v186 offset:6144
	ds_read_b128 v[200:203], v186 offset:7168
	s_mov_b32 m0, s61
	s_nop 0
	global_load_lds_dwordx4 v0, s[6:7]
	s_nop 0
	s_mov_b32 m0, s64
	s_nop 0
	global_load_lds_dwordx4 v181, s[6:7]
	s_waitcnt vmcnt(8)
	s_waitcnt lgkmcnt(0)
	s_barrier
	s_setprio 1
	v_mfma_f32_16x16x32_bf16 v[134:137], v[122:125], v[162:165], v[134:137]
	v_mfma_f32_16x16x32_bf16 v[134:137], v[130:133], v[166:169], v[134:137]
	v_mfma_f32_16x16x32_bf16 v[126:129], v[138:141], v[162:165], v[126:129]
	v_mfma_f32_16x16x32_bf16 v[126:129], v[142:145], v[166:169], v[126:129]
	v_mfma_f32_16x16x32_bf16 v[110:113], v[122:125], v[170:173], v[110:113]
	v_mfma_f32_16x16x32_bf16 v[110:113], v[130:133], v[174:177], v[110:113]
	v_mfma_f32_16x16x32_bf16 v[106:109], v[138:141], v[170:173], v[106:109]
	v_mfma_f32_16x16x32_bf16 v[106:109], v[142:145], v[174:177], v[106:109]
	v_mfma_f32_16x16x32_bf16 v[94:97], v[122:125], v[188:191], v[94:97]
	v_mfma_f32_16x16x32_bf16 v[94:97], v[130:133], v[192:195], v[94:97]
	v_mfma_f32_16x16x32_bf16 v[90:93], v[138:141], v[188:191], v[90:93]
	v_mfma_f32_16x16x32_bf16 v[90:93], v[142:145], v[192:195], v[90:93]
	v_mfma_f32_16x16x32_bf16 v[78:81], v[122:125], v[196:199], v[78:81]
	v_mfma_f32_16x16x32_bf16 v[78:81], v[130:133], v[200:203], v[78:81]
	v_mfma_f32_16x16x32_bf16 v[74:77], v[138:141], v[196:199], v[74:77]
	v_mfma_f32_16x16x32_bf16 v[74:77], v[142:145], v[200:203], v[74:77]
	v_mfma_f32_16x16x32_bf16 v[118:121], v[146:149], v[162:165], v[118:121]
	v_mfma_f32_16x16x32_bf16 v[118:121], v[150:153], v[166:169], v[118:121]
	v_mfma_f32_16x16x32_bf16 v[114:117], v[154:157], v[162:165], v[114:117]
	v_mfma_f32_16x16x32_bf16 v[114:117], v[158:161], v[166:169], v[114:117]
	v_mfma_f32_16x16x32_bf16 v[102:105], v[146:149], v[170:173], v[102:105]
	v_mfma_f32_16x16x32_bf16 v[102:105], v[150:153], v[174:177], v[102:105]
	v_mfma_f32_16x16x32_bf16 v[98:101], v[154:157], v[170:173], v[98:101]
	v_mfma_f32_16x16x32_bf16 v[98:101], v[158:161], v[174:177], v[98:101]
	v_mfma_f32_16x16x32_bf16 v[86:89], v[146:149], v[188:191], v[86:89]
	v_mfma_f32_16x16x32_bf16 v[86:89], v[150:153], v[192:195], v[86:89]
	v_mfma_f32_16x16x32_bf16 v[82:85], v[154:157], v[188:191], v[82:85]
	v_mfma_f32_16x16x32_bf16 v[82:85], v[158:161], v[192:195], v[82:85]
	v_mfma_f32_16x16x32_bf16 v[70:73], v[146:149], v[196:199], v[70:73]
	v_mfma_f32_16x16x32_bf16 v[70:73], v[150:153], v[200:203], v[70:73]
	v_mfma_f32_16x16x32_bf16 v[66:69], v[154:157], v[196:199], v[66:69]
	v_mfma_f32_16x16x32_bf16 v[66:69], v[158:161], v[200:203], v[66:69]
	s_setprio 0
	s_barrier
	ds_read_b128 v[162:165], v186 offset:16384
	ds_read_b128 v[166:169], v186 offset:17408
	ds_read_b128 v[170:173], v186 offset:18432
	ds_read_b128 v[174:177], v186 offset:19456
	ds_read_b128 v[188:191], v186 offset:20480
	ds_read_b128 v[192:195], v186 offset:21504
	ds_read_b128 v[196:199], v186 offset:22528
	ds_read_b128 v[200:203], v186 offset:23552
	s_mov_b32 m0, s41
	s_nop 0
	global_load_lds_dwordx4 v180, s[30:31]
	s_add_u32 s90, s30, 0x4000
	s_mov_b32 m0, s42
	s_nop 0
	global_load_lds_dwordx4 v182, s[30:31]
	s_addc_u32 s91, s31, 0
	s_mov_b32 m0, s43
	s_nop 0
	global_load_lds_dwordx4 v180, s[90:91]
	s_nop 0
	s_mov_b32 m0, s44
	s_nop 0
	global_load_lds_dwordx4 v182, s[90:91]
	s_nop 0
	s_mov_b32 m0, s10
	s_nop 0
	global_load_lds_dwordx4 v0, s[34:35]
	s_nop 0
	s_mov_b32 m0, s45
	s_nop 0
	global_load_lds_dwordx4 v181, s[34:35]
	s_waitcnt vmcnt(8)
	s_waitcnt lgkmcnt(0)
	s_barrier
	s_setprio 1
	v_mfma_f32_16x16x32_bf16 v[62:65], v[122:125], v[162:165], v[62:65]
	v_mfma_f32_16x16x32_bf16 v[62:65], v[130:133], v[166:169], v[62:65]
	v_mfma_f32_16x16x32_bf16 v[58:61], v[138:141], v[162:165], v[58:61]
	v_mfma_f32_16x16x32_bf16 v[58:61], v[142:145], v[166:169], v[58:61]
	v_mfma_f32_16x16x32_bf16 v[46:49], v[122:125], v[170:173], v[46:49]
	v_mfma_f32_16x16x32_bf16 v[46:49], v[130:133], v[174:177], v[46:49]
	v_mfma_f32_16x16x32_bf16 v[42:45], v[138:141], v[170:173], v[42:45]
	v_mfma_f32_16x16x32_bf16 v[42:45], v[142:145], v[174:177], v[42:45]
	v_mfma_f32_16x16x32_bf16 v[30:33], v[122:125], v[188:191], v[30:33]
	v_mfma_f32_16x16x32_bf16 v[30:33], v[130:133], v[192:195], v[30:33]
	v_mfma_f32_16x16x32_bf16 v[26:29], v[138:141], v[188:191], v[26:29]
	v_mfma_f32_16x16x32_bf16 v[26:29], v[142:145], v[192:195], v[26:29]
	v_mfma_f32_16x16x32_bf16 v[14:17], v[122:125], v[196:199], v[14:17]
	v_mfma_f32_16x16x32_bf16 v[14:17], v[130:133], v[200:203], v[14:17]
	v_mfma_f32_16x16x32_bf16 v[10:13], v[138:141], v[196:199], v[10:13]
	v_mfma_f32_16x16x32_bf16 v[10:13], v[142:145], v[200:203], v[10:13]
	v_mfma_f32_16x16x32_bf16 v[54:57], v[146:149], v[162:165], v[54:57]
	v_mfma_f32_16x16x32_bf16 v[54:57], v[150:153], v[166:169], v[54:57]
	v_mfma_f32_16x16x32_bf16 v[50:53], v[154:157], v[162:165], v[50:53]
	v_mfma_f32_16x16x32_bf16 v[50:53], v[158:161], v[166:169], v[50:53]
	v_mfma_f32_16x16x32_bf16 v[38:41], v[146:149], v[170:173], v[38:41]
	v_mfma_f32_16x16x32_bf16 v[38:41], v[150:153], v[174:177], v[38:41]
	v_mfma_f32_16x16x32_bf16 v[34:37], v[154:157], v[170:173], v[34:37]
	v_mfma_f32_16x16x32_bf16 v[34:37], v[158:161], v[174:177], v[34:37]
	v_mfma_f32_16x16x32_bf16 v[22:25], v[146:149], v[188:191], v[22:25]
	v_mfma_f32_16x16x32_bf16 v[22:25], v[150:153], v[192:195], v[22:25]
	v_mfma_f32_16x16x32_bf16 v[18:21], v[154:157], v[188:191], v[18:21]
	v_mfma_f32_16x16x32_bf16 v[18:21], v[158:161], v[192:195], v[18:21]
	v_mfma_f32_16x16x32_bf16 v[6:9], v[146:149], v[196:199], v[6:9]
	v_mfma_f32_16x16x32_bf16 v[6:9], v[150:153], v[200:203], v[6:9]
	v_mfma_f32_16x16x32_bf16 v[2:5], v[154:157], v[196:199], v[2:5]
	v_mfma_f32_16x16x32_bf16 v[2:5], v[158:161], v[200:203], v[2:5]
	s_setprio 0
	s_barrier
; #define PG8_LDA(dst, b, h) do { _Pragma("unroll") for (int m = 0; m < 4; ++m) _Pragma("unroll") for (int k = 0; k < 2; ++k) dst[m][k] = *(const PG8_LAS bf16x8*)(lds + PG8_SA(b, h) + aoff + m * 2048 + k * 1024); } while (0)
; #define PG8_LDB(dst, b, h) do { _Pragma("unroll") for (int n = 0; n < 2; ++n) _Pragma("unroll") for (int k = 0; k < 2; ++k) dst[n][k] = *(const PG8_LAS bf16x8*)(lds + PG8_SB(b, h) + boff + n * 2048 + k * 1024); } while (0)
; #define PG8_MMA(ai, bj, At, Bt) do { __builtin_amdgcn_s_setprio(1); _Pragma("unroll") for (int m = 0; m < 4; ++m) _Pragma("unroll") for (int n = 0; n < 2; ++n) _Pragma("unroll") for (int k = 0; k < 2; ++k) \
;         acc[ai][bj][m][n] = __builtin_amdgcn_mfma_f32_16x16x32_bf16(Bt[n][k], At[m][k], acc[ai][bj][m][n], 0, 0, 0); __builtin_amdgcn_s_setprio(0); } while (0)
; #define PG8_WAIT_V(n) asm volatile("s_waitcnt vmcnt(" #n ")" ::: "memory")
; #define PG8_WAIT_L(n) asm volatile("s_waitcnt lgkmcnt(" #n ")" ::: "memory")
; #define PG8_BAR __builtin_amdgcn_s_barrier()
; #define PG8_SCHED __builtin_amdgcn_sched_barrier(0)
; template <class Epi, class Sched, bool ALIGN_EPI = false, bool SP2 = false>
; __device__ __forceinline__ void gemm_phase(PG8_LAS unsigned char* lds, const Gemm g, const Sched& S, const Epi& E, const int tid) {
;     ...
;             PG8_LDB(B0, 1, 0); PG8_LDB(B1, 1, 1); PG8_SCHED; PG8_LDA(At, 1, 0); PG8_STAGE(PG8_SA(0, 1), a2 + hstepA, voffA);
;             PG8_WAIT_V(8); PG8_WAIT_L(0); PG8_BAR; PG8_MMA(0, 0, At, B0); PG8_MMA(0, 1, At, B1); PG8_BAR; PG8_SCHED;
;             PG8_LDA(At, 1, 1); PG8_STAGE(PG8_SB(1, 0), b3, voffB); PG8_STAGE(PG8_SB(1, 1), b3 + hstepB, voffB); PG8_STAGE(PG8_SA(1, 0), a3, voffA);
;             PG8_WAIT_V(8); PG8_WAIT_L(0); PG8_BAR; PG8_MMA(1, 0, At, B0); PG8_MMA(1, 1, At, B1); PG8_BAR; PG8_SCHED;
	v_add_u32_e32 v142, 0x18000, v185
	v_add_u32_e32 v158, 0x1c000, v185
	ds_read_b128 v[122:125], v142
	ds_read_b128 v[130:133], v142 offset:1024
	ds_read_b128 v[138:141], v142 offset:2048
	ds_read_b128 v[142:145], v142 offset:3072
	ds_read_b128 v[146:149], v158
	ds_read_b128 v[150:153], v158 offset:1024
	ds_read_b128 v[154:157], v158 offset:2048
	ds_read_b128 v[158:161], v158 offset:3072
	ds_read_b128 v[162:165], v186 offset:32768
	ds_read_b128 v[166:169], v186 offset:33792
	ds_read_b128 v[170:173], v186 offset:34816
	ds_read_b128 v[174:177], v186 offset:35840
	ds_read_b128 v[188:191], v186 offset:36864
	ds_read_b128 v[192:195], v186 offset:37888
	ds_read_b128 v[196:199], v186 offset:38912
	ds_read_b128 v[200:203], v186 offset:39936
	s_add_u32 s34, s34, 0x4000
	s_addc_u32 s35, s35, 0
	s_mov_b32 m0, s46
	s_nop 0
	global_load_lds_dwordx4 v0, s[34:35]
	s_nop 0
	s_mov_b32 m0, s47
	s_nop 0
	global_load_lds_dwordx4 v181, s[34:35]
	s_waitcnt vmcnt(8)
	s_waitcnt lgkmcnt(0)
	s_barrier
	s_setprio 1
	v_mfma_f32_16x16x32_bf16 v[134:137], v[122:125], v[162:165], v[134:137]
	v_mfma_f32_16x16x32_bf16 v[134:137], v[130:133], v[166:169], v[134:137]
	v_mfma_f32_16x16x32_bf16 v[126:129], v[138:141], v[162:165], v[126:129]
	v_mfma_f32_16x16x32_bf16 v[126:129], v[142:145], v[166:169], v[126:129]
	v_mfma_f32_16x16x32_bf16 v[110:113], v[122:125], v[170:173], v[110:113]
	v_mfma_f32_16x16x32_bf16 v[110:113], v[130:133], v[174:177], v[110:113]
	v_mfma_f32_16x16x32_bf16 v[106:109], v[138:141], v[170:173], v[106:109]
	v_mfma_f32_16x16x32_bf16 v[106:109], v[142:145], v[174:177], v[106:109]
	v_mfma_f32_16x16x32_bf16 v[94:97], v[122:125], v[188:191], v[94:97]
	v_mfma_f32_16x16x32_bf16 v[94:97], v[130:133], v[192:195], v[94:97]
	v_mfma_f32_16x16x32_bf16 v[90:93], v[138:141], v[188:191], v[90:93]
	v_mfma_f32_16x16x32_bf16 v[90:93], v[142:145], v[192:195], v[90:93]
	v_mfma_f32_16x16x32_bf16 v[78:81], v[122:125], v[196:199], v[78:81]
	v_mfma_f32_16x16x32_bf16 v[78:81], v[130:133], v[200:203], v[78:81]
	v_mfma_f32_16x16x32_bf16 v[74:77], v[138:141], v[196:199], v[74:77]
	v_mfma_f32_16x16x32_bf16 v[74:77], v[142:145], v[200:203], v[74:77]
	v_mfma_f32_16x16x32_bf16 v[118:121], v[146:149], v[162:165], v[118:121]
	v_mfma_f32_16x16x32_bf16 v[118:121], v[150:153], v[166:169], v[118:121]
	v_mfma_f32_16x16x32_bf16 v[114:117], v[154:157], v[162:165], v[114:117]
	v_mfma_f32_16x16x32_bf16 v[114:117], v[158:161], v[166:169], v[114:117]
	v_mfma_f32_16x16x32_bf16 v[102:105], v[146:149], v[170:173], v[102:105]
	v_mfma_f32_16x16x32_bf16 v[102:105], v[150:153], v[174:177], v[102:105]
	v_mfma_f32_16x16x32_bf16 v[98:101], v[154:157], v[170:173], v[98:101]
	v_mfma_f32_16x16x32_bf16 v[98:101], v[158:161], v[174:177], v[98:101]
	v_mfma_f32_16x16x32_bf16 v[86:89], v[146:149], v[188:191], v[86:89]
	v_mfma_f32_16x16x32_bf16 v[86:89], v[150:153], v[192:195], v[86:89]
	v_mfma_f32_16x16x32_bf16 v[82:85], v[154:157], v[188:191], v[82:85]
	v_mfma_f32_16x16x32_bf16 v[82:85], v[158:161], v[192:195], v[82:85]
	v_mfma_f32_16x16x32_bf16 v[70:73], v[146:149], v[196:199], v[70:73]
	v_mfma_f32_16x16x32_bf16 v[70:73], v[150:153], v[200:203], v[70:73]
	v_mfma_f32_16x16x32_bf16 v[66:69], v[154:157], v[196:199], v[66:69]
	v_mfma_f32_16x16x32_bf16 v[66:69], v[158:161], v[200:203], v[66:69]
	s_setprio 0
	s_barrier
	ds_read_b128 v[162:165], v186 offset:49152
	ds_read_b128 v[166:169], v186 offset:50176
	ds_read_b128 v[170:173], v186 offset:51200
	ds_read_b128 v[174:177], v186 offset:52224
	ds_read_b128 v[188:191], v186 offset:53248
	ds_read_b128 v[192:195], v186 offset:54272
	ds_read_b128 v[196:199], v186 offset:55296
	ds_read_b128 v[200:203], v186 offset:56320
	s_add_u32 s34, s30, 0x8000
	s_addc_u32 s35, s31, 0
	s_mov_b32 m0, s50
	s_nop 0
	global_load_lds_dwordx4 v180, s[34:35]
	s_add_u32 s30, s30, 0xc000
	s_mov_b32 m0, s51
	s_nop 0
	global_load_lds_dwordx4 v182, s[34:35]
	s_addc_u32 s31, s31, 0
	s_mov_b32 m0, s56
	s_nop 0
	global_load_lds_dwordx4 v180, s[30:31]
	s_nop 0
	s_mov_b32 m0, s57
	s_nop 0
	global_load_lds_dwordx4 v182, s[30:31]
	s_mov_b32 m0, s54
	s_nop 0
	global_load_lds_dwordx4 v0, s[8:9]
	s_nop 0
	s_mov_b32 m0, s55
	s_nop 0
	global_load_lds_dwordx4 v181, s[8:9]
	s_waitcnt vmcnt(8)
	s_waitcnt lgkmcnt(0)
	s_barrier
	s_setprio 1
	v_mfma_f32_16x16x32_bf16 v[62:65], v[122:125], v[162:165], v[62:65]
	v_mfma_f32_16x16x32_bf16 v[62:65], v[130:133], v[166:169], v[62:65]
	v_mfma_f32_16x16x32_bf16 v[58:61], v[138:141], v[162:165], v[58:61]
	v_mfma_f32_16x16x32_bf16 v[58:61], v[142:145], v[166:169], v[58:61]
	v_mfma_f32_16x16x32_bf16 v[46:49], v[122:125], v[170:173], v[46:49]
	v_mfma_f32_16x16x32_bf16 v[46:49], v[130:133], v[174:177], v[46:49]
	v_mfma_f32_16x16x32_bf16 v[42:45], v[138:141], v[170:173], v[42:45]
	v_mfma_f32_16x16x32_bf16 v[42:45], v[142:145], v[174:177], v[42:45]
	v_mfma_f32_16x16x32_bf16 v[30:33], v[122:125], v[188:191], v[30:33]
	v_mfma_f32_16x16x32_bf16 v[30:33], v[130:133], v[192:195], v[30:33]
	v_mfma_f32_16x16x32_bf16 v[26:29], v[138:141], v[188:191], v[26:29]
	v_mfma_f32_16x16x32_bf16 v[26:29], v[142:145], v[192:195], v[26:29]
	v_mfma_f32_16x16x32_bf16 v[14:17], v[122:125], v[196:199], v[14:17]
	v_mfma_f32_16x16x32_bf16 v[14:17], v[130:133], v[200:203], v[14:17]
	v_mfma_f32_16x16x32_bf16 v[10:13], v[138:141], v[196:199], v[10:13]
	v_mfma_f32_16x16x32_bf16 v[10:13], v[142:145], v[200:203], v[10:13]
	v_mfma_f32_16x16x32_bf16 v[54:57], v[146:149], v[162:165], v[54:57]
	v_mfma_f32_16x16x32_bf16 v[54:57], v[150:153], v[166:169], v[54:57]
	v_mfma_f32_16x16x32_bf16 v[50:53], v[154:157], v[162:165], v[50:53]
	v_mfma_f32_16x16x32_bf16 v[50:53], v[158:161], v[166:169], v[50:53]
	v_mfma_f32_16x16x32_bf16 v[38:41], v[146:149], v[170:173], v[38:41]
	v_mfma_f32_16x16x32_bf16 v[38:41], v[150:153], v[174:177], v[38:41]
	v_mfma_f32_16x16x32_bf16 v[34:37], v[154:157], v[170:173], v[34:37]
	v_mfma_f32_16x16x32_bf16 v[34:37], v[158:161], v[174:177], v[34:37]
	v_mfma_f32_16x16x32_bf16 v[22:25], v[146:149], v[188:191], v[22:25]
	v_mfma_f32_16x16x32_bf16 v[22:25], v[150:153], v[192:195], v[22:25]
	v_mfma_f32_16x16x32_bf16 v[18:21], v[154:157], v[188:191], v[18:21]
	v_mfma_f32_16x16x32_bf16 v[18:21], v[158:161], v[192:195], v[18:21]
	v_mfma_f32_16x16x32_bf16 v[6:9], v[146:149], v[196:199], v[6:9]
	v_mfma_f32_16x16x32_bf16 v[6:9], v[150:153], v[200:203], v[6:9]
	v_mfma_f32_16x16x32_bf16 v[2:5], v[154:157], v[196:199], v[2:5]
	v_mfma_f32_16x16x32_bf16 v[2:5], v[158:161], v[200:203], v[2:5]
	s_setprio 0
	s_barrier
	s_add_i32 s89, s89, 2
	s_add_u32 s59, s59, 0x10000
	s_addc_u32 s67, s67, 0
	s_add_u32 s83, s83, 0x10000
	s_addc_u32 s87, s87, 0
	s_add_u32 s6, s6, 0x10000
	s_addc_u32 s7, s7, 0
	s_cmpk_gt_u32 s89, 0x55
	s_cbranch_scc0 .LBB0_1151
	s_and_b64 vcc, exec, s[20:21]
	s_cbranch_vccz .LBB0_1154
	s_barrier
